# GEMM K loops: 88 LDS-DMA loads use the saddr form (SGPR base + VGPR offset) instead of a v_lshl_add_u64 address built from an SGPR pair
# baseline (speedup 1.0000x reference)
; #define PG8_STAGE(bufoff, gbase, voff) do { _Pragma("unroll") for (int _i = 0; _i < 2; ++_i) \
;         __builtin_amdgcn_global_load_lds((const unsigned*)((const char*)(gbase) + (voff)[_i]), (LAS unsigned*)(lds + (bufoff) + ldsw + _i * 8192), 16, 0, 0); } while (0)
; #define PG8_LDA(dst, b, h) do { _Pragma("unroll") for (int m = 0; m < 4; ++m) _Pragma("unroll") for (int k = 0; k < 2; ++k) dst[m][k] = *(const LAS bf16x8*)(lds + PG8_SA(b, h) + aoff + m * 2048 + k * 1024); } while (0)
; #define PG8_LDB(dst, b, h) do { _Pragma("unroll") for (int n = 0; n < 2; ++n) _Pragma("unroll") for (int k = 0; k < 2; ++k) dst[n][k] = *(const LAS bf16x8*)(lds + PG8_SB(b, h) + boff + n * 2048 + k * 1024); } while (0)
; #define PG8_MMA(ai, bj, At, Bt) do { __builtin_amdgcn_s_setprio(1); _Pragma("unroll") for (int m = 0; m < 4; ++m) _Pragma("unroll") for (int n = 0; n < 2; ++n) _Pragma("unroll") for (int k = 0; k < 2; ++k) \
;         acc[ai][bj][m][n] = __builtin_amdgcn_mfma_f32_16x16x32_bf16(Bt[n][k], At[m][k], acc[ai][bj][m][n], 0, 0, 0); __builtin_amdgcn_s_setprio(0); } while (0)
; #define PG8_WAIT_V(n) asm volatile("s_waitcnt vmcnt(" #n ")" ::: "memory")
; #define PG8_WAIT_L(n) asm volatile("s_waitcnt lgkmcnt(" #n ")" ::: "memory")
; #define PG8_BAR __builtin_amdgcn_s_barrier()
; #define PG8_SCHED __builtin_amdgcn_sched_barrier(0)
; template <class Epi, class Sched, bool ALIGN_EPI = true, bool SP2 = true>
; __device__ __forceinline__ void gemm_phase(LAS unsigned char* lds, const Gemm g, const Sched& S, const Epi& E) {
;     ...
;             PG8_LDB(B0, 0, 0); PG8_LDB(B1, 0, 1); PG8_SCHED; PG8_LDA(At, 0, 0); PG8_STAGE(PG8_SA(1, 1), a1 + hstepA, voffA);
;             PG8_WAIT_V(8); PG8_WAIT_L(0); PG8_BAR; PG8_MMA(0, 0, At, B0); PG8_MMA(0, 1, At, B1); PG8_BAR; PG8_SCHED;
;             PG8_LDA(At, 0, 1); PG8_STAGE(PG8_SB(0, 0), b2, voffB); PG8_STAGE(PG8_SB(0, 1), b2 + hstepB, voffB); PG8_STAGE(PG8_SA(0, 0), a2, voffA);
.LBB0_357:
	ds_read_b128 v[146:149], v161
	ds_read_b128 v[150:153], v161 offset:1024
	ds_read_b128 v[166:169], v161 offset:2048
	ds_read_b128 v[170:173], v161 offset:3072
	ds_read_b128 v[174:177], v162
	ds_read_b128 v[178:181], v162 offset:1024
	ds_read_b128 v[182:185], v162 offset:2048
	ds_read_b128 v[186:189], v162 offset:3072
	s_add_u32 s56, s54, 0xfffc0080
	s_addc_u32 s57, s55, -1
	s_cmp_eq_u32 s77, 12
	s_cselect_b32 s59, s7, s57
	s_cselect_b32 s58, s41, s56
	s_cselect_b32 s57, s31, s76
	s_cselect_b32 s56, s53, s75
	s_nop 0
	s_add_i32 m0, s33, 0xc000
	ds_read_b128 v[190:193], v163
	ds_read_b128 v[194:197], v163 offset:1024
	ds_read_b128 v[198:201], v163 offset:2048
	ds_read_b128 v[202:205], v163 offset:3072
	ds_read_b128 v[206:209], v163 offset:4096
	ds_read_b128 v[210:213], v163 offset:5120
	ds_read_b128 v[214:217], v163 offset:6144
	ds_read_b128 v[218:221], v163 offset:7168
	global_load_lds_dwordx4 v138, s[54:55]
	s_nop 0
	s_add_i32 m0, s33, 0xe000
	s_nop 0
	global_load_lds_dwordx4 v140, s[54:55]
	s_waitcnt vmcnt(8)
	s_waitcnt lgkmcnt(0)
	s_barrier
	s_setprio 1
	s_waitcnt lgkmcnt(0)
	v_mfma_f32_16x16x32_bf16 v[124:127], v[146:149], v[190:193], v[124:127]
	v_mfma_f32_16x16x32_bf16 v[120:123], v[166:169], v[190:193], v[120:123]
	v_mfma_f32_16x16x32_bf16 v[108:111], v[146:149], v[198:201], v[108:111]
	v_mfma_f32_16x16x32_bf16 v[104:107], v[166:169], v[198:201], v[104:107]
	v_mfma_f32_16x16x32_bf16 v[92:95], v[146:149], v[206:209], v[92:95]
	v_mfma_f32_16x16x32_bf16 v[88:91], v[166:169], v[206:209], v[88:91]
	v_mfma_f32_16x16x32_bf16 v[76:79], v[146:149], v[214:217], v[76:79]
	v_mfma_f32_16x16x32_bf16 v[72:75], v[166:169], v[214:217], v[72:75]
	v_mfma_f32_16x16x32_bf16 v[124:127], v[150:153], v[194:197], v[124:127]
	v_mfma_f32_16x16x32_bf16 v[120:123], v[170:173], v[194:197], v[120:123]
	v_mfma_f32_16x16x32_bf16 v[108:111], v[150:153], v[202:205], v[108:111]
	v_mfma_f32_16x16x32_bf16 v[104:107], v[170:173], v[202:205], v[104:107]
	v_mfma_f32_16x16x32_bf16 v[92:95], v[150:153], v[210:213], v[92:95]
	v_mfma_f32_16x16x32_bf16 v[88:91], v[170:173], v[210:213], v[88:91]
	v_mfma_f32_16x16x32_bf16 v[76:79], v[150:153], v[218:221], v[76:79]
	v_mfma_f32_16x16x32_bf16 v[72:75], v[170:173], v[218:221], v[72:75]
	s_setprio 0
	s_setprio 1
	v_mfma_f32_16x16x32_bf16 v[116:119], v[174:177], v[190:193], v[116:119]
	v_mfma_f32_16x16x32_bf16 v[112:115], v[182:185], v[190:193], v[112:115]
	v_mfma_f32_16x16x32_bf16 v[100:103], v[174:177], v[198:201], v[100:103]
	v_mfma_f32_16x16x32_bf16 v[96:99], v[182:185], v[198:201], v[96:99]
	v_mfma_f32_16x16x32_bf16 v[84:87], v[174:177], v[206:209], v[84:87]
	v_mfma_f32_16x16x32_bf16 v[80:83], v[182:185], v[206:209], v[80:83]
	v_mfma_f32_16x16x32_bf16 v[68:71], v[174:177], v[214:217], v[68:71]
	v_mfma_f32_16x16x32_bf16 v[64:67], v[182:185], v[214:217], v[64:67]
	v_mfma_f32_16x16x32_bf16 v[116:119], v[178:181], v[194:197], v[116:119]
	v_mfma_f32_16x16x32_bf16 v[112:115], v[186:189], v[194:197], v[112:115]
	v_mfma_f32_16x16x32_bf16 v[100:103], v[178:181], v[202:205], v[100:103]
	v_mfma_f32_16x16x32_bf16 v[96:99], v[186:189], v[202:205], v[96:99]
	v_mfma_f32_16x16x32_bf16 v[84:87], v[178:181], v[210:213], v[84:87]
	v_mfma_f32_16x16x32_bf16 v[80:83], v[186:189], v[210:213], v[80:83]
	v_mfma_f32_16x16x32_bf16 v[68:71], v[178:181], v[218:221], v[68:71]
	v_mfma_f32_16x16x32_bf16 v[64:67], v[186:189], v[218:221], v[64:67]
	s_setprio 0
	s_barrier
	s_add_i32 s70, s68, s3
	v_lshl_add_u64 v[154:155], s[56:57], 0, v[130:131]
	s_mov_b32 m0, s70
	ds_read_b128 v[190:193], v163 offset:16384
	ds_read_b128 v[194:197], v163 offset:17408
	ds_read_b128 v[198:201], v163 offset:18432
	ds_read_b128 v[202:205], v163 offset:19456
	ds_read_b128 v[206:209], v163 offset:20480
	ds_read_b128 v[210:213], v163 offset:21504
	ds_read_b128 v[214:217], v163 offset:22528
	ds_read_b128 v[218:221], v163 offset:23552
	global_load_lds_dwordx4 v[154:155], off
	s_add_i32 m0, s70, 0x2000
	s_add_u32 s78, s56, 0x40000
	v_lshl_add_u64 v[222:223], s[56:57], 0, v[134:135]
	s_addc_u32 s79, s57, 0
	s_add_i32 s70, s69, s3
	global_load_lds_dwordx4 v[222:223], off
	s_nop 0
	s_mov_b32 m0, s70
	v_lshl_add_u64 v[226:227], s[58:59], 0, v[132:133]
	global_load_lds_dwordx4 v130, s[78:79]
	s_nop 0
	s_add_i32 m0, s70, 0x2000
	s_nop 0
	global_load_lds_dwordx4 v134, s[78:79]
	v_lshl_add_u64 v[224:225], s[58:59], 0, v[128:129]
	s_mov_b32 m0, s33
	s_nop 0
	global_load_lds_dwordx4 v[224:225], off
	s_mov_b32 m0, s34
	s_nop 0
	global_load_lds_dwordx4 v[226:227], off
	s_waitcnt vmcnt(8)
	s_waitcnt lgkmcnt(0)
	s_barrier
; #define PG8_STAGE(bufoff, gbase, voff) do { _Pragma("unroll") for (int _i = 0; _i < 2; ++_i) \
;         __builtin_amdgcn_global_load_lds((const unsigned*)((const char*)(gbase) + (voff)[_i]), (LAS unsigned*)(lds + (bufoff) + ldsw + _i * 8192), 16, 0, 0); } while (0)
; #define PG8_LDA(dst, b, h) do { _Pragma("unroll") for (int m = 0; m < 4; ++m) _Pragma("unroll") for (int k = 0; k < 2; ++k) dst[m][k] = *(const LAS bf16x8*)(lds + PG8_SA(b, h) + aoff + m * 2048 + k * 1024); } while (0)
; #define PG8_LDB(dst, b, h) do { _Pragma("unroll") for (int n = 0; n < 2; ++n) _Pragma("unroll") for (int k = 0; k < 2; ++k) dst[n][k] = *(const LAS bf16x8*)(lds + PG8_SB(b, h) + boff + n * 2048 + k * 1024); } while (0)
; #define PG8_MMA(ai, bj, At, Bt) do { __builtin_amdgcn_s_setprio(1); _Pragma("unroll") for (int m = 0; m < 4; ++m) _Pragma("unroll") for (int n = 0; n < 2; ++n) _Pragma("unroll") for (int k = 0; k < 2; ++k) \
;         acc[ai][bj][m][n] = __builtin_amdgcn_mfma_f32_16x16x32_bf16(Bt[n][k], At[m][k], acc[ai][bj][m][n], 0, 0, 0); __builtin_amdgcn_s_setprio(0); } while (0)
; #define PG8_WAIT_V(n) asm volatile("s_waitcnt vmcnt(" #n ")" ::: "memory")
; #define PG8_WAIT_L(n) asm volatile("s_waitcnt lgkmcnt(" #n ")" ::: "memory")
; #define PG8_BAR __builtin_amdgcn_s_barrier()
; #define PG8_SCHED __builtin_amdgcn_sched_barrier(0)
; template <class Epi, class Sched, bool ALIGN_EPI = true, bool SP2 = true>
; __device__ __forceinline__ void gemm_phase(LAS unsigned char* lds, const Gemm g, const Sched& S, const Epi& E) {
;     ...
;             PG8_WAIT_V(8); PG8_WAIT_L(0); PG8_BAR; PG8_MMA(1, 0, At, B0); PG8_MMA(1, 1, At, B1); PG8_BAR; PG8_SCHED;
;             PG8_LDB(B0, 1, 0); PG8_LDB(B1, 1, 1); PG8_SCHED; PG8_LDA(At, 1, 0); PG8_STAGE(PG8_SA(0, 1), a2 + hstepA, voffA);
;             PG8_WAIT_V(8); PG8_WAIT_L(0); PG8_BAR; PG8_MMA(0, 0, At, B0); PG8_MMA(0, 1, At, B1); PG8_BAR; PG8_SCHED;
	s_setprio 1
	s_waitcnt lgkmcnt(0)
	v_mfma_f32_16x16x32_bf16 v[60:63], v[146:149], v[190:193], v[60:63]
	v_mfma_f32_16x16x32_bf16 v[56:59], v[166:169], v[190:193], v[56:59]
	v_mfma_f32_16x16x32_bf16 v[44:47], v[146:149], v[198:201], v[44:47]
	v_mfma_f32_16x16x32_bf16 v[40:43], v[166:169], v[198:201], v[40:43]
	v_mfma_f32_16x16x32_bf16 v[28:31], v[146:149], v[206:209], v[28:31]
	v_mfma_f32_16x16x32_bf16 v[24:27], v[166:169], v[206:209], v[24:27]
	v_mfma_f32_16x16x32_bf16 v[12:15], v[146:149], v[214:217], v[12:15]
	v_mfma_f32_16x16x32_bf16 v[8:11], v[166:169], v[214:217], v[8:11]
	v_mfma_f32_16x16x32_bf16 v[60:63], v[150:153], v[194:197], v[60:63]
	v_mfma_f32_16x16x32_bf16 v[56:59], v[170:173], v[194:197], v[56:59]
	v_mfma_f32_16x16x32_bf16 v[44:47], v[150:153], v[202:205], v[44:47]
	v_mfma_f32_16x16x32_bf16 v[40:43], v[170:173], v[202:205], v[40:43]
	v_mfma_f32_16x16x32_bf16 v[28:31], v[150:153], v[210:213], v[28:31]
	v_mfma_f32_16x16x32_bf16 v[24:27], v[170:173], v[210:213], v[24:27]
	v_mfma_f32_16x16x32_bf16 v[12:15], v[150:153], v[218:221], v[12:15]
	v_mfma_f32_16x16x32_bf16 v[8:11], v[170:173], v[218:221], v[8:11]
	s_setprio 0
	s_setprio 1
	v_mfma_f32_16x16x32_bf16 v[52:55], v[174:177], v[190:193], v[52:55]
	v_mfma_f32_16x16x32_bf16 v[48:51], v[182:185], v[190:193], v[48:51]
	v_mfma_f32_16x16x32_bf16 v[36:39], v[174:177], v[198:201], v[36:39]
	v_mfma_f32_16x16x32_bf16 v[32:35], v[182:185], v[198:201], v[32:35]
	v_mfma_f32_16x16x32_bf16 v[20:23], v[174:177], v[206:209], v[20:23]
	v_mfma_f32_16x16x32_bf16 v[16:19], v[182:185], v[206:209], v[16:19]
	v_mfma_f32_16x16x32_bf16 v[4:7], v[174:177], v[214:217], v[4:7]
	v_mfma_f32_16x16x32_bf16 v[0:3], v[182:185], v[214:217], v[0:3]
	v_mfma_f32_16x16x32_bf16 v[52:55], v[178:181], v[194:197], v[52:55]
	v_mfma_f32_16x16x32_bf16 v[48:51], v[186:189], v[194:197], v[48:51]
	v_mfma_f32_16x16x32_bf16 v[36:39], v[178:181], v[202:205], v[36:39]
	v_mfma_f32_16x16x32_bf16 v[32:35], v[186:189], v[202:205], v[32:35]
	v_mfma_f32_16x16x32_bf16 v[20:23], v[178:181], v[210:213], v[20:23]
	v_mfma_f32_16x16x32_bf16 v[16:19], v[186:189], v[210:213], v[16:19]
	v_mfma_f32_16x16x32_bf16 v[4:7], v[178:181], v[218:221], v[4:7]
	v_mfma_f32_16x16x32_bf16 v[0:3], v[186:189], v[218:221], v[0:3]
	s_setprio 0
	s_barrier
	s_add_i32 s70, 0, 0x18000
	v_add_u32_e32 v136, s70, v159
	s_add_i32 s78, 0, 0x1c000
	ds_read_b128 v[146:149], v136
	ds_read_b128 v[150:153], v136 offset:1024
	ds_read_b128 v[166:169], v136 offset:2048
	ds_read_b128 v[170:173], v136 offset:3072
	v_add_u32_e32 v136, s78, v159
	ds_read_b128 v[174:177], v136
	ds_read_b128 v[178:181], v136 offset:1024
	ds_read_b128 v[182:185], v136 offset:2048
	ds_read_b128 v[186:189], v136 offset:3072
	s_add_u32 s58, s58, 0x40000
	s_addc_u32 s59, s59, 0
	s_mov_b32 m0, s35
	s_nop 0
	ds_read_b128 v[190:193], v163 offset:32768
	ds_read_b128 v[194:197], v163 offset:33792
	ds_read_b128 v[198:201], v163 offset:34816
	ds_read_b128 v[202:205], v163 offset:35840
	ds_read_b128 v[206:209], v163 offset:36864
	ds_read_b128 v[210:213], v163 offset:37888
	ds_read_b128 v[214:217], v163 offset:38912
	ds_read_b128 v[218:221], v163 offset:39936
	global_load_lds_dwordx4 v128, s[58:59]
	s_nop 0
	s_mov_b32 m0, s60
	s_nop 0
	global_load_lds_dwordx4 v132, s[58:59]
	s_waitcnt vmcnt(8)
	s_waitcnt lgkmcnt(0)
	s_barrier
	s_setprio 1
	s_waitcnt lgkmcnt(0)
	v_mfma_f32_16x16x32_bf16 v[124:127], v[146:149], v[190:193], v[124:127]
	v_mfma_f32_16x16x32_bf16 v[120:123], v[166:169], v[190:193], v[120:123]
	v_mfma_f32_16x16x32_bf16 v[108:111], v[146:149], v[198:201], v[108:111]
	v_mfma_f32_16x16x32_bf16 v[104:107], v[166:169], v[198:201], v[104:107]
	v_mfma_f32_16x16x32_bf16 v[92:95], v[146:149], v[206:209], v[92:95]
	v_mfma_f32_16x16x32_bf16 v[88:91], v[166:169], v[206:209], v[88:91]
	v_mfma_f32_16x16x32_bf16 v[76:79], v[146:149], v[214:217], v[76:79]
	v_mfma_f32_16x16x32_bf16 v[72:75], v[166:169], v[214:217], v[72:75]
	v_mfma_f32_16x16x32_bf16 v[124:127], v[150:153], v[194:197], v[124:127]
	v_mfma_f32_16x16x32_bf16 v[120:123], v[170:173], v[194:197], v[120:123]
	v_mfma_f32_16x16x32_bf16 v[108:111], v[150:153], v[202:205], v[108:111]
	v_mfma_f32_16x16x32_bf16 v[104:107], v[170:173], v[202:205], v[104:107]
	v_mfma_f32_16x16x32_bf16 v[92:95], v[150:153], v[210:213], v[92:95]
	v_mfma_f32_16x16x32_bf16 v[88:91], v[170:173], v[210:213], v[88:91]
	v_mfma_f32_16x16x32_bf16 v[76:79], v[150:153], v[218:221], v[76:79]
	v_mfma_f32_16x16x32_bf16 v[72:75], v[170:173], v[218:221], v[72:75]
	s_setprio 0
	s_setprio 1
	v_mfma_f32_16x16x32_bf16 v[116:119], v[174:177], v[190:193], v[116:119]
	v_mfma_f32_16x16x32_bf16 v[112:115], v[182:185], v[190:193], v[112:115]
	v_mfma_f32_16x16x32_bf16 v[100:103], v[174:177], v[198:201], v[100:103]
	v_mfma_f32_16x16x32_bf16 v[96:99], v[182:185], v[198:201], v[96:99]
	v_mfma_f32_16x16x32_bf16 v[84:87], v[174:177], v[206:209], v[84:87]
	v_mfma_f32_16x16x32_bf16 v[80:83], v[182:185], v[206:209], v[80:83]
	v_mfma_f32_16x16x32_bf16 v[68:71], v[174:177], v[214:217], v[68:71]
	v_mfma_f32_16x16x32_bf16 v[64:67], v[182:185], v[214:217], v[64:67]
	v_mfma_f32_16x16x32_bf16 v[116:119], v[178:181], v[194:197], v[116:119]
	v_mfma_f32_16x16x32_bf16 v[112:115], v[186:189], v[194:197], v[112:115]
	v_mfma_f32_16x16x32_bf16 v[100:103], v[178:181], v[202:205], v[100:103]
	v_mfma_f32_16x16x32_bf16 v[96:99], v[186:189], v[202:205], v[96:99]
	v_mfma_f32_16x16x32_bf16 v[84:87], v[178:181], v[210:213], v[84:87]
	v_mfma_f32_16x16x32_bf16 v[80:83], v[186:189], v[210:213], v[80:83]
	v_mfma_f32_16x16x32_bf16 v[68:71], v[178:181], v[218:221], v[68:71]
	v_mfma_f32_16x16x32_bf16 v[64:67], v[186:189], v[218:221], v[64:67]
	s_setprio 0
	s_barrier
; #define PG8_STAGE(bufoff, gbase, voff) do { _Pragma("unroll") for (int _i = 0; _i < 2; ++_i) \
;         __builtin_amdgcn_global_load_lds((const unsigned*)((const char*)(gbase) + (voff)[_i]), (LAS unsigned*)(lds + (bufoff) + ldsw + _i * 8192), 16, 0, 0); } while (0)
; #define PG8_LDA(dst, b, h) do { _Pragma("unroll") for (int m = 0; m < 4; ++m) _Pragma("unroll") for (int k = 0; k < 2; ++k) dst[m][k] = *(const LAS bf16x8*)(lds + PG8_SA(b, h) + aoff + m * 2048 + k * 1024); } while (0)
; #define PG8_MMA(ai, bj, At, Bt) do { __builtin_amdgcn_s_setprio(1); _Pragma("unroll") for (int m = 0; m < 4; ++m) _Pragma("unroll") for (int n = 0; n < 2; ++n) _Pragma("unroll") for (int k = 0; k < 2; ++k) \
;         acc[ai][bj][m][n] = __builtin_amdgcn_mfma_f32_16x16x32_bf16(Bt[n][k], At[m][k], acc[ai][bj][m][n], 0, 0, 0); __builtin_amdgcn_s_setprio(0); } while (0)
; #define PG8_WAIT_V(n) asm volatile("s_waitcnt vmcnt(" #n ")" ::: "memory")
; #define PG8_WAIT_L(n) asm volatile("s_waitcnt lgkmcnt(" #n ")" ::: "memory")
; #define PG8_BAR __builtin_amdgcn_s_barrier()
; #define PG8_SCHED __builtin_amdgcn_sched_barrier(0)
; template <class Epi, class Sched, bool ALIGN_EPI = true, bool SP2 = true>
; __device__ __forceinline__ void gemm_phase(LAS unsigned char* lds, const Gemm g, const Sched& S, const Epi& E) {
;     ...
;             PG8_LDA(At, 1, 1); PG8_STAGE(PG8_SB(1, 0), b3, voffB); PG8_STAGE(PG8_SB(1, 1), b3 + hstepB, voffB); PG8_STAGE(PG8_SA(1, 0), a3, voffA);
;             PG8_WAIT_V(8); PG8_WAIT_L(0); PG8_BAR; PG8_MMA(1, 0, At, B0); PG8_MMA(1, 1, At, B1); PG8_BAR; PG8_SCHED;
	s_add_i32 s58, s70, s3
	v_lshl_add_u64 v[154:155], v[154:155], 0, s[26:27]
	s_mov_b32 m0, s58
	ds_read_b128 v[190:193], v163 offset:49152
	ds_read_b128 v[194:197], v163 offset:50176
	ds_read_b128 v[198:201], v163 offset:51200
	ds_read_b128 v[202:205], v163 offset:52224
	ds_read_b128 v[206:209], v163 offset:53248
	ds_read_b128 v[210:213], v163 offset:54272
	ds_read_b128 v[214:217], v163 offset:55296
	ds_read_b128 v[218:221], v163 offset:56320
	global_load_lds_dwordx4 v[154:155], off
	s_add_i32 m0, s58, 0x2000
	s_add_u32 s56, s56, 0x40080
	v_lshl_add_u64 v[154:155], v[222:223], 0, s[26:27]
	s_addc_u32 s57, s57, 0
	s_add_i32 s58, s78, s3
	global_load_lds_dwordx4 v[154:155], off
	s_nop 0
	s_mov_b32 m0, s58
	s_nop 0
	global_load_lds_dwordx4 v130, s[56:57]
	s_nop 0
	s_add_i32 m0, s58, 0x2000
	s_nop 0
	global_load_lds_dwordx4 v134, s[56:57]
	v_lshl_add_u64 v[154:155], v[224:225], 0, s[26:27]
	s_mov_b32 m0, s63
	s_nop 0
	global_load_lds_dwordx4 v[154:155], off
	v_lshl_add_u64 v[154:155], v[226:227], 0, s[26:27]
	s_mov_b32 m0, s64
	s_nop 0
	global_load_lds_dwordx4 v[154:155], off
	s_waitcnt vmcnt(8)
	s_waitcnt lgkmcnt(0)
	s_barrier
	s_setprio 1
	s_waitcnt lgkmcnt(0)
	v_mfma_f32_16x16x32_bf16 v[60:63], v[146:149], v[190:193], v[60:63]
	v_mfma_f32_16x16x32_bf16 v[56:59], v[166:169], v[190:193], v[56:59]
	v_mfma_f32_16x16x32_bf16 v[44:47], v[146:149], v[198:201], v[44:47]
	v_mfma_f32_16x16x32_bf16 v[40:43], v[166:169], v[198:201], v[40:43]
	v_mfma_f32_16x16x32_bf16 v[28:31], v[146:149], v[206:209], v[28:31]
	v_mfma_f32_16x16x32_bf16 v[24:27], v[166:169], v[206:209], v[24:27]
	v_mfma_f32_16x16x32_bf16 v[12:15], v[146:149], v[214:217], v[12:15]
	v_mfma_f32_16x16x32_bf16 v[8:11], v[166:169], v[214:217], v[8:11]
	v_mfma_f32_16x16x32_bf16 v[60:63], v[150:153], v[194:197], v[60:63]
	v_mfma_f32_16x16x32_bf16 v[56:59], v[170:173], v[194:197], v[56:59]
	v_mfma_f32_16x16x32_bf16 v[44:47], v[150:153], v[202:205], v[44:47]
	v_mfma_f32_16x16x32_bf16 v[40:43], v[170:173], v[202:205], v[40:43]
	v_mfma_f32_16x16x32_bf16 v[28:31], v[150:153], v[210:213], v[28:31]
	v_mfma_f32_16x16x32_bf16 v[24:27], v[170:173], v[210:213], v[24:27]
	v_mfma_f32_16x16x32_bf16 v[12:15], v[150:153], v[218:221], v[12:15]
	v_mfma_f32_16x16x32_bf16 v[8:11], v[170:173], v[218:221], v[8:11]
	s_setprio 0
	s_setprio 1
	v_mfma_f32_16x16x32_bf16 v[52:55], v[174:177], v[190:193], v[52:55]
	v_mfma_f32_16x16x32_bf16 v[48:51], v[182:185], v[190:193], v[48:51]
	v_mfma_f32_16x16x32_bf16 v[36:39], v[174:177], v[198:201], v[36:39]
	v_mfma_f32_16x16x32_bf16 v[32:35], v[182:185], v[198:201], v[32:35]
	v_mfma_f32_16x16x32_bf16 v[20:23], v[174:177], v[206:209], v[20:23]
	v_mfma_f32_16x16x32_bf16 v[16:19], v[182:185], v[206:209], v[16:19]
	v_mfma_f32_16x16x32_bf16 v[4:7], v[174:177], v[214:217], v[4:7]
	v_mfma_f32_16x16x32_bf16 v[0:3], v[182:185], v[214:217], v[0:3]
	v_mfma_f32_16x16x32_bf16 v[52:55], v[178:181], v[194:197], v[52:55]
	v_mfma_f32_16x16x32_bf16 v[48:51], v[186:189], v[194:197], v[48:51]
	v_mfma_f32_16x16x32_bf16 v[36:39], v[178:181], v[202:205], v[36:39]
	v_mfma_f32_16x16x32_bf16 v[32:35], v[186:189], v[202:205], v[32:35]
	v_mfma_f32_16x16x32_bf16 v[20:23], v[178:181], v[210:213], v[20:23]
	v_mfma_f32_16x16x32_bf16 v[16:19], v[186:189], v[210:213], v[16:19]
	v_mfma_f32_16x16x32_bf16 v[4:7], v[178:181], v[218:221], v[4:7]
	v_mfma_f32_16x16x32_bf16 v[0:3], v[186:189], v[218:221], v[0:3]
	s_setprio 0
	s_barrier
	s_add_i32 s77, s77, 2
	s_add_u32 s75, s75, 0x100
	s_addc_u32 s76, s76, 0
	s_add_u32 s54, s54, 0x100
	s_addc_u32 s55, s55, 0
	s_cmp_gt_u32 s77, 13
	s_cbranch_scc0 .LBB0_357
	s_and_b64 vcc, exec, s[28:29]
	s_cbranch_vccz .LBB0_360
	s_barrier

; #define PG8_STAGE(bufoff, gbase, voff) do { _Pragma("unroll") for (int _i = 0; _i < 2; ++_i) \
;         __builtin_amdgcn_global_load_lds((const unsigned*)((const char*)(gbase) + (voff)[_i]), (LAS unsigned*)(lds + (bufoff) + ldsw + _i * 8192), 16, 0, 0); } while (0)
; #define PG8_LDA(dst, b, h) do { _Pragma("unroll") for (int m = 0; m < 4; ++m) _Pragma("unroll") for (int k = 0; k < 2; ++k) dst[m][k] = *(const LAS bf16x8*)(lds + PG8_SA(b, h) + aoff + m * 2048 + k * 1024); } while (0)
; #define PG8_LDB(dst, b, h) do { _Pragma("unroll") for (int n = 0; n < 2; ++n) _Pragma("unroll") for (int k = 0; k < 2; ++k) dst[n][k] = *(const LAS bf16x8*)(lds + PG8_SB(b, h) + boff + n * 2048 + k * 1024); } while (0)
; #define PG8_MMA(ai, bj, At, Bt) do { __builtin_amdgcn_s_setprio(1); _Pragma("unroll") for (int m = 0; m < 4; ++m) _Pragma("unroll") for (int n = 0; n < 2; ++n) _Pragma("unroll") for (int k = 0; k < 2; ++k) \
;         acc[ai][bj][m][n] = __builtin_amdgcn_mfma_f32_16x16x32_bf16(Bt[n][k], At[m][k], acc[ai][bj][m][n], 0, 0, 0); __builtin_amdgcn_s_setprio(0); } while (0)
; #define PG8_WAIT_V(n) asm volatile("s_waitcnt vmcnt(" #n ")" ::: "memory")
; #define PG8_WAIT_L(n) asm volatile("s_waitcnt lgkmcnt(" #n ")" ::: "memory")
; #define PG8_BAR __builtin_amdgcn_s_barrier()
; #define PG8_SCHED __builtin_amdgcn_sched_barrier(0)
; template <class Epi, class Sched, bool ALIGN_EPI = true, bool SP2 = true>
; __device__ __forceinline__ void gemm_phase(LAS unsigned char* lds, const Gemm g, const Sched& S, const Epi& E) {
;     ...
;             PG8_LDB(B0, 0, 0); PG8_LDB(B1, 0, 1); PG8_SCHED; PG8_LDA(At, 0, 0); PG8_STAGE(PG8_SA(1, 1), a1 + hstepA, voffA);
;             PG8_WAIT_V(8); PG8_WAIT_L(0); PG8_BAR; PG8_MMA(0, 0, At, B0); PG8_MMA(0, 1, At, B1); PG8_BAR; PG8_SCHED;
;             PG8_LDA(At, 0, 1); PG8_STAGE(PG8_SB(0, 0), b2, voffB); PG8_STAGE(PG8_SB(0, 1), b2 + hstepB, voffB); PG8_STAGE(PG8_SA(0, 0), a2, voffA);
.LBB0_502:
	ds_read_b128 v[140:143], v161
	ds_read_b128 v[144:147], v161 offset:1024
	ds_read_b128 v[164:167], v161 offset:2048
	ds_read_b128 v[168:171], v161 offset:3072
	ds_read_b128 v[172:175], v162
	ds_read_b128 v[176:179], v162 offset:1024
	ds_read_b128 v[180:183], v162 offset:2048
	ds_read_b128 v[184:187], v162 offset:3072
	s_add_u32 s40, s20, 0xff301a00
	s_addc_u32 s41, s21, -1
	s_cmp_eq_u32 s78, 28
	s_cselect_b32 s58, s54, s40
	s_cselect_b32 s59, s55, s41
	s_cselect_b32 s44, s53, s76
	s_cselect_b32 s45, s35, s77
	s_add_u32 s40, s58, 0x1a00
	s_addc_u32 s41, s59, 0
	s_nop 0
	s_add_i32 m0, s63, 0xc000
	ds_read_b128 v[188:191], v163
	ds_read_b128 v[192:195], v163 offset:1024
	ds_read_b128 v[196:199], v163 offset:2048
	ds_read_b128 v[200:203], v163 offset:3072
	ds_read_b128 v[204:207], v163 offset:4096
	ds_read_b128 v[208:211], v163 offset:5120
	ds_read_b128 v[212:215], v163 offset:6144
	ds_read_b128 v[216:219], v163 offset:7168
	global_load_lds_dwordx4 v136, s[20:21]
	s_nop 0
	s_add_i32 m0, s63, 0xe000
	s_nop 0
	global_load_lds_dwordx4 v138, s[20:21]
	s_waitcnt vmcnt(8)
	s_waitcnt lgkmcnt(0)
	s_barrier
	s_setprio 1
	s_waitcnt lgkmcnt(0)
	v_mfma_f32_16x16x32_bf16 v[124:127], v[140:143], v[188:191], v[124:127]
	v_mfma_f32_16x16x32_bf16 v[120:123], v[164:167], v[188:191], v[120:123]
	v_mfma_f32_16x16x32_bf16 v[108:111], v[140:143], v[196:199], v[108:111]
	v_mfma_f32_16x16x32_bf16 v[104:107], v[164:167], v[196:199], v[104:107]
	v_mfma_f32_16x16x32_bf16 v[92:95], v[140:143], v[204:207], v[92:95]
	v_mfma_f32_16x16x32_bf16 v[88:91], v[164:167], v[204:207], v[88:91]
	v_mfma_f32_16x16x32_bf16 v[76:79], v[140:143], v[212:215], v[76:79]
	v_mfma_f32_16x16x32_bf16 v[72:75], v[164:167], v[212:215], v[72:75]
	v_mfma_f32_16x16x32_bf16 v[124:127], v[144:147], v[192:195], v[124:127]
	v_mfma_f32_16x16x32_bf16 v[120:123], v[168:171], v[192:195], v[120:123]
	v_mfma_f32_16x16x32_bf16 v[108:111], v[144:147], v[200:203], v[108:111]
	v_mfma_f32_16x16x32_bf16 v[104:107], v[168:171], v[200:203], v[104:107]
	v_mfma_f32_16x16x32_bf16 v[92:95], v[144:147], v[208:211], v[92:95]
	v_mfma_f32_16x16x32_bf16 v[88:91], v[168:171], v[208:211], v[88:91]
	v_mfma_f32_16x16x32_bf16 v[76:79], v[144:147], v[216:219], v[76:79]
	v_mfma_f32_16x16x32_bf16 v[72:75], v[168:171], v[216:219], v[72:75]
	s_setprio 0
	s_setprio 1
	v_mfma_f32_16x16x32_bf16 v[116:119], v[172:175], v[188:191], v[116:119]
	v_mfma_f32_16x16x32_bf16 v[112:115], v[180:183], v[188:191], v[112:115]
	v_mfma_f32_16x16x32_bf16 v[100:103], v[172:175], v[196:199], v[100:103]
	v_mfma_f32_16x16x32_bf16 v[96:99], v[180:183], v[196:199], v[96:99]
	v_mfma_f32_16x16x32_bf16 v[84:87], v[172:175], v[204:207], v[84:87]
	v_mfma_f32_16x16x32_bf16 v[80:83], v[180:183], v[204:207], v[80:83]
	v_mfma_f32_16x16x32_bf16 v[68:71], v[172:175], v[212:215], v[68:71]
	v_mfma_f32_16x16x32_bf16 v[64:67], v[180:183], v[212:215], v[64:67]
	v_mfma_f32_16x16x32_bf16 v[116:119], v[176:179], v[192:195], v[116:119]
	v_mfma_f32_16x16x32_bf16 v[112:115], v[184:187], v[192:195], v[112:115]
	v_mfma_f32_16x16x32_bf16 v[100:103], v[176:179], v[200:203], v[100:103]
	v_mfma_f32_16x16x32_bf16 v[96:99], v[184:187], v[200:203], v[96:99]
	v_mfma_f32_16x16x32_bf16 v[84:87], v[176:179], v[208:211], v[84:87]
	v_mfma_f32_16x16x32_bf16 v[80:83], v[184:187], v[208:211], v[80:83]
	v_mfma_f32_16x16x32_bf16 v[68:71], v[176:179], v[216:219], v[68:71]
	v_mfma_f32_16x16x32_bf16 v[64:67], v[184:187], v[216:219], v[64:67]
	s_setprio 0
	s_barrier
	s_add_i32 s70, s72, s62
	v_lshl_add_u64 v[220:221], s[44:45], 0, v[130:131]
	s_mov_b32 m0, s70
	ds_read_b128 v[188:191], v163 offset:16384
	ds_read_b128 v[192:195], v163 offset:17408
	ds_read_b128 v[196:199], v163 offset:18432
	ds_read_b128 v[200:203], v163 offset:19456
	ds_read_b128 v[204:207], v163 offset:20480
	ds_read_b128 v[208:211], v163 offset:21504
	ds_read_b128 v[212:215], v163 offset:22528
	ds_read_b128 v[216:219], v163 offset:23552
	global_load_lds_dwordx4 v[220:221], off
	s_add_i32 m0, s70, 0x2000
	s_add_u32 s80, s44, 0x80000
	v_lshl_add_u64 v[222:223], s[44:45], 0, v[134:135]
	s_addc_u32 s81, s45, 0
	s_add_i32 s70, s73, s62
	global_load_lds_dwordx4 v[222:223], off
	s_nop 0
	s_mov_b32 m0, s70
	s_nop 0
	global_load_lds_dwordx4 v130, s[80:81]
	s_nop 0
	s_add_i32 m0, s70, 0x2000
	s_nop 0
	global_load_lds_dwordx4 v134, s[80:81]
	s_nop 0
	s_mov_b32 m0, s63
	s_nop 0
	global_load_lds_dwordx4 v128, s[58:59]
	s_nop 0
	s_mov_b32 m0, s64
	s_nop 0
	global_load_lds_dwordx4 v132, s[58:59]
	s_waitcnt vmcnt(8)
	s_waitcnt lgkmcnt(0)
	s_barrier
; #define PG8_STAGE(bufoff, gbase, voff) do { _Pragma("unroll") for (int _i = 0; _i < 2; ++_i) \
;         __builtin_amdgcn_global_load_lds((const unsigned*)((const char*)(gbase) + (voff)[_i]), (LAS unsigned*)(lds + (bufoff) + ldsw + _i * 8192), 16, 0, 0); } while (0)
; #define PG8_LDA(dst, b, h) do { _Pragma("unroll") for (int m = 0; m < 4; ++m) _Pragma("unroll") for (int k = 0; k < 2; ++k) dst[m][k] = *(const LAS bf16x8*)(lds + PG8_SA(b, h) + aoff + m * 2048 + k * 1024); } while (0)
; #define PG8_LDB(dst, b, h) do { _Pragma("unroll") for (int n = 0; n < 2; ++n) _Pragma("unroll") for (int k = 0; k < 2; ++k) dst[n][k] = *(const LAS bf16x8*)(lds + PG8_SB(b, h) + boff + n * 2048 + k * 1024); } while (0)
; #define PG8_MMA(ai, bj, At, Bt) do { __builtin_amdgcn_s_setprio(1); _Pragma("unroll") for (int m = 0; m < 4; ++m) _Pragma("unroll") for (int n = 0; n < 2; ++n) _Pragma("unroll") for (int k = 0; k < 2; ++k) \
;         acc[ai][bj][m][n] = __builtin_amdgcn_mfma_f32_16x16x32_bf16(Bt[n][k], At[m][k], acc[ai][bj][m][n], 0, 0, 0); __builtin_amdgcn_s_setprio(0); } while (0)
; #define PG8_WAIT_V(n) asm volatile("s_waitcnt vmcnt(" #n ")" ::: "memory")
; #define PG8_WAIT_L(n) asm volatile("s_waitcnt lgkmcnt(" #n ")" ::: "memory")
; #define PG8_BAR __builtin_amdgcn_s_barrier()
; #define PG8_SCHED __builtin_amdgcn_sched_barrier(0)
; template <class Epi, class Sched, bool ALIGN_EPI = true, bool SP2 = true>
; __device__ __forceinline__ void gemm_phase(LAS unsigned char* lds, const Gemm g, const Sched& S, const Epi& E) {
;     ...
;             PG8_WAIT_V(8); PG8_WAIT_L(0); PG8_BAR; PG8_MMA(1, 0, At, B0); PG8_MMA(1, 1, At, B1); PG8_BAR; PG8_SCHED;
;             PG8_LDB(B0, 1, 0); PG8_LDB(B1, 1, 1); PG8_SCHED; PG8_LDA(At, 1, 0); PG8_STAGE(PG8_SA(0, 1), a2 + hstepA, voffA);
;             PG8_WAIT_V(8); PG8_WAIT_L(0); PG8_BAR; PG8_MMA(0, 0, At, B0); PG8_MMA(0, 1, At, B1); PG8_BAR; PG8_SCHED;
	s_setprio 1
	s_waitcnt lgkmcnt(0)
	v_mfma_f32_16x16x32_bf16 v[60:63], v[140:143], v[188:191], v[60:63]
	v_mfma_f32_16x16x32_bf16 v[56:59], v[164:167], v[188:191], v[56:59]
	v_mfma_f32_16x16x32_bf16 v[44:47], v[140:143], v[196:199], v[44:47]
	v_mfma_f32_16x16x32_bf16 v[40:43], v[164:167], v[196:199], v[40:43]
	v_mfma_f32_16x16x32_bf16 v[28:31], v[140:143], v[204:207], v[28:31]
	v_mfma_f32_16x16x32_bf16 v[24:27], v[164:167], v[204:207], v[24:27]
	v_mfma_f32_16x16x32_bf16 v[12:15], v[140:143], v[212:215], v[12:15]
	v_mfma_f32_16x16x32_bf16 v[8:11], v[164:167], v[212:215], v[8:11]
	v_mfma_f32_16x16x32_bf16 v[60:63], v[144:147], v[192:195], v[60:63]
	v_mfma_f32_16x16x32_bf16 v[56:59], v[168:171], v[192:195], v[56:59]
	v_mfma_f32_16x16x32_bf16 v[44:47], v[144:147], v[200:203], v[44:47]
	v_mfma_f32_16x16x32_bf16 v[40:43], v[168:171], v[200:203], v[40:43]
	v_mfma_f32_16x16x32_bf16 v[28:31], v[144:147], v[208:211], v[28:31]
	v_mfma_f32_16x16x32_bf16 v[24:27], v[168:171], v[208:211], v[24:27]
	v_mfma_f32_16x16x32_bf16 v[12:15], v[144:147], v[216:219], v[12:15]
	v_mfma_f32_16x16x32_bf16 v[8:11], v[168:171], v[216:219], v[8:11]
	s_setprio 0
	s_setprio 1
	v_mfma_f32_16x16x32_bf16 v[52:55], v[172:175], v[188:191], v[52:55]
	v_mfma_f32_16x16x32_bf16 v[48:51], v[180:183], v[188:191], v[48:51]
	v_mfma_f32_16x16x32_bf16 v[36:39], v[172:175], v[196:199], v[36:39]
	v_mfma_f32_16x16x32_bf16 v[32:35], v[180:183], v[196:199], v[32:35]
	v_mfma_f32_16x16x32_bf16 v[20:23], v[172:175], v[204:207], v[20:23]
	v_mfma_f32_16x16x32_bf16 v[16:19], v[180:183], v[204:207], v[16:19]
	v_mfma_f32_16x16x32_bf16 v[4:7], v[172:175], v[212:215], v[4:7]
	v_mfma_f32_16x16x32_bf16 v[0:3], v[180:183], v[212:215], v[0:3]
	v_mfma_f32_16x16x32_bf16 v[52:55], v[176:179], v[192:195], v[52:55]
	v_mfma_f32_16x16x32_bf16 v[48:51], v[184:187], v[192:195], v[48:51]
	v_mfma_f32_16x16x32_bf16 v[36:39], v[176:179], v[200:203], v[36:39]
	v_mfma_f32_16x16x32_bf16 v[32:35], v[184:187], v[200:203], v[32:35]
	v_mfma_f32_16x16x32_bf16 v[20:23], v[176:179], v[208:211], v[20:23]
	v_mfma_f32_16x16x32_bf16 v[16:19], v[184:187], v[208:211], v[16:19]
	v_mfma_f32_16x16x32_bf16 v[4:7], v[176:179], v[216:219], v[4:7]
	v_mfma_f32_16x16x32_bf16 v[0:3], v[184:187], v[216:219], v[0:3]
	s_setprio 0
	s_barrier
	s_add_i32 s70, 0, 0x18000
	s_add_i32 s79, 0, 0x1c000
	v_add_u32_e32 v168, s70, v159
	v_add_u32_e32 v184, s79, v159
	ds_read_b128 v[140:143], v168
	ds_read_b128 v[144:147], v168 offset:1024
	ds_read_b128 v[164:167], v168 offset:2048
	ds_read_b128 v[168:171], v168 offset:3072
	ds_read_b128 v[172:175], v184
	ds_read_b128 v[176:179], v184 offset:1024
	ds_read_b128 v[180:183], v184 offset:2048
	ds_read_b128 v[184:187], v184 offset:3072
	s_add_u32 s58, s58, 0xd00000
	s_addc_u32 s59, s59, 0
	s_mov_b32 m0, s65
	s_nop 0
	ds_read_b128 v[188:191], v163 offset:32768
	ds_read_b128 v[192:195], v163 offset:33792
	ds_read_b128 v[196:199], v163 offset:34816
	ds_read_b128 v[200:203], v163 offset:35840
	ds_read_b128 v[204:207], v163 offset:36864
	ds_read_b128 v[208:211], v163 offset:37888
	ds_read_b128 v[212:215], v163 offset:38912
	ds_read_b128 v[216:219], v163 offset:39936
	global_load_lds_dwordx4 v128, s[58:59]
	s_nop 0
	s_mov_b32 m0, s66
	s_nop 0
	global_load_lds_dwordx4 v132, s[58:59]
	s_waitcnt vmcnt(8)
	s_waitcnt lgkmcnt(0)
	s_barrier
	s_setprio 1
	s_waitcnt lgkmcnt(0)
	v_mfma_f32_16x16x32_bf16 v[124:127], v[140:143], v[188:191], v[124:127]
	v_mfma_f32_16x16x32_bf16 v[120:123], v[164:167], v[188:191], v[120:123]
	v_mfma_f32_16x16x32_bf16 v[108:111], v[140:143], v[196:199], v[108:111]
	v_mfma_f32_16x16x32_bf16 v[104:107], v[164:167], v[196:199], v[104:107]
	v_mfma_f32_16x16x32_bf16 v[92:95], v[140:143], v[204:207], v[92:95]
	v_mfma_f32_16x16x32_bf16 v[88:91], v[164:167], v[204:207], v[88:91]
	v_mfma_f32_16x16x32_bf16 v[76:79], v[140:143], v[212:215], v[76:79]
	v_mfma_f32_16x16x32_bf16 v[72:75], v[164:167], v[212:215], v[72:75]
	v_mfma_f32_16x16x32_bf16 v[124:127], v[144:147], v[192:195], v[124:127]
	v_mfma_f32_16x16x32_bf16 v[120:123], v[168:171], v[192:195], v[120:123]
	v_mfma_f32_16x16x32_bf16 v[108:111], v[144:147], v[200:203], v[108:111]
	v_mfma_f32_16x16x32_bf16 v[104:107], v[168:171], v[200:203], v[104:107]
	v_mfma_f32_16x16x32_bf16 v[92:95], v[144:147], v[208:211], v[92:95]
	v_mfma_f32_16x16x32_bf16 v[88:91], v[168:171], v[208:211], v[88:91]
	v_mfma_f32_16x16x32_bf16 v[76:79], v[144:147], v[216:219], v[76:79]
	v_mfma_f32_16x16x32_bf16 v[72:75], v[168:171], v[216:219], v[72:75]
	s_setprio 0
	s_setprio 1
	v_mfma_f32_16x16x32_bf16 v[116:119], v[172:175], v[188:191], v[116:119]
	v_mfma_f32_16x16x32_bf16 v[112:115], v[180:183], v[188:191], v[112:115]
	v_mfma_f32_16x16x32_bf16 v[100:103], v[172:175], v[196:199], v[100:103]
	v_mfma_f32_16x16x32_bf16 v[96:99], v[180:183], v[196:199], v[96:99]
	v_mfma_f32_16x16x32_bf16 v[84:87], v[172:175], v[204:207], v[84:87]
	v_mfma_f32_16x16x32_bf16 v[80:83], v[180:183], v[204:207], v[80:83]
	v_mfma_f32_16x16x32_bf16 v[68:71], v[172:175], v[212:215], v[68:71]
	v_mfma_f32_16x16x32_bf16 v[64:67], v[180:183], v[212:215], v[64:67]
	v_mfma_f32_16x16x32_bf16 v[116:119], v[176:179], v[192:195], v[116:119]
	v_mfma_f32_16x16x32_bf16 v[112:115], v[184:187], v[192:195], v[112:115]
	v_mfma_f32_16x16x32_bf16 v[100:103], v[176:179], v[200:203], v[100:103]
	v_mfma_f32_16x16x32_bf16 v[96:99], v[184:187], v[200:203], v[96:99]
	v_mfma_f32_16x16x32_bf16 v[84:87], v[176:179], v[208:211], v[84:87]
	v_mfma_f32_16x16x32_bf16 v[80:83], v[184:187], v[208:211], v[80:83]
	v_mfma_f32_16x16x32_bf16 v[68:71], v[176:179], v[216:219], v[68:71]
	v_mfma_f32_16x16x32_bf16 v[64:67], v[184:187], v[216:219], v[64:67]
	s_setprio 0
	s_barrier
; #define PG8_STAGE(bufoff, gbase, voff) do { _Pragma("unroll") for (int _i = 0; _i < 2; ++_i) \
;         __builtin_amdgcn_global_load_lds((const unsigned*)((const char*)(gbase) + (voff)[_i]), (LAS unsigned*)(lds + (bufoff) + ldsw + _i * 8192), 16, 0, 0); } while (0)
; #define PG8_LDA(dst, b, h) do { _Pragma("unroll") for (int m = 0; m < 4; ++m) _Pragma("unroll") for (int k = 0; k < 2; ++k) dst[m][k] = *(const LAS bf16x8*)(lds + PG8_SA(b, h) + aoff + m * 2048 + k * 1024); } while (0)
; #define PG8_MMA(ai, bj, At, Bt) do { __builtin_amdgcn_s_setprio(1); _Pragma("unroll") for (int m = 0; m < 4; ++m) _Pragma("unroll") for (int n = 0; n < 2; ++n) _Pragma("unroll") for (int k = 0; k < 2; ++k) \
;         acc[ai][bj][m][n] = __builtin_amdgcn_mfma_f32_16x16x32_bf16(Bt[n][k], At[m][k], acc[ai][bj][m][n], 0, 0, 0); __builtin_amdgcn_s_setprio(0); } while (0)
; #define PG8_WAIT_V(n) asm volatile("s_waitcnt vmcnt(" #n ")" ::: "memory")
; #define PG8_WAIT_L(n) asm volatile("s_waitcnt lgkmcnt(" #n ")" ::: "memory")
; #define PG8_BAR __builtin_amdgcn_s_barrier()
; #define PG8_SCHED __builtin_amdgcn_sched_barrier(0)
; template <class Epi, class Sched, bool ALIGN_EPI = true, bool SP2 = true>
; __device__ __forceinline__ void gemm_phase(LAS unsigned char* lds, const Gemm g, const Sched& S, const Epi& E) {
;     ...
;             PG8_LDA(At, 1, 1); PG8_STAGE(PG8_SB(1, 0), b3, voffB); PG8_STAGE(PG8_SB(1, 1), b3 + hstepB, voffB); PG8_STAGE(PG8_SA(1, 0), a3, voffA);
;             PG8_WAIT_V(8); PG8_WAIT_L(0); PG8_BAR; PG8_MMA(1, 0, At, B0); PG8_MMA(1, 1, At, B1); PG8_BAR; PG8_SCHED;
	s_add_i32 s58, s70, s62
	v_lshl_add_u64 v[220:221], v[220:221], 0, s[48:49]
	s_mov_b32 m0, s58
	ds_read_b128 v[188:191], v163 offset:49152
	ds_read_b128 v[192:195], v163 offset:50176
	ds_read_b128 v[196:199], v163 offset:51200
	ds_read_b128 v[200:203], v163 offset:52224
	ds_read_b128 v[204:207], v163 offset:53248
	ds_read_b128 v[208:211], v163 offset:54272
	ds_read_b128 v[212:215], v163 offset:55296
	ds_read_b128 v[216:219], v163 offset:56320
	global_load_lds_dwordx4 v[220:221], off
	s_add_i32 m0, s58, 0x2000
	s_add_u32 s44, s44, 0x80080
	v_lshl_add_u64 v[220:221], v[222:223], 0, s[48:49]
	s_addc_u32 s45, s45, 0
	s_add_i32 s58, s79, s62
	global_load_lds_dwordx4 v[220:221], off
	s_nop 0
	s_mov_b32 m0, s58
	s_nop 0
	global_load_lds_dwordx4 v130, s[44:45]
	s_nop 0
	s_add_i32 m0, s58, 0x2000
	s_nop 0
	global_load_lds_dwordx4 v134, s[44:45]
	s_nop 0
	s_mov_b32 m0, s67
	s_nop 0
	global_load_lds_dwordx4 v128, s[40:41]
	s_nop 0
	s_mov_b32 m0, s68
	s_nop 0
	global_load_lds_dwordx4 v132, s[40:41]
	s_waitcnt vmcnt(8)
	s_waitcnt lgkmcnt(0)
	s_barrier
	s_setprio 1
	s_waitcnt lgkmcnt(0)
	v_mfma_f32_16x16x32_bf16 v[60:63], v[140:143], v[188:191], v[60:63]
	v_mfma_f32_16x16x32_bf16 v[56:59], v[164:167], v[188:191], v[56:59]
	v_mfma_f32_16x16x32_bf16 v[44:47], v[140:143], v[196:199], v[44:47]
	v_mfma_f32_16x16x32_bf16 v[40:43], v[164:167], v[196:199], v[40:43]
	v_mfma_f32_16x16x32_bf16 v[28:31], v[140:143], v[204:207], v[28:31]
	v_mfma_f32_16x16x32_bf16 v[24:27], v[164:167], v[204:207], v[24:27]
	v_mfma_f32_16x16x32_bf16 v[12:15], v[140:143], v[212:215], v[12:15]
	v_mfma_f32_16x16x32_bf16 v[8:11], v[164:167], v[212:215], v[8:11]
	v_mfma_f32_16x16x32_bf16 v[60:63], v[144:147], v[192:195], v[60:63]
	v_mfma_f32_16x16x32_bf16 v[56:59], v[168:171], v[192:195], v[56:59]
	v_mfma_f32_16x16x32_bf16 v[44:47], v[144:147], v[200:203], v[44:47]
	v_mfma_f32_16x16x32_bf16 v[40:43], v[168:171], v[200:203], v[40:43]
	v_mfma_f32_16x16x32_bf16 v[28:31], v[144:147], v[208:211], v[28:31]
	v_mfma_f32_16x16x32_bf16 v[24:27], v[168:171], v[208:211], v[24:27]
	v_mfma_f32_16x16x32_bf16 v[12:15], v[144:147], v[216:219], v[12:15]
	v_mfma_f32_16x16x32_bf16 v[8:11], v[168:171], v[216:219], v[8:11]
	s_setprio 0
	s_setprio 1
	v_mfma_f32_16x16x32_bf16 v[52:55], v[172:175], v[188:191], v[52:55]
	v_mfma_f32_16x16x32_bf16 v[48:51], v[180:183], v[188:191], v[48:51]
	v_mfma_f32_16x16x32_bf16 v[36:39], v[172:175], v[196:199], v[36:39]
	v_mfma_f32_16x16x32_bf16 v[32:35], v[180:183], v[196:199], v[32:35]
	v_mfma_f32_16x16x32_bf16 v[20:23], v[172:175], v[204:207], v[20:23]
	v_mfma_f32_16x16x32_bf16 v[16:19], v[180:183], v[204:207], v[16:19]
	v_mfma_f32_16x16x32_bf16 v[4:7], v[172:175], v[212:215], v[4:7]
	v_mfma_f32_16x16x32_bf16 v[0:3], v[180:183], v[212:215], v[0:3]
	v_mfma_f32_16x16x32_bf16 v[52:55], v[176:179], v[192:195], v[52:55]
	v_mfma_f32_16x16x32_bf16 v[48:51], v[184:187], v[192:195], v[48:51]
	v_mfma_f32_16x16x32_bf16 v[36:39], v[176:179], v[200:203], v[36:39]
	v_mfma_f32_16x16x32_bf16 v[32:35], v[184:187], v[200:203], v[32:35]
	v_mfma_f32_16x16x32_bf16 v[20:23], v[176:179], v[208:211], v[20:23]
	v_mfma_f32_16x16x32_bf16 v[16:19], v[184:187], v[208:211], v[16:19]
	v_mfma_f32_16x16x32_bf16 v[4:7], v[176:179], v[216:219], v[4:7]
	v_mfma_f32_16x16x32_bf16 v[0:3], v[184:187], v[216:219], v[0:3]
	s_setprio 0
	s_barrier
	s_add_i32 s78, s78, 2
	s_add_u32 s76, s76, 0x100
	s_addc_u32 s77, s77, 0
	s_add_u32 s20, s20, 0x3400
	s_addc_u32 s21, s21, 0
	s_cmp_gt_u32 s78, 29
	s_cbranch_scc0 .LBB0_502
	s_and_b64 vcc, exec, s[30:31]
	s_cbranch_vccz .LBB0_505
	s_barrier

; #define PG8_STAGE(bufoff, gbase, voff) do { _Pragma("unroll") for (int _i = 0; _i < 2; ++_i) \
;         __builtin_amdgcn_global_load_lds((const unsigned*)((const char*)(gbase) + (voff)[_i]), (LAS unsigned*)(lds + (bufoff) + ldsw + _i * 8192), 16, 0, 0); } while (0)
; #define PG8_LDA(dst, b, h) do { _Pragma("unroll") for (int m = 0; m < 4; ++m) _Pragma("unroll") for (int k = 0; k < 2; ++k) dst[m][k] = *(const LAS bf16x8*)(lds + PG8_SA(b, h) + aoff + m * 2048 + k * 1024); } while (0)
; #define PG8_LDB(dst, b, h) do { _Pragma("unroll") for (int n = 0; n < 2; ++n) _Pragma("unroll") for (int k = 0; k < 2; ++k) dst[n][k] = *(const LAS bf16x8*)(lds + PG8_SB(b, h) + boff + n * 2048 + k * 1024); } while (0)
; #define PG8_MMA(ai, bj, At, Bt) do { __builtin_amdgcn_s_setprio(1); _Pragma("unroll") for (int m = 0; m < 4; ++m) _Pragma("unroll") for (int n = 0; n < 2; ++n) _Pragma("unroll") for (int k = 0; k < 2; ++k) \
;         acc[ai][bj][m][n] = __builtin_amdgcn_mfma_f32_16x16x32_bf16(Bt[n][k], At[m][k], acc[ai][bj][m][n], 0, 0, 0); __builtin_amdgcn_s_setprio(0); } while (0)
; #define PG8_WAIT_V(n) asm volatile("s_waitcnt vmcnt(" #n ")" ::: "memory")
; #define PG8_WAIT_L(n) asm volatile("s_waitcnt lgkmcnt(" #n ")" ::: "memory")
; #define PG8_BAR __builtin_amdgcn_s_barrier()
; #define PG8_SCHED __builtin_amdgcn_sched_barrier(0)
; template <class Epi, class Sched, bool ALIGN_EPI = true, bool SP2 = true>
; __device__ __forceinline__ void gemm_phase(LAS unsigned char* lds, const Gemm g, const Sched& S, const Epi& E) {
;     ...
;             PG8_LDB(B0, 0, 0); PG8_LDB(B1, 0, 1); PG8_SCHED; PG8_LDA(At, 0, 0); PG8_STAGE(PG8_SA(1, 1), a1 + hstepA, voffA);
;             PG8_WAIT_V(8); PG8_WAIT_L(0); PG8_BAR; PG8_MMA(0, 0, At, B0); PG8_MMA(0, 1, At, B1); PG8_BAR; PG8_SCHED;
;             PG8_LDA(At, 0, 1); PG8_STAGE(PG8_SB(0, 0), b2, voffB); PG8_STAGE(PG8_SB(0, 1), b2 + hstepB, voffB); PG8_STAGE(PG8_SA(0, 0), a2, voffA);
.LBB0_528:
	ds_read_b128 v[140:143], v148
	ds_read_b128 v[144:147], v148 offset:1024
	ds_read_b128 v[160:163], v148 offset:2048
	ds_read_b128 v[164:167], v148 offset:3072
	ds_read_b128 v[168:171], v149
	ds_read_b128 v[172:175], v149 offset:1024
	ds_read_b128 v[176:179], v149 offset:2048
	ds_read_b128 v[180:183], v149 offset:3072
	s_add_u32 s40, s20, 0xff301a00
	s_addc_u32 s41, s21, -1
	s_cmp_eq_u32 s77, 28
	s_cselect_b32 s56, s52, s40
	s_cselect_b32 s57, s53, s41
	s_cselect_b32 s44, s49, s75
	s_cselect_b32 s45, s35, s76
	s_add_u32 s40, s56, 0x1a00
	s_addc_u32 s41, s57, 0
	s_nop 0
	s_add_i32 m0, s62, 0xc000
	ds_read_b128 v[184:187], v151
	ds_read_b128 v[188:191], v151 offset:1024
	ds_read_b128 v[192:195], v151 offset:2048
	ds_read_b128 v[196:199], v151 offset:3072
	ds_read_b128 v[200:203], v151 offset:4096
	ds_read_b128 v[204:207], v151 offset:5120
	ds_read_b128 v[208:211], v151 offset:6144
	ds_read_b128 v[212:215], v151 offset:7168
	global_load_lds_dwordx4 v136, s[20:21]
	s_nop 0
	s_add_i32 m0, s62, 0xe000
	s_nop 0
	global_load_lds_dwordx4 v138, s[20:21]
	s_waitcnt vmcnt(8)
	s_waitcnt lgkmcnt(0)
	s_barrier
	s_setprio 1
	s_waitcnt lgkmcnt(0)
	v_mfma_f32_16x16x32_bf16 v[124:127], v[140:143], v[184:187], v[124:127]
	v_mfma_f32_16x16x32_bf16 v[120:123], v[160:163], v[184:187], v[120:123]
	v_mfma_f32_16x16x32_bf16 v[108:111], v[140:143], v[192:195], v[108:111]
	v_mfma_f32_16x16x32_bf16 v[104:107], v[160:163], v[192:195], v[104:107]
	v_mfma_f32_16x16x32_bf16 v[92:95], v[140:143], v[200:203], v[92:95]
	v_mfma_f32_16x16x32_bf16 v[88:91], v[160:163], v[200:203], v[88:91]
	v_mfma_f32_16x16x32_bf16 v[76:79], v[140:143], v[208:211], v[76:79]
	v_mfma_f32_16x16x32_bf16 v[72:75], v[160:163], v[208:211], v[72:75]
	v_mfma_f32_16x16x32_bf16 v[124:127], v[144:147], v[188:191], v[124:127]
	v_mfma_f32_16x16x32_bf16 v[120:123], v[164:167], v[188:191], v[120:123]
	v_mfma_f32_16x16x32_bf16 v[108:111], v[144:147], v[196:199], v[108:111]
	v_mfma_f32_16x16x32_bf16 v[104:107], v[164:167], v[196:199], v[104:107]
	v_mfma_f32_16x16x32_bf16 v[92:95], v[144:147], v[204:207], v[92:95]
	v_mfma_f32_16x16x32_bf16 v[88:91], v[164:167], v[204:207], v[88:91]
	v_mfma_f32_16x16x32_bf16 v[76:79], v[144:147], v[212:215], v[76:79]
	v_mfma_f32_16x16x32_bf16 v[72:75], v[164:167], v[212:215], v[72:75]
	s_setprio 0
	s_setprio 1
	v_mfma_f32_16x16x32_bf16 v[116:119], v[168:171], v[184:187], v[116:119]
	v_mfma_f32_16x16x32_bf16 v[112:115], v[176:179], v[184:187], v[112:115]
	v_mfma_f32_16x16x32_bf16 v[100:103], v[168:171], v[192:195], v[100:103]
	v_mfma_f32_16x16x32_bf16 v[96:99], v[176:179], v[192:195], v[96:99]
	v_mfma_f32_16x16x32_bf16 v[84:87], v[168:171], v[200:203], v[84:87]
	v_mfma_f32_16x16x32_bf16 v[80:83], v[176:179], v[200:203], v[80:83]
	v_mfma_f32_16x16x32_bf16 v[68:71], v[168:171], v[208:211], v[68:71]
	v_mfma_f32_16x16x32_bf16 v[64:67], v[176:179], v[208:211], v[64:67]
	v_mfma_f32_16x16x32_bf16 v[116:119], v[172:175], v[188:191], v[116:119]
	v_mfma_f32_16x16x32_bf16 v[112:115], v[180:183], v[188:191], v[112:115]
	v_mfma_f32_16x16x32_bf16 v[100:103], v[172:175], v[196:199], v[100:103]
	v_mfma_f32_16x16x32_bf16 v[96:99], v[180:183], v[196:199], v[96:99]
	v_mfma_f32_16x16x32_bf16 v[84:87], v[172:175], v[204:207], v[84:87]
	v_mfma_f32_16x16x32_bf16 v[80:83], v[180:183], v[204:207], v[80:83]
	v_mfma_f32_16x16x32_bf16 v[68:71], v[172:175], v[212:215], v[68:71]
	v_mfma_f32_16x16x32_bf16 v[64:67], v[180:183], v[212:215], v[64:67]
	s_setprio 0
	s_barrier
	s_add_i32 s70, s71, s61
	v_lshl_add_u64 v[154:155], s[44:45], 0, v[130:131]
	s_mov_b32 m0, s70
	ds_read_b128 v[184:187], v151 offset:16384
	ds_read_b128 v[188:191], v151 offset:17408
	ds_read_b128 v[192:195], v151 offset:18432
	ds_read_b128 v[196:199], v151 offset:19456
	ds_read_b128 v[200:203], v151 offset:20480
	ds_read_b128 v[204:207], v151 offset:21504
	ds_read_b128 v[208:211], v151 offset:22528
	ds_read_b128 v[212:215], v151 offset:23552
	global_load_lds_dwordx4 v[154:155], off
	s_add_i32 m0, s70, 0x2000
	s_add_u32 s78, s44, 0x80000
	v_lshl_add_u64 v[216:217], s[44:45], 0, v[134:135]
	s_addc_u32 s79, s45, 0
	s_add_i32 s70, s72, s61
	global_load_lds_dwordx4 v[216:217], off
	s_nop 0
	s_mov_b32 m0, s70
	s_nop 0
	global_load_lds_dwordx4 v130, s[78:79]
	s_nop 0
	s_add_i32 m0, s70, 0x2000
	s_nop 0
	global_load_lds_dwordx4 v134, s[78:79]
	s_nop 0
	s_mov_b32 m0, s62
	s_nop 0
	global_load_lds_dwordx4 v128, s[56:57]
	s_nop 0
	s_mov_b32 m0, s63
	s_nop 0
	global_load_lds_dwordx4 v132, s[56:57]
	s_waitcnt vmcnt(8)
	s_waitcnt lgkmcnt(0)
	s_barrier
; #define PG8_STAGE(bufoff, gbase, voff) do { _Pragma("unroll") for (int _i = 0; _i < 2; ++_i) \
;         __builtin_amdgcn_global_load_lds((const unsigned*)((const char*)(gbase) + (voff)[_i]), (LAS unsigned*)(lds + (bufoff) + ldsw + _i * 8192), 16, 0, 0); } while (0)
; #define PG8_LDA(dst, b, h) do { _Pragma("unroll") for (int m = 0; m < 4; ++m) _Pragma("unroll") for (int k = 0; k < 2; ++k) dst[m][k] = *(const LAS bf16x8*)(lds + PG8_SA(b, h) + aoff + m * 2048 + k * 1024); } while (0)
; #define PG8_LDB(dst, b, h) do { _Pragma("unroll") for (int n = 0; n < 2; ++n) _Pragma("unroll") for (int k = 0; k < 2; ++k) dst[n][k] = *(const LAS bf16x8*)(lds + PG8_SB(b, h) + boff + n * 2048 + k * 1024); } while (0)
; #define PG8_MMA(ai, bj, At, Bt) do { __builtin_amdgcn_s_setprio(1); _Pragma("unroll") for (int m = 0; m < 4; ++m) _Pragma("unroll") for (int n = 0; n < 2; ++n) _Pragma("unroll") for (int k = 0; k < 2; ++k) \
;         acc[ai][bj][m][n] = __builtin_amdgcn_mfma_f32_16x16x32_bf16(Bt[n][k], At[m][k], acc[ai][bj][m][n], 0, 0, 0); __builtin_amdgcn_s_setprio(0); } while (0)
; #define PG8_WAIT_V(n) asm volatile("s_waitcnt vmcnt(" #n ")" ::: "memory")
; #define PG8_WAIT_L(n) asm volatile("s_waitcnt lgkmcnt(" #n ")" ::: "memory")
; #define PG8_BAR __builtin_amdgcn_s_barrier()
; #define PG8_SCHED __builtin_amdgcn_sched_barrier(0)
; template <class Epi, class Sched, bool ALIGN_EPI = true, bool SP2 = true>
; __device__ __forceinline__ void gemm_phase(LAS unsigned char* lds, const Gemm g, const Sched& S, const Epi& E) {
;     ...
;             PG8_WAIT_V(8); PG8_WAIT_L(0); PG8_BAR; PG8_MMA(1, 0, At, B0); PG8_MMA(1, 1, At, B1); PG8_BAR; PG8_SCHED;
;             PG8_LDB(B0, 1, 0); PG8_LDB(B1, 1, 1); PG8_SCHED; PG8_LDA(At, 1, 0); PG8_STAGE(PG8_SA(0, 1), a2 + hstepA, voffA);
;             PG8_WAIT_V(8); PG8_WAIT_L(0); PG8_BAR; PG8_MMA(0, 0, At, B0); PG8_MMA(0, 1, At, B1); PG8_BAR; PG8_SCHED;
	s_setprio 1
	s_waitcnt lgkmcnt(0)
	v_mfma_f32_16x16x32_bf16 v[60:63], v[140:143], v[184:187], v[60:63]
	v_mfma_f32_16x16x32_bf16 v[56:59], v[160:163], v[184:187], v[56:59]
	v_mfma_f32_16x16x32_bf16 v[44:47], v[140:143], v[192:195], v[44:47]
	v_mfma_f32_16x16x32_bf16 v[40:43], v[160:163], v[192:195], v[40:43]
	v_mfma_f32_16x16x32_bf16 v[28:31], v[140:143], v[200:203], v[28:31]
	v_mfma_f32_16x16x32_bf16 v[24:27], v[160:163], v[200:203], v[24:27]
	v_mfma_f32_16x16x32_bf16 v[12:15], v[140:143], v[208:211], v[12:15]
	v_mfma_f32_16x16x32_bf16 v[8:11], v[160:163], v[208:211], v[8:11]
	v_mfma_f32_16x16x32_bf16 v[60:63], v[144:147], v[188:191], v[60:63]
	v_mfma_f32_16x16x32_bf16 v[56:59], v[164:167], v[188:191], v[56:59]
	v_mfma_f32_16x16x32_bf16 v[44:47], v[144:147], v[196:199], v[44:47]
	v_mfma_f32_16x16x32_bf16 v[40:43], v[164:167], v[196:199], v[40:43]
	v_mfma_f32_16x16x32_bf16 v[28:31], v[144:147], v[204:207], v[28:31]
	v_mfma_f32_16x16x32_bf16 v[24:27], v[164:167], v[204:207], v[24:27]
	v_mfma_f32_16x16x32_bf16 v[12:15], v[144:147], v[212:215], v[12:15]
	v_mfma_f32_16x16x32_bf16 v[8:11], v[164:167], v[212:215], v[8:11]
	s_setprio 0
	s_setprio 1
	v_mfma_f32_16x16x32_bf16 v[52:55], v[168:171], v[184:187], v[52:55]
	v_mfma_f32_16x16x32_bf16 v[48:51], v[176:179], v[184:187], v[48:51]
	v_mfma_f32_16x16x32_bf16 v[36:39], v[168:171], v[192:195], v[36:39]
	v_mfma_f32_16x16x32_bf16 v[32:35], v[176:179], v[192:195], v[32:35]
	v_mfma_f32_16x16x32_bf16 v[20:23], v[168:171], v[200:203], v[20:23]
	v_mfma_f32_16x16x32_bf16 v[16:19], v[176:179], v[200:203], v[16:19]
	v_mfma_f32_16x16x32_bf16 v[4:7], v[168:171], v[208:211], v[4:7]
	v_mfma_f32_16x16x32_bf16 v[0:3], v[176:179], v[208:211], v[0:3]
	v_mfma_f32_16x16x32_bf16 v[52:55], v[172:175], v[188:191], v[52:55]
	v_mfma_f32_16x16x32_bf16 v[48:51], v[180:183], v[188:191], v[48:51]
	v_mfma_f32_16x16x32_bf16 v[36:39], v[172:175], v[196:199], v[36:39]
	v_mfma_f32_16x16x32_bf16 v[32:35], v[180:183], v[196:199], v[32:35]
	v_mfma_f32_16x16x32_bf16 v[20:23], v[172:175], v[204:207], v[20:23]
	v_mfma_f32_16x16x32_bf16 v[16:19], v[180:183], v[204:207], v[16:19]
	v_mfma_f32_16x16x32_bf16 v[4:7], v[172:175], v[212:215], v[4:7]
	v_mfma_f32_16x16x32_bf16 v[0:3], v[180:183], v[212:215], v[0:3]
	s_setprio 0
	s_barrier
	s_add_i32 s70, 0, 0x18000
	v_add_u32_e32 v152, s70, v153
	s_add_i32 s78, 0, 0x1c000
	ds_read_b128 v[140:143], v152
	ds_read_b128 v[144:147], v152 offset:1024
	ds_read_b128 v[160:163], v152 offset:2048
	ds_read_b128 v[164:167], v152 offset:3072
	v_add_u32_e32 v152, s78, v153
	ds_read_b128 v[168:171], v152
	ds_read_b128 v[172:175], v152 offset:1024
	ds_read_b128 v[176:179], v152 offset:2048
	ds_read_b128 v[180:183], v152 offset:3072
	s_add_u32 s56, s56, 0xd00000
	s_addc_u32 s57, s57, 0
	s_mov_b32 m0, s64
	s_nop 0
	ds_read_b128 v[184:187], v151 offset:32768
	ds_read_b128 v[188:191], v151 offset:33792
	ds_read_b128 v[192:195], v151 offset:34816
	ds_read_b128 v[196:199], v151 offset:35840
	ds_read_b128 v[200:203], v151 offset:36864
	ds_read_b128 v[204:207], v151 offset:37888
	ds_read_b128 v[208:211], v151 offset:38912
	ds_read_b128 v[212:215], v151 offset:39936
	global_load_lds_dwordx4 v128, s[56:57]
	s_nop 0
	s_mov_b32 m0, s65
	s_nop 0
	global_load_lds_dwordx4 v132, s[56:57]
	s_waitcnt vmcnt(8)
	s_waitcnt lgkmcnt(0)
	s_barrier
	s_setprio 1
	s_waitcnt lgkmcnt(0)
	v_mfma_f32_16x16x32_bf16 v[124:127], v[140:143], v[184:187], v[124:127]
	v_mfma_f32_16x16x32_bf16 v[120:123], v[160:163], v[184:187], v[120:123]
	v_mfma_f32_16x16x32_bf16 v[108:111], v[140:143], v[192:195], v[108:111]
	v_mfma_f32_16x16x32_bf16 v[104:107], v[160:163], v[192:195], v[104:107]
	v_mfma_f32_16x16x32_bf16 v[92:95], v[140:143], v[200:203], v[92:95]
	v_mfma_f32_16x16x32_bf16 v[88:91], v[160:163], v[200:203], v[88:91]
	v_mfma_f32_16x16x32_bf16 v[76:79], v[140:143], v[208:211], v[76:79]
	v_mfma_f32_16x16x32_bf16 v[72:75], v[160:163], v[208:211], v[72:75]
	v_mfma_f32_16x16x32_bf16 v[124:127], v[144:147], v[188:191], v[124:127]
	v_mfma_f32_16x16x32_bf16 v[120:123], v[164:167], v[188:191], v[120:123]
	v_mfma_f32_16x16x32_bf16 v[108:111], v[144:147], v[196:199], v[108:111]
	v_mfma_f32_16x16x32_bf16 v[104:107], v[164:167], v[196:199], v[104:107]
	v_mfma_f32_16x16x32_bf16 v[92:95], v[144:147], v[204:207], v[92:95]
	v_mfma_f32_16x16x32_bf16 v[88:91], v[164:167], v[204:207], v[88:91]
	v_mfma_f32_16x16x32_bf16 v[76:79], v[144:147], v[212:215], v[76:79]
	v_mfma_f32_16x16x32_bf16 v[72:75], v[164:167], v[212:215], v[72:75]
	s_setprio 0
	s_setprio 1
	v_mfma_f32_16x16x32_bf16 v[116:119], v[168:171], v[184:187], v[116:119]
	v_mfma_f32_16x16x32_bf16 v[112:115], v[176:179], v[184:187], v[112:115]
	v_mfma_f32_16x16x32_bf16 v[100:103], v[168:171], v[192:195], v[100:103]
	v_mfma_f32_16x16x32_bf16 v[96:99], v[176:179], v[192:195], v[96:99]
	v_mfma_f32_16x16x32_bf16 v[84:87], v[168:171], v[200:203], v[84:87]
	v_mfma_f32_16x16x32_bf16 v[80:83], v[176:179], v[200:203], v[80:83]
	v_mfma_f32_16x16x32_bf16 v[68:71], v[168:171], v[208:211], v[68:71]
	v_mfma_f32_16x16x32_bf16 v[64:67], v[176:179], v[208:211], v[64:67]
	v_mfma_f32_16x16x32_bf16 v[116:119], v[172:175], v[188:191], v[116:119]
	v_mfma_f32_16x16x32_bf16 v[112:115], v[180:183], v[188:191], v[112:115]
	v_mfma_f32_16x16x32_bf16 v[100:103], v[172:175], v[196:199], v[100:103]
	v_mfma_f32_16x16x32_bf16 v[96:99], v[180:183], v[196:199], v[96:99]
	v_mfma_f32_16x16x32_bf16 v[84:87], v[172:175], v[204:207], v[84:87]
	v_mfma_f32_16x16x32_bf16 v[80:83], v[180:183], v[204:207], v[80:83]
	v_mfma_f32_16x16x32_bf16 v[68:71], v[172:175], v[212:215], v[68:71]
	v_mfma_f32_16x16x32_bf16 v[64:67], v[180:183], v[212:215], v[64:67]
	s_setprio 0
	s_barrier
; #define PG8_STAGE(bufoff, gbase, voff) do { _Pragma("unroll") for (int _i = 0; _i < 2; ++_i) \
;         __builtin_amdgcn_global_load_lds((const unsigned*)((const char*)(gbase) + (voff)[_i]), (LAS unsigned*)(lds + (bufoff) + ldsw + _i * 8192), 16, 0, 0); } while (0)
; #define PG8_LDA(dst, b, h) do { _Pragma("unroll") for (int m = 0; m < 4; ++m) _Pragma("unroll") for (int k = 0; k < 2; ++k) dst[m][k] = *(const LAS bf16x8*)(lds + PG8_SA(b, h) + aoff + m * 2048 + k * 1024); } while (0)
; #define PG8_MMA(ai, bj, At, Bt) do { __builtin_amdgcn_s_setprio(1); _Pragma("unroll") for (int m = 0; m < 4; ++m) _Pragma("unroll") for (int n = 0; n < 2; ++n) _Pragma("unroll") for (int k = 0; k < 2; ++k) \
;         acc[ai][bj][m][n] = __builtin_amdgcn_mfma_f32_16x16x32_bf16(Bt[n][k], At[m][k], acc[ai][bj][m][n], 0, 0, 0); __builtin_amdgcn_s_setprio(0); } while (0)
; #define PG8_WAIT_V(n) asm volatile("s_waitcnt vmcnt(" #n ")" ::: "memory")
; #define PG8_WAIT_L(n) asm volatile("s_waitcnt lgkmcnt(" #n ")" ::: "memory")
; #define PG8_BAR __builtin_amdgcn_s_barrier()
; #define PG8_SCHED __builtin_amdgcn_sched_barrier(0)
; template <class Epi, class Sched, bool ALIGN_EPI = true, bool SP2 = true>
; __device__ __forceinline__ void gemm_phase(LAS unsigned char* lds, const Gemm g, const Sched& S, const Epi& E) {
;     ...
;             PG8_LDA(At, 1, 1); PG8_STAGE(PG8_SB(1, 0), b3, voffB); PG8_STAGE(PG8_SB(1, 1), b3 + hstepB, voffB); PG8_STAGE(PG8_SA(1, 0), a3, voffA);
;             PG8_WAIT_V(8); PG8_WAIT_L(0); PG8_BAR; PG8_MMA(1, 0, At, B0); PG8_MMA(1, 1, At, B1); PG8_BAR; PG8_SCHED;
	s_add_i32 s56, s70, s61
	v_lshl_add_u64 v[154:155], v[154:155], 0, s[30:31]
	s_mov_b32 m0, s56
	ds_read_b128 v[184:187], v151 offset:49152
	ds_read_b128 v[188:191], v151 offset:50176
	ds_read_b128 v[192:195], v151 offset:51200
	ds_read_b128 v[196:199], v151 offset:52224
	ds_read_b128 v[200:203], v151 offset:53248
	ds_read_b128 v[204:207], v151 offset:54272
	ds_read_b128 v[208:211], v151 offset:55296
	ds_read_b128 v[212:215], v151 offset:56320
	global_load_lds_dwordx4 v[154:155], off
	s_add_i32 m0, s56, 0x2000
	s_add_u32 s44, s44, 0x80080
	v_lshl_add_u64 v[154:155], v[216:217], 0, s[30:31]
	s_addc_u32 s45, s45, 0
	s_add_i32 s56, s78, s61
	global_load_lds_dwordx4 v[154:155], off
	s_nop 0
	s_mov_b32 m0, s56
	s_nop 0
	global_load_lds_dwordx4 v130, s[44:45]
	s_nop 0
	s_add_i32 m0, s56, 0x2000
	s_nop 0
	global_load_lds_dwordx4 v134, s[44:45]
	s_nop 0
	s_mov_b32 m0, s66
	s_nop 0
	global_load_lds_dwordx4 v128, s[40:41]
	s_nop 0
	s_mov_b32 m0, s67
	s_nop 0
	global_load_lds_dwordx4 v132, s[40:41]
	s_waitcnt vmcnt(8)
	s_waitcnt lgkmcnt(0)
	s_barrier
	s_setprio 1
	s_waitcnt lgkmcnt(0)
	v_mfma_f32_16x16x32_bf16 v[60:63], v[140:143], v[184:187], v[60:63]
	v_mfma_f32_16x16x32_bf16 v[56:59], v[160:163], v[184:187], v[56:59]
	v_mfma_f32_16x16x32_bf16 v[44:47], v[140:143], v[192:195], v[44:47]
	v_mfma_f32_16x16x32_bf16 v[40:43], v[160:163], v[192:195], v[40:43]
	v_mfma_f32_16x16x32_bf16 v[28:31], v[140:143], v[200:203], v[28:31]
	v_mfma_f32_16x16x32_bf16 v[24:27], v[160:163], v[200:203], v[24:27]
	v_mfma_f32_16x16x32_bf16 v[12:15], v[140:143], v[208:211], v[12:15]
	v_mfma_f32_16x16x32_bf16 v[8:11], v[160:163], v[208:211], v[8:11]
	v_mfma_f32_16x16x32_bf16 v[60:63], v[144:147], v[188:191], v[60:63]
	v_mfma_f32_16x16x32_bf16 v[56:59], v[164:167], v[188:191], v[56:59]
	v_mfma_f32_16x16x32_bf16 v[44:47], v[144:147], v[196:199], v[44:47]
	v_mfma_f32_16x16x32_bf16 v[40:43], v[164:167], v[196:199], v[40:43]
	v_mfma_f32_16x16x32_bf16 v[28:31], v[144:147], v[204:207], v[28:31]
	v_mfma_f32_16x16x32_bf16 v[24:27], v[164:167], v[204:207], v[24:27]
	v_mfma_f32_16x16x32_bf16 v[12:15], v[144:147], v[212:215], v[12:15]
	v_mfma_f32_16x16x32_bf16 v[8:11], v[164:167], v[212:215], v[8:11]
	s_setprio 0
	s_setprio 1
	v_mfma_f32_16x16x32_bf16 v[52:55], v[168:171], v[184:187], v[52:55]
	v_mfma_f32_16x16x32_bf16 v[48:51], v[176:179], v[184:187], v[48:51]
	v_mfma_f32_16x16x32_bf16 v[36:39], v[168:171], v[192:195], v[36:39]
	v_mfma_f32_16x16x32_bf16 v[32:35], v[176:179], v[192:195], v[32:35]
	v_mfma_f32_16x16x32_bf16 v[20:23], v[168:171], v[200:203], v[20:23]
	v_mfma_f32_16x16x32_bf16 v[16:19], v[176:179], v[200:203], v[16:19]
	v_mfma_f32_16x16x32_bf16 v[4:7], v[168:171], v[208:211], v[4:7]
	v_mfma_f32_16x16x32_bf16 v[0:3], v[176:179], v[208:211], v[0:3]
	v_mfma_f32_16x16x32_bf16 v[52:55], v[172:175], v[188:191], v[52:55]
	v_mfma_f32_16x16x32_bf16 v[48:51], v[180:183], v[188:191], v[48:51]
	v_mfma_f32_16x16x32_bf16 v[36:39], v[172:175], v[196:199], v[36:39]
	v_mfma_f32_16x16x32_bf16 v[32:35], v[180:183], v[196:199], v[32:35]
	v_mfma_f32_16x16x32_bf16 v[20:23], v[172:175], v[204:207], v[20:23]
	v_mfma_f32_16x16x32_bf16 v[16:19], v[180:183], v[204:207], v[16:19]
	v_mfma_f32_16x16x32_bf16 v[4:7], v[172:175], v[212:215], v[4:7]
	v_mfma_f32_16x16x32_bf16 v[0:3], v[180:183], v[212:215], v[0:3]
	s_setprio 0
	s_barrier
	s_add_i32 s77, s77, 2
	s_add_u32 s75, s75, 0x100
	s_addc_u32 s76, s76, 0
	s_add_u32 s20, s20, 0x3400
	s_addc_u32 s21, s21, 0
	s_cmp_gt_u32 s77, 29
	s_cbranch_scc0 .LBB0_528
	s_and_b64 vcc, exec, s[28:29]
	s_cbranch_vccz .LBB0_531
	s_barrier

; #define PG8_STAGE(bufoff, gbase, voff) do { _Pragma("unroll") for (int _i = 0; _i < 2; ++_i) \
;         __builtin_amdgcn_global_load_lds((const unsigned*)((const char*)(gbase) + (voff)[_i]), (LAS unsigned*)(lds + (bufoff) + ldsw + _i * 8192), 16, 0, 0); } while (0)
; #define PG8_LDA(dst, b, h) do { _Pragma("unroll") for (int m = 0; m < 4; ++m) _Pragma("unroll") for (int k = 0; k < 2; ++k) dst[m][k] = *(const LAS bf16x8*)(lds + PG8_SA(b, h) + aoff + m * 2048 + k * 1024); } while (0)
; #define PG8_LDB(dst, b, h) do { _Pragma("unroll") for (int n = 0; n < 2; ++n) _Pragma("unroll") for (int k = 0; k < 2; ++k) dst[n][k] = *(const LAS bf16x8*)(lds + PG8_SB(b, h) + boff + n * 2048 + k * 1024); } while (0)
; #define PG8_MMA(ai, bj, At, Bt) do { __builtin_amdgcn_s_setprio(1); _Pragma("unroll") for (int m = 0; m < 4; ++m) _Pragma("unroll") for (int n = 0; n < 2; ++n) _Pragma("unroll") for (int k = 0; k < 2; ++k) \
;         acc[ai][bj][m][n] = __builtin_amdgcn_mfma_f32_16x16x32_bf16(Bt[n][k], At[m][k], acc[ai][bj][m][n], 0, 0, 0); __builtin_amdgcn_s_setprio(0); } while (0)
; #define PG8_WAIT_V(n) asm volatile("s_waitcnt vmcnt(" #n ")" ::: "memory")
; #define PG8_WAIT_L(n) asm volatile("s_waitcnt lgkmcnt(" #n ")" ::: "memory")
; #define PG8_BAR __builtin_amdgcn_s_barrier()
; #define PG8_SCHED __builtin_amdgcn_sched_barrier(0)
; template <class Epi, class Sched, bool ALIGN_EPI = true, bool SP2 = true>
; __device__ __forceinline__ void gemm_phase(LAS unsigned char* lds, const Gemm g, const Sched& S, const Epi& E) {
;     ...
;             PG8_LDB(B0, 0, 0); PG8_LDB(B1, 0, 1); PG8_SCHED; PG8_LDA(At, 0, 0); PG8_STAGE(PG8_SA(1, 1), a1 + hstepA, voffA);
;             PG8_WAIT_V(8); PG8_WAIT_L(0); PG8_BAR; PG8_MMA(0, 0, At, B0); PG8_MMA(0, 1, At, B1); PG8_BAR; PG8_SCHED;
;             PG8_LDA(At, 0, 1); PG8_STAGE(PG8_SB(0, 0), b2, voffB); PG8_STAGE(PG8_SB(0, 1), b2 + hstepB, voffB); PG8_STAGE(PG8_SA(0, 0), a2, voffA);
.LBB0_644:
	s_add_u32 s66, s44, s60
	s_addc_u32 s67, s45, s61
	s_add_u32 s64, s66, 0x100
	s_addc_u32 s65, s67, 0
	s_and_b64 s[62:63], s[58:59], exec
	s_cselect_b32 s63, s41, s65
	s_cselect_b32 s62, s82, s64
	s_add_u32 s60, s26, s60
	s_addc_u32 s61, s27, s61
	s_add_u32 s60, s60, 0x100
	s_addc_u32 s61, s61, 0
	s_and_b64 s[58:59], s[58:59], exec
	s_cselect_b32 s65, s29, s61
	s_cselect_b32 s64, s83, s60
	s_add_u32 s68, s66, 0x10080
	ds_read_b128 v[150:153], v147
	ds_read_b128 v[160:163], v147 offset:1024
	ds_read_b128 v[164:167], v147 offset:2048
	ds_read_b128 v[168:171], v147 offset:3072
	ds_read_b128 v[172:175], v148
	ds_read_b128 v[176:179], v148 offset:1024
	ds_read_b128 v[180:183], v148 offset:2048
	ds_read_b128 v[184:187], v148 offset:3072
	s_addc_u32 s69, s67, 0
	s_add_i32 s95, s78, s3
	s_add_i32 m0, s12, 0xc000
	s_add_i32 s25, s12, 0xe000
	s_add_i32 s70, s95, 0x2000
	s_add_u32 s66, s64, 0x10000
	s_addc_u32 s67, s65, 0
	s_add_i32 vcc_hi, s79, s3
	s_add_i32 vcc_lo, vcc_hi, 0x2000
	s_add_i32 s93, 0, 0x18000
	s_add_i32 s92, 0, 0x1c000
	s_add_u32 s60, s62, 0x10000
	s_addc_u32 s61, s63, 0
	s_add_i32 s91, s93, s3
	s_add_i32 s89, s91, 0x2000
	s_add_u32 s58, s64, 0x10080
	s_addc_u32 s59, s65, 0
	s_add_i32 s90, s92, s3
	s_add_i32 s88, s90, 0x2000
	s_nop 0
	ds_read_b128 v[188:191], v149
	ds_read_b128 v[192:195], v149 offset:1024
	ds_read_b128 v[196:199], v149 offset:2048
	ds_read_b128 v[200:203], v149 offset:3072
	ds_read_b128 v[204:207], v149 offset:4096
	ds_read_b128 v[208:211], v149 offset:5120
	ds_read_b128 v[212:215], v149 offset:6144
	ds_read_b128 v[216:219], v149 offset:7168
	global_load_lds_dwordx4 v128, s[68:69]
	s_nop 0
	s_mov_b32 m0, s25
	s_nop 0
	global_load_lds_dwordx4 v132, s[68:69]
	s_waitcnt vmcnt(8)
	s_waitcnt lgkmcnt(0)
	s_barrier
	s_setprio 1
	s_waitcnt lgkmcnt(0)
	v_mfma_f32_16x16x32_bf16 v[124:127], v[150:153], v[188:191], v[124:127]
	v_mfma_f32_16x16x32_bf16 v[120:123], v[164:167], v[188:191], v[120:123]
	v_mfma_f32_16x16x32_bf16 v[116:119], v[150:153], v[196:199], v[116:119]
	v_mfma_f32_16x16x32_bf16 v[112:115], v[164:167], v[196:199], v[112:115]
	v_mfma_f32_16x16x32_bf16 v[100:103], v[150:153], v[204:207], v[100:103]
	v_mfma_f32_16x16x32_bf16 v[96:99], v[164:167], v[204:207], v[96:99]
	v_mfma_f32_16x16x32_bf16 v[84:87], v[150:153], v[212:215], v[84:87]
	v_mfma_f32_16x16x32_bf16 v[80:83], v[164:167], v[212:215], v[80:83]
	v_mfma_f32_16x16x32_bf16 v[124:127], v[160:163], v[192:195], v[124:127]
	v_mfma_f32_16x16x32_bf16 v[120:123], v[168:171], v[192:195], v[120:123]
	v_mfma_f32_16x16x32_bf16 v[116:119], v[160:163], v[200:203], v[116:119]
	v_mfma_f32_16x16x32_bf16 v[112:115], v[168:171], v[200:203], v[112:115]
	v_mfma_f32_16x16x32_bf16 v[100:103], v[160:163], v[208:211], v[100:103]
	v_mfma_f32_16x16x32_bf16 v[96:99], v[168:171], v[208:211], v[96:99]
	v_mfma_f32_16x16x32_bf16 v[84:87], v[160:163], v[216:219], v[84:87]
	v_mfma_f32_16x16x32_bf16 v[80:83], v[168:171], v[216:219], v[80:83]
	s_setprio 0
	s_setprio 1
	v_mfma_f32_16x16x32_bf16 v[108:111], v[172:175], v[188:191], v[108:111]
	v_mfma_f32_16x16x32_bf16 v[104:107], v[180:183], v[188:191], v[104:107]
	v_mfma_f32_16x16x32_bf16 v[92:95], v[172:175], v[196:199], v[92:95]
	v_mfma_f32_16x16x32_bf16 v[88:91], v[180:183], v[196:199], v[88:91]
	v_mfma_f32_16x16x32_bf16 v[76:79], v[172:175], v[204:207], v[76:79]
	v_mfma_f32_16x16x32_bf16 v[72:75], v[180:183], v[204:207], v[72:75]
	v_mfma_f32_16x16x32_bf16 v[68:71], v[172:175], v[212:215], v[68:71]
	v_mfma_f32_16x16x32_bf16 v[64:67], v[180:183], v[212:215], v[64:67]
	v_mfma_f32_16x16x32_bf16 v[108:111], v[176:179], v[192:195], v[108:111]
	v_mfma_f32_16x16x32_bf16 v[104:107], v[184:187], v[192:195], v[104:107]
	v_mfma_f32_16x16x32_bf16 v[92:95], v[176:179], v[200:203], v[92:95]
	v_mfma_f32_16x16x32_bf16 v[88:91], v[184:187], v[200:203], v[88:91]
	v_mfma_f32_16x16x32_bf16 v[76:79], v[176:179], v[208:211], v[76:79]
	v_mfma_f32_16x16x32_bf16 v[72:75], v[184:187], v[208:211], v[72:75]
	v_mfma_f32_16x16x32_bf16 v[68:71], v[176:179], v[216:219], v[68:71]
	v_mfma_f32_16x16x32_bf16 v[64:67], v[184:187], v[216:219], v[64:67]
	s_setprio 0
	s_barrier
	s_mov_b32 m0, s95
	v_lshl_add_u64 v[154:155], s[64:65], 0, v[130:131]
	ds_read_b128 v[188:191], v149 offset:16384
	ds_read_b128 v[192:195], v149 offset:17408
	ds_read_b128 v[196:199], v149 offset:18432
	ds_read_b128 v[200:203], v149 offset:19456
	ds_read_b128 v[204:207], v149 offset:20480
	ds_read_b128 v[208:211], v149 offset:21504
	ds_read_b128 v[212:215], v149 offset:22528
	ds_read_b128 v[216:219], v149 offset:23552
	global_load_lds_dwordx4 v[154:155], off
	v_lshl_add_u64 v[220:221], s[64:65], 0, v[134:135]
	s_mov_b32 m0, s70
	s_nop 0
	global_load_lds_dwordx4 v[220:221], off
	s_mov_b32 m0, vcc_hi
	v_lshl_add_u64 v[224:225], s[62:63], 0, v[132:133]
	global_load_lds_dwordx4 v130, s[66:67]
	s_nop 0
	s_mov_b32 m0, vcc_lo
	s_nop 0
	global_load_lds_dwordx4 v134, s[66:67]
	v_lshl_add_u64 v[222:223], s[62:63], 0, v[128:129]
	s_mov_b32 m0, s12
	s_nop 0
	global_load_lds_dwordx4 v[222:223], off
	s_mov_b32 m0, s35
	s_nop 0
	global_load_lds_dwordx4 v[224:225], off
	s_waitcnt vmcnt(8)
	s_waitcnt lgkmcnt(0)
	s_barrier
; #define PG8_STAGE(bufoff, gbase, voff) do { _Pragma("unroll") for (int _i = 0; _i < 2; ++_i) \
;         __builtin_amdgcn_global_load_lds((const unsigned*)((const char*)(gbase) + (voff)[_i]), (LAS unsigned*)(lds + (bufoff) + ldsw + _i * 8192), 16, 0, 0); } while (0)
; #define PG8_LDA(dst, b, h) do { _Pragma("unroll") for (int m = 0; m < 4; ++m) _Pragma("unroll") for (int k = 0; k < 2; ++k) dst[m][k] = *(const LAS bf16x8*)(lds + PG8_SA(b, h) + aoff + m * 2048 + k * 1024); } while (0)
; #define PG8_LDB(dst, b, h) do { _Pragma("unroll") for (int n = 0; n < 2; ++n) _Pragma("unroll") for (int k = 0; k < 2; ++k) dst[n][k] = *(const LAS bf16x8*)(lds + PG8_SB(b, h) + boff + n * 2048 + k * 1024); } while (0)
; #define PG8_MMA(ai, bj, At, Bt) do { __builtin_amdgcn_s_setprio(1); _Pragma("unroll") for (int m = 0; m < 4; ++m) _Pragma("unroll") for (int n = 0; n < 2; ++n) _Pragma("unroll") for (int k = 0; k < 2; ++k) \
;         acc[ai][bj][m][n] = __builtin_amdgcn_mfma_f32_16x16x32_bf16(Bt[n][k], At[m][k], acc[ai][bj][m][n], 0, 0, 0); __builtin_amdgcn_s_setprio(0); } while (0)
; #define PG8_WAIT_V(n) asm volatile("s_waitcnt vmcnt(" #n ")" ::: "memory")
; #define PG8_WAIT_L(n) asm volatile("s_waitcnt lgkmcnt(" #n ")" ::: "memory")
; #define PG8_BAR __builtin_amdgcn_s_barrier()
; #define PG8_SCHED __builtin_amdgcn_sched_barrier(0)
; template <class Epi, class Sched, bool ALIGN_EPI = true, bool SP2 = true>
; __device__ __forceinline__ void gemm_phase(LAS unsigned char* lds, const Gemm g, const Sched& S, const Epi& E) {
;     ...
;             PG8_WAIT_V(8); PG8_WAIT_L(0); PG8_BAR; PG8_MMA(1, 0, At, B0); PG8_MMA(1, 1, At, B1); PG8_BAR; PG8_SCHED;
;             PG8_LDB(B0, 1, 0); PG8_LDB(B1, 1, 1); PG8_SCHED; PG8_LDA(At, 1, 0); PG8_STAGE(PG8_SA(0, 1), a2 + hstepA, voffA);
;             PG8_WAIT_V(8); PG8_WAIT_L(0); PG8_BAR; PG8_MMA(0, 0, At, B0); PG8_MMA(0, 1, At, B1); PG8_BAR; PG8_SCHED;
	s_setprio 1
	s_waitcnt lgkmcnt(0)
	v_mfma_f32_16x16x32_bf16 v[60:63], v[150:153], v[188:191], v[60:63]
	v_mfma_f32_16x16x32_bf16 v[56:59], v[164:167], v[188:191], v[56:59]
	v_mfma_f32_16x16x32_bf16 v[52:55], v[150:153], v[196:199], v[52:55]
	v_mfma_f32_16x16x32_bf16 v[48:51], v[164:167], v[196:199], v[48:51]
	v_mfma_f32_16x16x32_bf16 v[36:39], v[150:153], v[204:207], v[36:39]
	v_mfma_f32_16x16x32_bf16 v[32:35], v[164:167], v[204:207], v[32:35]
	v_mfma_f32_16x16x32_bf16 v[20:23], v[150:153], v[212:215], v[20:23]
	v_mfma_f32_16x16x32_bf16 v[16:19], v[164:167], v[212:215], v[16:19]
	v_mfma_f32_16x16x32_bf16 v[60:63], v[160:163], v[192:195], v[60:63]
	v_mfma_f32_16x16x32_bf16 v[56:59], v[168:171], v[192:195], v[56:59]
	v_mfma_f32_16x16x32_bf16 v[52:55], v[160:163], v[200:203], v[52:55]
	v_mfma_f32_16x16x32_bf16 v[48:51], v[168:171], v[200:203], v[48:51]
	v_mfma_f32_16x16x32_bf16 v[36:39], v[160:163], v[208:211], v[36:39]
	v_mfma_f32_16x16x32_bf16 v[32:35], v[168:171], v[208:211], v[32:35]
	v_mfma_f32_16x16x32_bf16 v[20:23], v[160:163], v[216:219], v[20:23]
	v_mfma_f32_16x16x32_bf16 v[16:19], v[168:171], v[216:219], v[16:19]
	s_setprio 0
	s_setprio 1
	v_mfma_f32_16x16x32_bf16 v[44:47], v[172:175], v[188:191], v[44:47]
	v_mfma_f32_16x16x32_bf16 v[40:43], v[180:183], v[188:191], v[40:43]
	v_mfma_f32_16x16x32_bf16 v[28:31], v[172:175], v[196:199], v[28:31]
	v_mfma_f32_16x16x32_bf16 v[24:27], v[180:183], v[196:199], v[24:27]
	v_mfma_f32_16x16x32_bf16 v[12:15], v[172:175], v[204:207], v[12:15]
	v_mfma_f32_16x16x32_bf16 v[8:11], v[180:183], v[204:207], v[8:11]
	v_mfma_f32_16x16x32_bf16 v[4:7], v[172:175], v[212:215], v[4:7]
	v_mfma_f32_16x16x32_bf16 v[0:3], v[180:183], v[212:215], v[0:3]
	v_mfma_f32_16x16x32_bf16 v[44:47], v[176:179], v[192:195], v[44:47]
	v_mfma_f32_16x16x32_bf16 v[40:43], v[184:187], v[192:195], v[40:43]
	v_mfma_f32_16x16x32_bf16 v[28:31], v[176:179], v[200:203], v[28:31]
	v_mfma_f32_16x16x32_bf16 v[24:27], v[184:187], v[200:203], v[24:27]
	v_mfma_f32_16x16x32_bf16 v[12:15], v[176:179], v[208:211], v[12:15]
	v_mfma_f32_16x16x32_bf16 v[8:11], v[184:187], v[208:211], v[8:11]
	v_mfma_f32_16x16x32_bf16 v[4:7], v[176:179], v[216:219], v[4:7]
	v_mfma_f32_16x16x32_bf16 v[0:3], v[184:187], v[216:219], v[0:3]
	s_setprio 0
	s_barrier
	v_add_u32_e32 v157, s93, v145
	ds_read_b128 v[150:153], v157
	ds_read_b128 v[160:163], v157 offset:1024
	ds_read_b128 v[164:167], v157 offset:2048
	ds_read_b128 v[168:171], v157 offset:3072
	v_add_u32_e32 v157, s92, v145
	ds_read_b128 v[172:175], v157
	ds_read_b128 v[176:179], v157 offset:1024
	ds_read_b128 v[180:183], v157 offset:2048
	ds_read_b128 v[184:187], v157 offset:3072
	s_mov_b32 m0, s71
	s_nop 0
	ds_read_b128 v[188:191], v149 offset:32768
	ds_read_b128 v[192:195], v149 offset:33792
	ds_read_b128 v[196:199], v149 offset:34816
	ds_read_b128 v[200:203], v149 offset:35840
	ds_read_b128 v[204:207], v149 offset:36864
	ds_read_b128 v[208:211], v149 offset:37888
	ds_read_b128 v[212:215], v149 offset:38912
	ds_read_b128 v[216:219], v149 offset:39936
	global_load_lds_dwordx4 v128, s[60:61]
	s_nop 0
	s_mov_b32 m0, s72
	s_nop 0
	global_load_lds_dwordx4 v132, s[60:61]
	s_waitcnt vmcnt(8)
	s_waitcnt lgkmcnt(0)
	s_barrier
	s_setprio 1
	s_waitcnt lgkmcnt(0)
	v_mfma_f32_16x16x32_bf16 v[124:127], v[150:153], v[188:191], v[124:127]
	v_mfma_f32_16x16x32_bf16 v[120:123], v[164:167], v[188:191], v[120:123]
	v_mfma_f32_16x16x32_bf16 v[116:119], v[150:153], v[196:199], v[116:119]
	v_mfma_f32_16x16x32_bf16 v[112:115], v[164:167], v[196:199], v[112:115]
	v_mfma_f32_16x16x32_bf16 v[100:103], v[150:153], v[204:207], v[100:103]
	v_mfma_f32_16x16x32_bf16 v[96:99], v[164:167], v[204:207], v[96:99]
	v_mfma_f32_16x16x32_bf16 v[84:87], v[150:153], v[212:215], v[84:87]
	v_mfma_f32_16x16x32_bf16 v[80:83], v[164:167], v[212:215], v[80:83]
	v_mfma_f32_16x16x32_bf16 v[124:127], v[160:163], v[192:195], v[124:127]
	v_mfma_f32_16x16x32_bf16 v[120:123], v[168:171], v[192:195], v[120:123]
	v_mfma_f32_16x16x32_bf16 v[116:119], v[160:163], v[200:203], v[116:119]
	v_mfma_f32_16x16x32_bf16 v[112:115], v[168:171], v[200:203], v[112:115]
	v_mfma_f32_16x16x32_bf16 v[100:103], v[160:163], v[208:211], v[100:103]
	v_mfma_f32_16x16x32_bf16 v[96:99], v[168:171], v[208:211], v[96:99]
	v_mfma_f32_16x16x32_bf16 v[84:87], v[160:163], v[216:219], v[84:87]
	v_mfma_f32_16x16x32_bf16 v[80:83], v[168:171], v[216:219], v[80:83]
	s_setprio 0
	s_setprio 1
	v_mfma_f32_16x16x32_bf16 v[108:111], v[172:175], v[188:191], v[108:111]
	v_mfma_f32_16x16x32_bf16 v[104:107], v[180:183], v[188:191], v[104:107]
	v_mfma_f32_16x16x32_bf16 v[92:95], v[172:175], v[196:199], v[92:95]
	v_mfma_f32_16x16x32_bf16 v[88:91], v[180:183], v[196:199], v[88:91]
	v_mfma_f32_16x16x32_bf16 v[76:79], v[172:175], v[204:207], v[76:79]
	v_mfma_f32_16x16x32_bf16 v[72:75], v[180:183], v[204:207], v[72:75]
	v_mfma_f32_16x16x32_bf16 v[68:71], v[172:175], v[212:215], v[68:71]
	v_mfma_f32_16x16x32_bf16 v[64:67], v[180:183], v[212:215], v[64:67]
	v_mfma_f32_16x16x32_bf16 v[108:111], v[176:179], v[192:195], v[108:111]
	v_mfma_f32_16x16x32_bf16 v[104:107], v[184:187], v[192:195], v[104:107]
	v_mfma_f32_16x16x32_bf16 v[92:95], v[176:179], v[200:203], v[92:95]
	v_mfma_f32_16x16x32_bf16 v[88:91], v[184:187], v[200:203], v[88:91]
	v_mfma_f32_16x16x32_bf16 v[76:79], v[176:179], v[208:211], v[76:79]
	v_mfma_f32_16x16x32_bf16 v[72:75], v[184:187], v[208:211], v[72:75]
	v_mfma_f32_16x16x32_bf16 v[68:71], v[176:179], v[216:219], v[68:71]
	v_mfma_f32_16x16x32_bf16 v[64:67], v[184:187], v[216:219], v[64:67]
	s_setprio 0
	s_barrier
; #define PG8_STAGE(bufoff, gbase, voff) do { _Pragma("unroll") for (int _i = 0; _i < 2; ++_i) \
;         __builtin_amdgcn_global_load_lds((const unsigned*)((const char*)(gbase) + (voff)[_i]), (LAS unsigned*)(lds + (bufoff) + ldsw + _i * 8192), 16, 0, 0); } while (0)
; #define PG8_LDA(dst, b, h) do { _Pragma("unroll") for (int m = 0; m < 4; ++m) _Pragma("unroll") for (int k = 0; k < 2; ++k) dst[m][k] = *(const LAS bf16x8*)(lds + PG8_SA(b, h) + aoff + m * 2048 + k * 1024); } while (0)
; #define PG8_MMA(ai, bj, At, Bt) do { __builtin_amdgcn_s_setprio(1); _Pragma("unroll") for (int m = 0; m < 4; ++m) _Pragma("unroll") for (int n = 0; n < 2; ++n) _Pragma("unroll") for (int k = 0; k < 2; ++k) \
;         acc[ai][bj][m][n] = __builtin_amdgcn_mfma_f32_16x16x32_bf16(Bt[n][k], At[m][k], acc[ai][bj][m][n], 0, 0, 0); __builtin_amdgcn_s_setprio(0); } while (0)
; #define PG8_WAIT_V(n) asm volatile("s_waitcnt vmcnt(" #n ")" ::: "memory")
; #define PG8_WAIT_L(n) asm volatile("s_waitcnt lgkmcnt(" #n ")" ::: "memory")
; #define PG8_BAR __builtin_amdgcn_s_barrier()
; #define PG8_SCHED __builtin_amdgcn_sched_barrier(0)
; template <class Epi, class Sched, bool ALIGN_EPI = true, bool SP2 = true>
; __device__ __forceinline__ void gemm_phase(LAS unsigned char* lds, const Gemm g, const Sched& S, const Epi& E) {
;     ...
;         for (int t = 0; t < nt; t += 2) {
;             const bool last = (t == nt - 2);
;     ...
;             PG8_LDA(At, 1, 1); PG8_STAGE(PG8_SB(1, 0), b3, voffB); PG8_STAGE(PG8_SB(1, 1), b3 + hstepB, voffB); PG8_STAGE(PG8_SA(1, 0), a3, voffA);
;             PG8_WAIT_V(8); PG8_WAIT_L(0); PG8_BAR; PG8_MMA(1, 0, At, B0); PG8_MMA(1, 1, At, B1); PG8_BAR; PG8_SCHED;
	s_mov_b32 m0, s91
	v_lshl_add_u64 v[154:155], v[154:155], 0, s[20:21]
	ds_read_b128 v[188:191], v149 offset:49152
	ds_read_b128 v[192:195], v149 offset:50176
	ds_read_b128 v[196:199], v149 offset:51200
	ds_read_b128 v[200:203], v149 offset:52224
	ds_read_b128 v[204:207], v149 offset:53248
	ds_read_b128 v[208:211], v149 offset:54272
	ds_read_b128 v[212:215], v149 offset:55296
	ds_read_b128 v[216:219], v149 offset:56320
	global_load_lds_dwordx4 v[154:155], off
	v_lshl_add_u64 v[154:155], v[220:221], 0, s[20:21]
	s_mov_b32 m0, s89
	s_nop 0
	global_load_lds_dwordx4 v[154:155], off
	s_nop 0
	s_mov_b32 m0, s90
	s_nop 0
	global_load_lds_dwordx4 v130, s[58:59]
	s_nop 0
	s_mov_b32 m0, s88
	s_nop 0
	global_load_lds_dwordx4 v134, s[58:59]
	v_lshl_add_u64 v[154:155], v[222:223], 0, s[20:21]
	s_mov_b32 m0, s74
	s_nop 0
	global_load_lds_dwordx4 v[154:155], off
	v_lshl_add_u64 v[154:155], v[224:225], 0, s[20:21]
	s_mov_b32 m0, s75
	s_nop 0
	global_load_lds_dwordx4 v[154:155], off
	s_waitcnt vmcnt(8)
	s_waitcnt lgkmcnt(0)
	s_barrier
	s_setprio 1
	s_waitcnt lgkmcnt(0)
	v_mfma_f32_16x16x32_bf16 v[60:63], v[150:153], v[188:191], v[60:63]
	v_mfma_f32_16x16x32_bf16 v[56:59], v[164:167], v[188:191], v[56:59]
	v_mfma_f32_16x16x32_bf16 v[52:55], v[150:153], v[196:199], v[52:55]
	v_mfma_f32_16x16x32_bf16 v[48:51], v[164:167], v[196:199], v[48:51]
	v_mfma_f32_16x16x32_bf16 v[36:39], v[150:153], v[204:207], v[36:39]
	v_mfma_f32_16x16x32_bf16 v[32:35], v[164:167], v[204:207], v[32:35]
	v_mfma_f32_16x16x32_bf16 v[20:23], v[150:153], v[212:215], v[20:23]
	v_mfma_f32_16x16x32_bf16 v[16:19], v[164:167], v[212:215], v[16:19]
	v_mfma_f32_16x16x32_bf16 v[60:63], v[160:163], v[192:195], v[60:63]
	v_mfma_f32_16x16x32_bf16 v[56:59], v[168:171], v[192:195], v[56:59]
	v_mfma_f32_16x16x32_bf16 v[52:55], v[160:163], v[200:203], v[52:55]
	v_mfma_f32_16x16x32_bf16 v[48:51], v[168:171], v[200:203], v[48:51]
	v_mfma_f32_16x16x32_bf16 v[36:39], v[160:163], v[208:211], v[36:39]
	v_mfma_f32_16x16x32_bf16 v[32:35], v[168:171], v[208:211], v[32:35]
	v_mfma_f32_16x16x32_bf16 v[20:23], v[160:163], v[216:219], v[20:23]
	v_mfma_f32_16x16x32_bf16 v[16:19], v[168:171], v[216:219], v[16:19]
	s_setprio 0
	s_setprio 1
	v_mfma_f32_16x16x32_bf16 v[44:47], v[172:175], v[188:191], v[44:47]
	v_mfma_f32_16x16x32_bf16 v[40:43], v[180:183], v[188:191], v[40:43]
	v_mfma_f32_16x16x32_bf16 v[28:31], v[172:175], v[196:199], v[28:31]
	v_mfma_f32_16x16x32_bf16 v[24:27], v[180:183], v[196:199], v[24:27]
	v_mfma_f32_16x16x32_bf16 v[12:15], v[172:175], v[204:207], v[12:15]
	v_mfma_f32_16x16x32_bf16 v[8:11], v[180:183], v[204:207], v[8:11]
	v_mfma_f32_16x16x32_bf16 v[4:7], v[172:175], v[212:215], v[4:7]
	v_mfma_f32_16x16x32_bf16 v[0:3], v[180:183], v[212:215], v[0:3]
	v_mfma_f32_16x16x32_bf16 v[44:47], v[176:179], v[192:195], v[44:47]
	v_mfma_f32_16x16x32_bf16 v[40:43], v[184:187], v[192:195], v[40:43]
	v_mfma_f32_16x16x32_bf16 v[28:31], v[176:179], v[200:203], v[28:31]
	v_mfma_f32_16x16x32_bf16 v[24:27], v[184:187], v[200:203], v[24:27]
	v_mfma_f32_16x16x32_bf16 v[12:15], v[176:179], v[208:211], v[12:15]
	v_mfma_f32_16x16x32_bf16 v[8:11], v[184:187], v[208:211], v[8:11]
	v_mfma_f32_16x16x32_bf16 v[4:7], v[176:179], v[216:219], v[4:7]
	v_mfma_f32_16x16x32_bf16 v[0:3], v[184:187], v[216:219], v[0:3]
	s_setprio 0
	s_barrier
	s_andn2_b64 vcc, exec, s[56:57]
	s_mov_b64 s[58:59], -1
	s_mov_b64 s[56:57], 0
	s_mov_b64 s[60:61], 0x100
	s_cbranch_vccz .LBB0_644
	s_and_b64 vcc, exec, s[22:23]
	s_cbranch_vccz .LBB0_647
	s_barrier

; #define PG8_STAGE(bufoff, gbase, voff) do { _Pragma("unroll") for (int _i = 0; _i < 2; ++_i) \
;         __builtin_amdgcn_global_load_lds((const unsigned*)((const char*)(gbase) + (voff)[_i]), (LAS unsigned*)(lds + (bufoff) + ldsw + _i * 8192), 16, 0, 0); } while (0)
; #define PG8_LDA(dst, b, h) do { _Pragma("unroll") for (int m = 0; m < 4; ++m) _Pragma("unroll") for (int k = 0; k < 2; ++k) dst[m][k] = *(const LAS bf16x8*)(lds + PG8_SA(b, h) + aoff + m * 2048 + k * 1024); } while (0)
; #define PG8_LDB(dst, b, h) do { _Pragma("unroll") for (int n = 0; n < 2; ++n) _Pragma("unroll") for (int k = 0; k < 2; ++k) dst[n][k] = *(const LAS bf16x8*)(lds + PG8_SB(b, h) + boff + n * 2048 + k * 1024); } while (0)
; #define PG8_WAIT_V(n) asm volatile("s_waitcnt vmcnt(" #n ")" ::: "memory")
; #define PG8_WAIT_L(n) asm volatile("s_waitcnt lgkmcnt(" #n ")" ::: "memory")
; #define PG8_BAR __builtin_amdgcn_s_barrier()
; #define PG8_SCHED __builtin_amdgcn_sched_barrier(0)
; template <class Epi, class Sched, bool ALIGN_EPI = true, bool SP2 = true>
; __device__ __forceinline__ void gemm_phase(LAS unsigned char* lds, const Gemm g, const Sched& S, const Epi& E) {
;     ...
;         const bool has_next = S.next(ui + 1, nxt);
;         const char* nA = has_next ? (const char*)g.A + a_unit_off(g, nxt.pm) : cA; const char* nB = has_next ? (const char*)g.Bt + (size_t)nxt.pn * tstepB : cB;
; #pragma nounroll
;         for (int t = 0; t < nt; t += 2) {
;             const bool last = (t == nt - 2);
;             const char* a1 = cA + (size_t)(t + 1) * kstepA;
;             const char* a2 = last ? nA : cA + (size_t)(t + 2) * kstepA; const char* b2 = last ? nB : cB + (size_t)(t + 2) * kstepB;
;             const char* a3 = a2 + kstepA; const char* b3 = b2 + kstepB;
;             if constexpr (SP2) {
;             PG8_LDB(B0, 0, 0); PG8_LDB(B1, 0, 1); PG8_SCHED; PG8_LDA(At, 0, 0); PG8_STAGE(PG8_SA(1, 1), a1 + hstepA, voffA);
;             PG8_WAIT_V(8); PG8_WAIT_L(0); PG8_BAR; PG8_MMA(0, 0, At, B0); PG8_MMA(0, 1, At, B1); PG8_BAR; PG8_SCHED;
;             PG8_LDA(At, 0, 1); PG8_STAGE(PG8_SB(0, 0), b2, voffB); PG8_STAGE(PG8_SB(0, 1), b2 + hstepB, voffB); PG8_STAGE(PG8_SA(0, 0), a2, voffA);
;             PG8_WAIT_V(8); PG8_WAIT_L(0); PG8_BAR; PG8_MMA(1, 0, At, B0); PG8_MMA(1, 1, At, B1); PG8_BAR; PG8_SCHED;
.LBB0_668:
	s_add_u32 s64, s44, s58
	s_addc_u32 s65, s45, s59
	s_add_u32 s62, s64, 0x100
	s_addc_u32 s63, s65, 0
	s_and_b64 s[60:61], s[56:57], exec
	s_cselect_b32 s61, s25, s63
	s_cselect_b32 s60, s78, s62
	s_add_u32 s58, s48, s58
	s_addc_u32 s59, s49, s59
	s_add_u32 s58, s58, 0x100
	s_addc_u32 s59, s59, 0
	s_and_b64 s[56:57], s[56:57], exec
	s_cselect_b32 s63, s23, s59
	s_cselect_b32 s62, s79, s58
	s_add_u32 s66, s64, 0x10080
	ds_read_b128 v[146:149], v139
	ds_read_b128 v[150:153], v139 offset:1024
	ds_read_b128 v[160:163], v139 offset:2048
	ds_read_b128 v[164:167], v139 offset:3072
	ds_read_b128 v[168:171], v144
	ds_read_b128 v[172:175], v144 offset:1024
	ds_read_b128 v[176:179], v144 offset:2048
	ds_read_b128 v[180:183], v144 offset:3072
	s_addc_u32 s67, s65, 0
	s_add_i32 s70, s74, s33
	s_add_i32 m0, s27, 0xc000
	s_add_i32 s93, s27, 0xe000
	s_add_i32 s90, s70, 0x2000
	s_add_u32 s64, s62, 0x10000
	s_addc_u32 s65, s63, 0
	s_add_i32 s92, s75, s33
	s_add_i32 s91, s92, 0x2000
	s_add_i32 s89, 0, 0x18000
	s_add_i32 s88, 0, 0x1c000
	s_add_u32 s58, s60, 0x10000
	s_addc_u32 s59, s61, 0
	s_add_i32 s83, s89, s33
	s_add_i32 s81, s83, 0x2000
	s_add_u32 s56, s62, 0x10080
	s_addc_u32 s57, s63, 0
	s_add_i32 s82, s88, s33
	s_add_i32 s80, s82, 0x2000
	s_nop 0
	ds_read_b128 v[184:187], v145
	ds_read_b128 v[188:191], v145 offset:1024
	ds_read_b128 v[192:195], v145 offset:2048
	ds_read_b128 v[196:199], v145 offset:3072
	ds_read_b128 v[200:203], v145 offset:4096
	ds_read_b128 v[204:207], v145 offset:5120
	ds_read_b128 v[208:211], v145 offset:6144
	ds_read_b128 v[212:215], v145 offset:7168
	global_load_lds_dwordx4 v128, s[66:67]
	s_nop 0
	s_mov_b32 m0, s93
	s_nop 0
	global_load_lds_dwordx4 v132, s[66:67]
	s_waitcnt vmcnt(8)
	s_waitcnt lgkmcnt(0)
	s_barrier
	s_setprio 1
	s_waitcnt lgkmcnt(0)
	v_mfma_f32_16x16x32_bf16 v[124:127], v[146:149], v[184:187], v[124:127]
	v_mfma_f32_16x16x32_bf16 v[120:123], v[160:163], v[184:187], v[120:123]
	v_mfma_f32_16x16x32_bf16 v[116:119], v[146:149], v[192:195], v[116:119]
	v_mfma_f32_16x16x32_bf16 v[112:115], v[160:163], v[192:195], v[112:115]
	v_mfma_f32_16x16x32_bf16 v[100:103], v[146:149], v[200:203], v[100:103]
	v_mfma_f32_16x16x32_bf16 v[96:99], v[160:163], v[200:203], v[96:99]
	v_mfma_f32_16x16x32_bf16 v[84:87], v[146:149], v[208:211], v[84:87]
	v_mfma_f32_16x16x32_bf16 v[80:83], v[160:163], v[208:211], v[80:83]
	v_mfma_f32_16x16x32_bf16 v[124:127], v[150:153], v[188:191], v[124:127]
	v_mfma_f32_16x16x32_bf16 v[120:123], v[164:167], v[188:191], v[120:123]
	v_mfma_f32_16x16x32_bf16 v[116:119], v[150:153], v[196:199], v[116:119]
	v_mfma_f32_16x16x32_bf16 v[112:115], v[164:167], v[196:199], v[112:115]
	v_mfma_f32_16x16x32_bf16 v[100:103], v[150:153], v[204:207], v[100:103]
	v_mfma_f32_16x16x32_bf16 v[96:99], v[164:167], v[204:207], v[96:99]
	v_mfma_f32_16x16x32_bf16 v[84:87], v[150:153], v[212:215], v[84:87]
	v_mfma_f32_16x16x32_bf16 v[80:83], v[164:167], v[212:215], v[80:83]
	s_setprio 0
	s_setprio 1
	v_mfma_f32_16x16x32_bf16 v[108:111], v[168:171], v[184:187], v[108:111]
	v_mfma_f32_16x16x32_bf16 v[104:107], v[176:179], v[184:187], v[104:107]
	v_mfma_f32_16x16x32_bf16 v[92:95], v[168:171], v[192:195], v[92:95]
	v_mfma_f32_16x16x32_bf16 v[88:91], v[176:179], v[192:195], v[88:91]
	v_mfma_f32_16x16x32_bf16 v[76:79], v[168:171], v[200:203], v[76:79]
	v_mfma_f32_16x16x32_bf16 v[72:75], v[176:179], v[200:203], v[72:75]
	v_mfma_f32_16x16x32_bf16 v[68:71], v[168:171], v[208:211], v[68:71]
	v_mfma_f32_16x16x32_bf16 v[64:67], v[176:179], v[208:211], v[64:67]
	v_mfma_f32_16x16x32_bf16 v[108:111], v[172:175], v[188:191], v[108:111]
	v_mfma_f32_16x16x32_bf16 v[104:107], v[180:183], v[188:191], v[104:107]
	v_mfma_f32_16x16x32_bf16 v[92:95], v[172:175], v[196:199], v[92:95]
	v_mfma_f32_16x16x32_bf16 v[88:91], v[180:183], v[196:199], v[88:91]
	v_mfma_f32_16x16x32_bf16 v[76:79], v[172:175], v[204:207], v[76:79]
	v_mfma_f32_16x16x32_bf16 v[72:75], v[180:183], v[204:207], v[72:75]
	v_mfma_f32_16x16x32_bf16 v[68:71], v[172:175], v[212:215], v[68:71]
	v_mfma_f32_16x16x32_bf16 v[64:67], v[180:183], v[212:215], v[64:67]
	s_setprio 0
	s_barrier
	s_mov_b32 m0, s70
	v_lshl_add_u64 v[154:155], s[62:63], 0, v[130:131]
	ds_read_b128 v[184:187], v145 offset:16384
	ds_read_b128 v[188:191], v145 offset:17408
	ds_read_b128 v[192:195], v145 offset:18432
	ds_read_b128 v[196:199], v145 offset:19456
	ds_read_b128 v[200:203], v145 offset:20480
	ds_read_b128 v[204:207], v145 offset:21504
	ds_read_b128 v[208:211], v145 offset:22528
	ds_read_b128 v[212:215], v145 offset:23552
	global_load_lds_dwordx4 v[154:155], off
	v_lshl_add_u64 v[216:217], s[62:63], 0, v[134:135]
	s_mov_b32 m0, s90
	s_nop 0
	global_load_lds_dwordx4 v[216:217], off
	s_mov_b32 m0, s92
	v_lshl_add_u64 v[220:221], s[60:61], 0, v[132:133]
	global_load_lds_dwordx4 v130, s[64:65]
	s_nop 0
	s_mov_b32 m0, s91
	s_nop 0
	global_load_lds_dwordx4 v134, s[64:65]
	v_lshl_add_u64 v[218:219], s[60:61], 0, v[128:129]
	s_mov_b32 m0, s27
	s_nop 0
	global_load_lds_dwordx4 v[218:219], off
	s_mov_b32 m0, s34
	s_nop 0
	global_load_lds_dwordx4 v[220:221], off
	s_waitcnt vmcnt(8)
	s_waitcnt lgkmcnt(0)
	s_barrier
; #define PG8_STAGE(bufoff, gbase, voff) do { _Pragma("unroll") for (int _i = 0; _i < 2; ++_i) \
;         __builtin_amdgcn_global_load_lds((const unsigned*)((const char*)(gbase) + (voff)[_i]), (LAS unsigned*)(lds + (bufoff) + ldsw + _i * 8192), 16, 0, 0); } while (0)
; #define PG8_LDA(dst, b, h) do { _Pragma("unroll") for (int m = 0; m < 4; ++m) _Pragma("unroll") for (int k = 0; k < 2; ++k) dst[m][k] = *(const LAS bf16x8*)(lds + PG8_SA(b, h) + aoff + m * 2048 + k * 1024); } while (0)
; #define PG8_LDB(dst, b, h) do { _Pragma("unroll") for (int n = 0; n < 2; ++n) _Pragma("unroll") for (int k = 0; k < 2; ++k) dst[n][k] = *(const LAS bf16x8*)(lds + PG8_SB(b, h) + boff + n * 2048 + k * 1024); } while (0)
; #define PG8_MMA(ai, bj, At, Bt) do { __builtin_amdgcn_s_setprio(1); _Pragma("unroll") for (int m = 0; m < 4; ++m) _Pragma("unroll") for (int n = 0; n < 2; ++n) _Pragma("unroll") for (int k = 0; k < 2; ++k) \
;         acc[ai][bj][m][n] = __builtin_amdgcn_mfma_f32_16x16x32_bf16(Bt[n][k], At[m][k], acc[ai][bj][m][n], 0, 0, 0); __builtin_amdgcn_s_setprio(0); } while (0)
; #define PG8_WAIT_V(n) asm volatile("s_waitcnt vmcnt(" #n ")" ::: "memory")
; #define PG8_WAIT_L(n) asm volatile("s_waitcnt lgkmcnt(" #n ")" ::: "memory")
; #define PG8_BAR __builtin_amdgcn_s_barrier()
; #define PG8_SCHED __builtin_amdgcn_sched_barrier(0)
; template <class Epi, class Sched, bool ALIGN_EPI = true, bool SP2 = true>
; __device__ __forceinline__ void gemm_phase(LAS unsigned char* lds, const Gemm g, const Sched& S, const Epi& E) {
;     ...
;             PG8_WAIT_V(8); PG8_WAIT_L(0); PG8_BAR; PG8_MMA(1, 0, At, B0); PG8_MMA(1, 1, At, B1); PG8_BAR; PG8_SCHED;
;             PG8_LDB(B0, 1, 0); PG8_LDB(B1, 1, 1); PG8_SCHED; PG8_LDA(At, 1, 0); PG8_STAGE(PG8_SA(0, 1), a2 + hstepA, voffA);
;             PG8_WAIT_V(8); PG8_WAIT_L(0); PG8_BAR; PG8_MMA(0, 0, At, B0); PG8_MMA(0, 1, At, B1); PG8_BAR; PG8_SCHED;
	s_setprio 1
	s_waitcnt lgkmcnt(0)
	v_mfma_f32_16x16x32_bf16 v[60:63], v[146:149], v[184:187], v[60:63]
	v_mfma_f32_16x16x32_bf16 v[56:59], v[160:163], v[184:187], v[56:59]
	v_mfma_f32_16x16x32_bf16 v[52:55], v[146:149], v[192:195], v[52:55]
	v_mfma_f32_16x16x32_bf16 v[48:51], v[160:163], v[192:195], v[48:51]
	v_mfma_f32_16x16x32_bf16 v[36:39], v[146:149], v[200:203], v[36:39]
	v_mfma_f32_16x16x32_bf16 v[32:35], v[160:163], v[200:203], v[32:35]
	v_mfma_f32_16x16x32_bf16 v[20:23], v[146:149], v[208:211], v[20:23]
	v_mfma_f32_16x16x32_bf16 v[16:19], v[160:163], v[208:211], v[16:19]
	v_mfma_f32_16x16x32_bf16 v[60:63], v[150:153], v[188:191], v[60:63]
	v_mfma_f32_16x16x32_bf16 v[56:59], v[164:167], v[188:191], v[56:59]
	v_mfma_f32_16x16x32_bf16 v[52:55], v[150:153], v[196:199], v[52:55]
	v_mfma_f32_16x16x32_bf16 v[48:51], v[164:167], v[196:199], v[48:51]
	v_mfma_f32_16x16x32_bf16 v[36:39], v[150:153], v[204:207], v[36:39]
	v_mfma_f32_16x16x32_bf16 v[32:35], v[164:167], v[204:207], v[32:35]
	v_mfma_f32_16x16x32_bf16 v[20:23], v[150:153], v[212:215], v[20:23]
	v_mfma_f32_16x16x32_bf16 v[16:19], v[164:167], v[212:215], v[16:19]
	s_setprio 0
	s_setprio 1
	v_mfma_f32_16x16x32_bf16 v[44:47], v[168:171], v[184:187], v[44:47]
	v_mfma_f32_16x16x32_bf16 v[40:43], v[176:179], v[184:187], v[40:43]
	v_mfma_f32_16x16x32_bf16 v[28:31], v[168:171], v[192:195], v[28:31]
	v_mfma_f32_16x16x32_bf16 v[24:27], v[176:179], v[192:195], v[24:27]
	v_mfma_f32_16x16x32_bf16 v[12:15], v[168:171], v[200:203], v[12:15]
	v_mfma_f32_16x16x32_bf16 v[8:11], v[176:179], v[200:203], v[8:11]
	v_mfma_f32_16x16x32_bf16 v[4:7], v[168:171], v[208:211], v[4:7]
	v_mfma_f32_16x16x32_bf16 v[0:3], v[176:179], v[208:211], v[0:3]
	v_mfma_f32_16x16x32_bf16 v[44:47], v[172:175], v[188:191], v[44:47]
	v_mfma_f32_16x16x32_bf16 v[40:43], v[180:183], v[188:191], v[40:43]
	v_mfma_f32_16x16x32_bf16 v[28:31], v[172:175], v[196:199], v[28:31]
	v_mfma_f32_16x16x32_bf16 v[24:27], v[180:183], v[196:199], v[24:27]
	v_mfma_f32_16x16x32_bf16 v[12:15], v[172:175], v[204:207], v[12:15]
	v_mfma_f32_16x16x32_bf16 v[8:11], v[180:183], v[204:207], v[8:11]
	v_mfma_f32_16x16x32_bf16 v[4:7], v[172:175], v[212:215], v[4:7]
	v_mfma_f32_16x16x32_bf16 v[0:3], v[180:183], v[212:215], v[0:3]
	s_setprio 0
	s_barrier
	v_add_u32_e32 v157, s89, v137
	ds_read_b128 v[146:149], v157
	ds_read_b128 v[150:153], v157 offset:1024
	ds_read_b128 v[160:163], v157 offset:2048
	ds_read_b128 v[164:167], v157 offset:3072
	v_add_u32_e32 v157, s88, v137
	ds_read_b128 v[168:171], v157
	ds_read_b128 v[172:175], v157 offset:1024
	ds_read_b128 v[176:179], v157 offset:2048
	ds_read_b128 v[180:183], v157 offset:3072
	s_mov_b32 m0, s35
	s_nop 0
	ds_read_b128 v[184:187], v145 offset:32768
	ds_read_b128 v[188:191], v145 offset:33792
	ds_read_b128 v[192:195], v145 offset:34816
	ds_read_b128 v[196:199], v145 offset:35840
	ds_read_b128 v[200:203], v145 offset:36864
	ds_read_b128 v[204:207], v145 offset:37888
	ds_read_b128 v[208:211], v145 offset:38912
	ds_read_b128 v[212:215], v145 offset:39936
	global_load_lds_dwordx4 v128, s[58:59]
	s_nop 0
	s_mov_b32 m0, s68
	s_nop 0
	global_load_lds_dwordx4 v132, s[58:59]
	s_waitcnt vmcnt(8)
	s_waitcnt lgkmcnt(0)
	s_barrier
	s_setprio 1
	s_waitcnt lgkmcnt(0)
	v_mfma_f32_16x16x32_bf16 v[124:127], v[146:149], v[184:187], v[124:127]
	v_mfma_f32_16x16x32_bf16 v[120:123], v[160:163], v[184:187], v[120:123]
	v_mfma_f32_16x16x32_bf16 v[116:119], v[146:149], v[192:195], v[116:119]
	v_mfma_f32_16x16x32_bf16 v[112:115], v[160:163], v[192:195], v[112:115]
	v_mfma_f32_16x16x32_bf16 v[100:103], v[146:149], v[200:203], v[100:103]
	v_mfma_f32_16x16x32_bf16 v[96:99], v[160:163], v[200:203], v[96:99]
	v_mfma_f32_16x16x32_bf16 v[84:87], v[146:149], v[208:211], v[84:87]
	v_mfma_f32_16x16x32_bf16 v[80:83], v[160:163], v[208:211], v[80:83]
	v_mfma_f32_16x16x32_bf16 v[124:127], v[150:153], v[188:191], v[124:127]
	v_mfma_f32_16x16x32_bf16 v[120:123], v[164:167], v[188:191], v[120:123]
	v_mfma_f32_16x16x32_bf16 v[116:119], v[150:153], v[196:199], v[116:119]
	v_mfma_f32_16x16x32_bf16 v[112:115], v[164:167], v[196:199], v[112:115]
	v_mfma_f32_16x16x32_bf16 v[100:103], v[150:153], v[204:207], v[100:103]
	v_mfma_f32_16x16x32_bf16 v[96:99], v[164:167], v[204:207], v[96:99]
	v_mfma_f32_16x16x32_bf16 v[84:87], v[150:153], v[212:215], v[84:87]
	v_mfma_f32_16x16x32_bf16 v[80:83], v[164:167], v[212:215], v[80:83]
	s_setprio 0
	s_setprio 1
	v_mfma_f32_16x16x32_bf16 v[108:111], v[168:171], v[184:187], v[108:111]
	v_mfma_f32_16x16x32_bf16 v[104:107], v[176:179], v[184:187], v[104:107]
	v_mfma_f32_16x16x32_bf16 v[92:95], v[168:171], v[192:195], v[92:95]
	v_mfma_f32_16x16x32_bf16 v[88:91], v[176:179], v[192:195], v[88:91]
	v_mfma_f32_16x16x32_bf16 v[76:79], v[168:171], v[200:203], v[76:79]
	v_mfma_f32_16x16x32_bf16 v[72:75], v[176:179], v[200:203], v[72:75]
	v_mfma_f32_16x16x32_bf16 v[68:71], v[168:171], v[208:211], v[68:71]
	v_mfma_f32_16x16x32_bf16 v[64:67], v[176:179], v[208:211], v[64:67]
	v_mfma_f32_16x16x32_bf16 v[108:111], v[172:175], v[188:191], v[108:111]
	v_mfma_f32_16x16x32_bf16 v[104:107], v[180:183], v[188:191], v[104:107]
	v_mfma_f32_16x16x32_bf16 v[92:95], v[172:175], v[196:199], v[92:95]
	v_mfma_f32_16x16x32_bf16 v[88:91], v[180:183], v[196:199], v[88:91]
	v_mfma_f32_16x16x32_bf16 v[76:79], v[172:175], v[204:207], v[76:79]
	v_mfma_f32_16x16x32_bf16 v[72:75], v[180:183], v[204:207], v[72:75]
	v_mfma_f32_16x16x32_bf16 v[68:71], v[172:175], v[212:215], v[68:71]
	v_mfma_f32_16x16x32_bf16 v[64:67], v[180:183], v[212:215], v[64:67]
	s_setprio 0
	s_barrier
; #define PG8_STAGE(bufoff, gbase, voff) do { _Pragma("unroll") for (int _i = 0; _i < 2; ++_i) \
;         __builtin_amdgcn_global_load_lds((const unsigned*)((const char*)(gbase) + (voff)[_i]), (LAS unsigned*)(lds + (bufoff) + ldsw + _i * 8192), 16, 0, 0); } while (0)
; #define PG8_LDA(dst, b, h) do { _Pragma("unroll") for (int m = 0; m < 4; ++m) _Pragma("unroll") for (int k = 0; k < 2; ++k) dst[m][k] = *(const LAS bf16x8*)(lds + PG8_SA(b, h) + aoff + m * 2048 + k * 1024); } while (0)
; #define PG8_MMA(ai, bj, At, Bt) do { __builtin_amdgcn_s_setprio(1); _Pragma("unroll") for (int m = 0; m < 4; ++m) _Pragma("unroll") for (int n = 0; n < 2; ++n) _Pragma("unroll") for (int k = 0; k < 2; ++k) \
;         acc[ai][bj][m][n] = __builtin_amdgcn_mfma_f32_16x16x32_bf16(Bt[n][k], At[m][k], acc[ai][bj][m][n], 0, 0, 0); __builtin_amdgcn_s_setprio(0); } while (0)
; #define PG8_WAIT_V(n) asm volatile("s_waitcnt vmcnt(" #n ")" ::: "memory")
; #define PG8_WAIT_L(n) asm volatile("s_waitcnt lgkmcnt(" #n ")" ::: "memory")
; #define PG8_BAR __builtin_amdgcn_s_barrier()
; #define PG8_SCHED __builtin_amdgcn_sched_barrier(0)
; template <class Epi, class Sched, bool ALIGN_EPI = true, bool SP2 = true>
; __device__ __forceinline__ void gemm_phase(LAS unsigned char* lds, const Gemm g, const Sched& S, const Epi& E) {
;     ...
;         for (int t = 0; t < nt; t += 2) {
;             const bool last = (t == nt - 2);
;     ...
;             PG8_LDA(At, 1, 1); PG8_STAGE(PG8_SB(1, 0), b3, voffB); PG8_STAGE(PG8_SB(1, 1), b3 + hstepB, voffB); PG8_STAGE(PG8_SA(1, 0), a3, voffA);
;             PG8_WAIT_V(8); PG8_WAIT_L(0); PG8_BAR; PG8_MMA(1, 0, At, B0); PG8_MMA(1, 1, At, B1); PG8_BAR; PG8_SCHED;
	s_mov_b32 m0, s83
	v_lshl_add_u64 v[154:155], v[154:155], 0, s[12:13]
	ds_read_b128 v[184:187], v145 offset:49152
	ds_read_b128 v[188:191], v145 offset:50176
	ds_read_b128 v[192:195], v145 offset:51200
	ds_read_b128 v[196:199], v145 offset:52224
	ds_read_b128 v[200:203], v145 offset:53248
	ds_read_b128 v[204:207], v145 offset:54272
	ds_read_b128 v[208:211], v145 offset:55296
	ds_read_b128 v[212:215], v145 offset:56320
	global_load_lds_dwordx4 v[154:155], off
	v_lshl_add_u64 v[154:155], v[216:217], 0, s[12:13]
	s_mov_b32 m0, s81
	s_nop 0
	global_load_lds_dwordx4 v[154:155], off
	s_nop 0
	s_mov_b32 m0, s82
	s_nop 0
	global_load_lds_dwordx4 v130, s[56:57]
	s_nop 0
	s_mov_b32 m0, s80
	s_nop 0
	global_load_lds_dwordx4 v134, s[56:57]
	v_lshl_add_u64 v[154:155], v[218:219], 0, s[12:13]
	s_mov_b32 m0, s69
	s_nop 0
	global_load_lds_dwordx4 v[154:155], off
	v_lshl_add_u64 v[154:155], v[220:221], 0, s[12:13]
	s_mov_b32 m0, s71
	s_nop 0
	global_load_lds_dwordx4 v[154:155], off
	s_waitcnt vmcnt(8)
	s_waitcnt lgkmcnt(0)
	s_barrier
	s_setprio 1
	s_waitcnt lgkmcnt(0)
	v_mfma_f32_16x16x32_bf16 v[60:63], v[146:149], v[184:187], v[60:63]
	v_mfma_f32_16x16x32_bf16 v[56:59], v[160:163], v[184:187], v[56:59]
	v_mfma_f32_16x16x32_bf16 v[52:55], v[146:149], v[192:195], v[52:55]
	v_mfma_f32_16x16x32_bf16 v[48:51], v[160:163], v[192:195], v[48:51]
	v_mfma_f32_16x16x32_bf16 v[36:39], v[146:149], v[200:203], v[36:39]
	v_mfma_f32_16x16x32_bf16 v[32:35], v[160:163], v[200:203], v[32:35]
	v_mfma_f32_16x16x32_bf16 v[20:23], v[146:149], v[208:211], v[20:23]
	v_mfma_f32_16x16x32_bf16 v[16:19], v[160:163], v[208:211], v[16:19]
	v_mfma_f32_16x16x32_bf16 v[60:63], v[150:153], v[188:191], v[60:63]
	v_mfma_f32_16x16x32_bf16 v[56:59], v[164:167], v[188:191], v[56:59]
	v_mfma_f32_16x16x32_bf16 v[52:55], v[150:153], v[196:199], v[52:55]
	v_mfma_f32_16x16x32_bf16 v[48:51], v[164:167], v[196:199], v[48:51]
	v_mfma_f32_16x16x32_bf16 v[36:39], v[150:153], v[204:207], v[36:39]
	v_mfma_f32_16x16x32_bf16 v[32:35], v[164:167], v[204:207], v[32:35]
	v_mfma_f32_16x16x32_bf16 v[20:23], v[150:153], v[212:215], v[20:23]
	v_mfma_f32_16x16x32_bf16 v[16:19], v[164:167], v[212:215], v[16:19]
	s_setprio 0
	s_setprio 1
	v_mfma_f32_16x16x32_bf16 v[44:47], v[168:171], v[184:187], v[44:47]
	v_mfma_f32_16x16x32_bf16 v[40:43], v[176:179], v[184:187], v[40:43]
	v_mfma_f32_16x16x32_bf16 v[28:31], v[168:171], v[192:195], v[28:31]
	v_mfma_f32_16x16x32_bf16 v[24:27], v[176:179], v[192:195], v[24:27]
	v_mfma_f32_16x16x32_bf16 v[12:15], v[168:171], v[200:203], v[12:15]
	v_mfma_f32_16x16x32_bf16 v[8:11], v[176:179], v[200:203], v[8:11]
	v_mfma_f32_16x16x32_bf16 v[4:7], v[168:171], v[208:211], v[4:7]
	v_mfma_f32_16x16x32_bf16 v[0:3], v[176:179], v[208:211], v[0:3]
	v_mfma_f32_16x16x32_bf16 v[44:47], v[172:175], v[188:191], v[44:47]
	v_mfma_f32_16x16x32_bf16 v[40:43], v[180:183], v[188:191], v[40:43]
	v_mfma_f32_16x16x32_bf16 v[28:31], v[172:175], v[196:199], v[28:31]
	v_mfma_f32_16x16x32_bf16 v[24:27], v[180:183], v[196:199], v[24:27]
	v_mfma_f32_16x16x32_bf16 v[12:15], v[172:175], v[204:207], v[12:15]
	v_mfma_f32_16x16x32_bf16 v[8:11], v[180:183], v[204:207], v[8:11]
	v_mfma_f32_16x16x32_bf16 v[4:7], v[172:175], v[212:215], v[4:7]
	v_mfma_f32_16x16x32_bf16 v[0:3], v[180:183], v[212:215], v[0:3]
	s_setprio 0
	s_barrier
	s_andn2_b64 vcc, exec, s[54:55]
	s_mov_b64 s[56:57], -1
	s_mov_b64 s[54:55], 0
	s_mov_b64 s[58:59], 0x100
	s_cbranch_vccz .LBB0_668
	s_and_b64 vcc, exec, s[14:15]
	s_cbranch_vccz .LBB0_671
	s_barrier

; #define PG8_STAGE(bufoff, gbase, voff) do { _Pragma("unroll") for (int _i = 0; _i < 2; ++_i) \
;         __builtin_amdgcn_global_load_lds((const unsigned*)((const char*)(gbase) + (voff)[_i]), (LAS unsigned*)(lds + (bufoff) + ldsw + _i * 8192), 16, 0, 0); } while (0)
; #define PG8_LDA(dst, b, h) do { _Pragma("unroll") for (int m = 0; m < 4; ++m) _Pragma("unroll") for (int k = 0; k < 2; ++k) dst[m][k] = *(const LAS bf16x8*)(lds + PG8_SA(b, h) + aoff + m * 2048 + k * 1024); } while (0)
; #define PG8_LDB(dst, b, h) do { _Pragma("unroll") for (int n = 0; n < 2; ++n) _Pragma("unroll") for (int k = 0; k < 2; ++k) dst[n][k] = *(const LAS bf16x8*)(lds + PG8_SB(b, h) + boff + n * 2048 + k * 1024); } while (0)
; #define PG8_MMA(ai, bj, At, Bt) do { __builtin_amdgcn_s_setprio(1); _Pragma("unroll") for (int m = 0; m < 4; ++m) _Pragma("unroll") for (int n = 0; n < 2; ++n) _Pragma("unroll") for (int k = 0; k < 2; ++k) \
;         acc[ai][bj][m][n] = __builtin_amdgcn_mfma_f32_16x16x32_bf16(Bt[n][k], At[m][k], acc[ai][bj][m][n], 0, 0, 0); __builtin_amdgcn_s_setprio(0); } while (0)
; #define PG8_WAIT_V(n) asm volatile("s_waitcnt vmcnt(" #n ")" ::: "memory")
; #define PG8_WAIT_L(n) asm volatile("s_waitcnt lgkmcnt(" #n ")" ::: "memory")
; #define PG8_BAR __builtin_amdgcn_s_barrier()
; template <class Epi, class Sched, bool ALIGN_EPI = true, bool SP2 = true>
; __device__ __forceinline__ void gemm_phase(LAS unsigned char* lds, const Gemm g, const Sched& S, const Epi& E) {
;     ...
;         for (int t = 0; t < nt; t += 2) {
;             const bool last = (t == nt - 2);
;             const char* a1 = cA + (size_t)(t + 1) * kstepA;
;             const char* a2 = last ? nA : cA + (size_t)(t + 2) * kstepA; const char* b2 = last ? nB : cB + (size_t)(t + 2) * kstepB;
;             const char* a3 = a2 + kstepA; const char* b3 = b2 + kstepB;
;             if constexpr (SP2) {
;             PG8_LDB(B0, 0, 0); PG8_LDB(B1, 0, 1); PG8_SCHED; PG8_LDA(At, 0, 0); PG8_STAGE(PG8_SA(1, 1), a1 + hstepA, voffA);
;             PG8_WAIT_V(8); PG8_WAIT_L(0); PG8_BAR; PG8_MMA(0, 0, At, B0); PG8_MMA(0, 1, At, B1); PG8_BAR; PG8_SCHED;
;             PG8_LDA(At, 0, 1); PG8_STAGE(PG8_SB(0, 0), b2, voffB); PG8_STAGE(PG8_SB(0, 1), b2 + hstepB, voffB); PG8_STAGE(PG8_SA(0, 0), a2, voffA);
;             PG8_WAIT_V(8); PG8_WAIT_L(0); PG8_BAR; PG8_MMA(1, 0, At, B0); PG8_MMA(1, 1, At, B1); PG8_BAR; PG8_SCHED;
.LBB0_1483:
	ds_read_b128 v[144:147], v151
	ds_read_b128 v[160:163], v151 offset:1024
	ds_read_b128 v[164:167], v151 offset:2048
	ds_read_b128 v[168:171], v151 offset:3072
	ds_read_b128 v[172:175], v152
	ds_read_b128 v[176:179], v152 offset:1024
	ds_read_b128 v[180:183], v152 offset:2048
	ds_read_b128 v[184:187], v152 offset:3072
	s_add_u32 s30, s28, 0xfffc0080
	s_addc_u32 s31, s29, -1
	s_cmp_eq_u32 s61, 12
	s_cselect_b32 s41, s21, s31
	s_cselect_b32 s40, s27, s30
	s_cselect_b32 s31, s19, s60
	s_cselect_b32 s30, s58, s59
	s_nop 0
	s_add_i32 m0, s33, 0xc000
	ds_read_b128 v[188:191], v153
	ds_read_b128 v[192:195], v153 offset:1024
	ds_read_b128 v[196:199], v153 offset:2048
	ds_read_b128 v[200:203], v153 offset:3072
	ds_read_b128 v[204:207], v153 offset:4096
	ds_read_b128 v[208:211], v153 offset:5120
	ds_read_b128 v[212:215], v153 offset:6144
	ds_read_b128 v[216:219], v153 offset:7168
	global_load_lds_dwordx4 v136, s[28:29]
	s_nop 0
	s_add_i32 m0, s33, 0xe000
	s_nop 0
	global_load_lds_dwordx4 v138, s[28:29]
	s_waitcnt vmcnt(8)
	s_waitcnt lgkmcnt(0)
	s_barrier
	s_setprio 1
	s_waitcnt lgkmcnt(0)
	v_mfma_f32_16x16x32_bf16 v[124:127], v[144:147], v[188:191], v[124:127]
	v_mfma_f32_16x16x32_bf16 v[120:123], v[164:167], v[188:191], v[120:123]
	v_mfma_f32_16x16x32_bf16 v[108:111], v[144:147], v[196:199], v[108:111]
	v_mfma_f32_16x16x32_bf16 v[104:107], v[164:167], v[196:199], v[104:107]
	v_mfma_f32_16x16x32_bf16 v[92:95], v[144:147], v[204:207], v[92:95]
	v_mfma_f32_16x16x32_bf16 v[88:91], v[164:167], v[204:207], v[88:91]
	v_mfma_f32_16x16x32_bf16 v[76:79], v[144:147], v[212:215], v[76:79]
	v_mfma_f32_16x16x32_bf16 v[72:75], v[164:167], v[212:215], v[72:75]
	v_mfma_f32_16x16x32_bf16 v[124:127], v[160:163], v[192:195], v[124:127]
	v_mfma_f32_16x16x32_bf16 v[120:123], v[168:171], v[192:195], v[120:123]
	v_mfma_f32_16x16x32_bf16 v[108:111], v[160:163], v[200:203], v[108:111]
	v_mfma_f32_16x16x32_bf16 v[104:107], v[168:171], v[200:203], v[104:107]
	v_mfma_f32_16x16x32_bf16 v[92:95], v[160:163], v[208:211], v[92:95]
	v_mfma_f32_16x16x32_bf16 v[88:91], v[168:171], v[208:211], v[88:91]
	v_mfma_f32_16x16x32_bf16 v[76:79], v[160:163], v[216:219], v[76:79]
	v_mfma_f32_16x16x32_bf16 v[72:75], v[168:171], v[216:219], v[72:75]
	s_setprio 0
	s_setprio 1
	v_mfma_f32_16x16x32_bf16 v[116:119], v[172:175], v[188:191], v[116:119]
	v_mfma_f32_16x16x32_bf16 v[112:115], v[180:183], v[188:191], v[112:115]
	v_mfma_f32_16x16x32_bf16 v[100:103], v[172:175], v[196:199], v[100:103]
	v_mfma_f32_16x16x32_bf16 v[96:99], v[180:183], v[196:199], v[96:99]
	v_mfma_f32_16x16x32_bf16 v[84:87], v[172:175], v[204:207], v[84:87]
	v_mfma_f32_16x16x32_bf16 v[80:83], v[180:183], v[204:207], v[80:83]
	v_mfma_f32_16x16x32_bf16 v[68:71], v[172:175], v[212:215], v[68:71]
	v_mfma_f32_16x16x32_bf16 v[64:67], v[180:183], v[212:215], v[64:67]
	v_mfma_f32_16x16x32_bf16 v[116:119], v[176:179], v[192:195], v[116:119]
	v_mfma_f32_16x16x32_bf16 v[112:115], v[184:187], v[192:195], v[112:115]
	v_mfma_f32_16x16x32_bf16 v[100:103], v[176:179], v[200:203], v[100:103]
	v_mfma_f32_16x16x32_bf16 v[96:99], v[184:187], v[200:203], v[96:99]
	v_mfma_f32_16x16x32_bf16 v[84:87], v[176:179], v[208:211], v[84:87]
	v_mfma_f32_16x16x32_bf16 v[80:83], v[184:187], v[208:211], v[80:83]
	v_mfma_f32_16x16x32_bf16 v[68:71], v[176:179], v[216:219], v[68:71]
	v_mfma_f32_16x16x32_bf16 v[64:67], v[184:187], v[216:219], v[64:67]
	s_setprio 0
	s_barrier
	s_add_i32 s62, s55, s3
	v_lshl_add_u64 v[220:221], s[30:31], 0, v[130:131]
	s_mov_b32 m0, s62
	ds_read_b128 v[188:191], v153 offset:16384
	ds_read_b128 v[192:195], v153 offset:17408
	ds_read_b128 v[196:199], v153 offset:18432
	ds_read_b128 v[200:203], v153 offset:19456
	ds_read_b128 v[204:207], v153 offset:20480
	ds_read_b128 v[208:211], v153 offset:21504
	ds_read_b128 v[212:215], v153 offset:22528
	ds_read_b128 v[216:219], v153 offset:23552
	global_load_lds_dwordx4 v[220:221], off
	s_add_i32 m0, s62, 0x2000
	s_add_u32 s62, s30, 0x40000
	v_lshl_add_u64 v[222:223], s[30:31], 0, v[134:135]
	s_addc_u32 s63, s31, 0
	s_add_i32 s64, s56, s3
	global_load_lds_dwordx4 v[222:223], off
	s_nop 0
	s_mov_b32 m0, s64
	v_lshl_add_u64 v[226:227], s[40:41], 0, v[132:133]
	global_load_lds_dwordx4 v130, s[62:63]
	s_nop 0
	s_add_i32 m0, s64, 0x2000
	s_nop 0
	global_load_lds_dwordx4 v134, s[62:63]
	v_lshl_add_u64 v[224:225], s[40:41], 0, v[128:129]
	s_mov_b32 m0, s33
	s_nop 0
	global_load_lds_dwordx4 v[224:225], off
	s_mov_b32 m0, s34
	s_nop 0
	global_load_lds_dwordx4 v[226:227], off
	s_waitcnt vmcnt(8)
	s_waitcnt lgkmcnt(0)
	s_barrier
; #define PG8_STAGE(bufoff, gbase, voff) do { _Pragma("unroll") for (int _i = 0; _i < 2; ++_i) \
;         __builtin_amdgcn_global_load_lds((const unsigned*)((const char*)(gbase) + (voff)[_i]), (LAS unsigned*)(lds + (bufoff) + ldsw + _i * 8192), 16, 0, 0); } while (0)
; #define PG8_LDA(dst, b, h) do { _Pragma("unroll") for (int m = 0; m < 4; ++m) _Pragma("unroll") for (int k = 0; k < 2; ++k) dst[m][k] = *(const LAS bf16x8*)(lds + PG8_SA(b, h) + aoff + m * 2048 + k * 1024); } while (0)
; #define PG8_LDB(dst, b, h) do { _Pragma("unroll") for (int n = 0; n < 2; ++n) _Pragma("unroll") for (int k = 0; k < 2; ++k) dst[n][k] = *(const LAS bf16x8*)(lds + PG8_SB(b, h) + boff + n * 2048 + k * 1024); } while (0)
; #define PG8_MMA(ai, bj, At, Bt) do { __builtin_amdgcn_s_setprio(1); _Pragma("unroll") for (int m = 0; m < 4; ++m) _Pragma("unroll") for (int n = 0; n < 2; ++n) _Pragma("unroll") for (int k = 0; k < 2; ++k) \
;         acc[ai][bj][m][n] = __builtin_amdgcn_mfma_f32_16x16x32_bf16(Bt[n][k], At[m][k], acc[ai][bj][m][n], 0, 0, 0); __builtin_amdgcn_s_setprio(0); } while (0)
; #define PG8_WAIT_V(n) asm volatile("s_waitcnt vmcnt(" #n ")" ::: "memory")
; #define PG8_WAIT_L(n) asm volatile("s_waitcnt lgkmcnt(" #n ")" ::: "memory")
; #define PG8_BAR __builtin_amdgcn_s_barrier()
; #define PG8_SCHED __builtin_amdgcn_sched_barrier(0)
; template <class Epi, class Sched, bool ALIGN_EPI = true, bool SP2 = true>
; __device__ __forceinline__ void gemm_phase(LAS unsigned char* lds, const Gemm g, const Sched& S, const Epi& E) {
;     ...
;             PG8_WAIT_V(8); PG8_WAIT_L(0); PG8_BAR; PG8_MMA(1, 0, At, B0); PG8_MMA(1, 1, At, B1); PG8_BAR; PG8_SCHED;
;             PG8_LDB(B0, 1, 0); PG8_LDB(B1, 1, 1); PG8_SCHED; PG8_LDA(At, 1, 0); PG8_STAGE(PG8_SA(0, 1), a2 + hstepA, voffA);
;             PG8_WAIT_V(8); PG8_WAIT_L(0); PG8_BAR; PG8_MMA(0, 0, At, B0); PG8_MMA(0, 1, At, B1); PG8_BAR; PG8_SCHED;
	s_setprio 1
	s_waitcnt lgkmcnt(0)
	v_mfma_f32_16x16x32_bf16 v[60:63], v[144:147], v[188:191], v[60:63]
	v_mfma_f32_16x16x32_bf16 v[56:59], v[164:167], v[188:191], v[56:59]
	v_mfma_f32_16x16x32_bf16 v[44:47], v[144:147], v[196:199], v[44:47]
	v_mfma_f32_16x16x32_bf16 v[40:43], v[164:167], v[196:199], v[40:43]
	v_mfma_f32_16x16x32_bf16 v[28:31], v[144:147], v[204:207], v[28:31]
	v_mfma_f32_16x16x32_bf16 v[24:27], v[164:167], v[204:207], v[24:27]
	v_mfma_f32_16x16x32_bf16 v[12:15], v[144:147], v[212:215], v[12:15]
	v_mfma_f32_16x16x32_bf16 v[8:11], v[164:167], v[212:215], v[8:11]
	v_mfma_f32_16x16x32_bf16 v[60:63], v[160:163], v[192:195], v[60:63]
	v_mfma_f32_16x16x32_bf16 v[56:59], v[168:171], v[192:195], v[56:59]
	v_mfma_f32_16x16x32_bf16 v[44:47], v[160:163], v[200:203], v[44:47]
	v_mfma_f32_16x16x32_bf16 v[40:43], v[168:171], v[200:203], v[40:43]
	v_mfma_f32_16x16x32_bf16 v[28:31], v[160:163], v[208:211], v[28:31]
	v_mfma_f32_16x16x32_bf16 v[24:27], v[168:171], v[208:211], v[24:27]
	v_mfma_f32_16x16x32_bf16 v[12:15], v[160:163], v[216:219], v[12:15]
	v_mfma_f32_16x16x32_bf16 v[8:11], v[168:171], v[216:219], v[8:11]
	s_setprio 0
	s_setprio 1
	v_mfma_f32_16x16x32_bf16 v[52:55], v[172:175], v[188:191], v[52:55]
	v_mfma_f32_16x16x32_bf16 v[48:51], v[180:183], v[188:191], v[48:51]
	v_mfma_f32_16x16x32_bf16 v[36:39], v[172:175], v[196:199], v[36:39]
	v_mfma_f32_16x16x32_bf16 v[32:35], v[180:183], v[196:199], v[32:35]
	v_mfma_f32_16x16x32_bf16 v[20:23], v[172:175], v[204:207], v[20:23]
	v_mfma_f32_16x16x32_bf16 v[16:19], v[180:183], v[204:207], v[16:19]
	v_mfma_f32_16x16x32_bf16 v[4:7], v[172:175], v[212:215], v[4:7]
	v_mfma_f32_16x16x32_bf16 v[0:3], v[180:183], v[212:215], v[0:3]
	v_mfma_f32_16x16x32_bf16 v[52:55], v[176:179], v[192:195], v[52:55]
	v_mfma_f32_16x16x32_bf16 v[48:51], v[184:187], v[192:195], v[48:51]
	v_mfma_f32_16x16x32_bf16 v[36:39], v[176:179], v[200:203], v[36:39]
	v_mfma_f32_16x16x32_bf16 v[32:35], v[184:187], v[200:203], v[32:35]
	v_mfma_f32_16x16x32_bf16 v[20:23], v[176:179], v[208:211], v[20:23]
	v_mfma_f32_16x16x32_bf16 v[16:19], v[184:187], v[208:211], v[16:19]
	v_mfma_f32_16x16x32_bf16 v[4:7], v[176:179], v[216:219], v[4:7]
	v_mfma_f32_16x16x32_bf16 v[0:3], v[184:187], v[216:219], v[0:3]
	s_setprio 0
	s_barrier
	s_add_i32 s62, 0, 0x18000
	v_add_u32_e32 v155, s62, v149
	s_add_i32 s63, 0, 0x1c000
	ds_read_b128 v[144:147], v155
	ds_read_b128 v[160:163], v155 offset:1024
	ds_read_b128 v[164:167], v155 offset:2048
	ds_read_b128 v[168:171], v155 offset:3072
	v_add_u32_e32 v155, s63, v149
	ds_read_b128 v[172:175], v155
	ds_read_b128 v[176:179], v155 offset:1024
	ds_read_b128 v[180:183], v155 offset:2048
	ds_read_b128 v[184:187], v155 offset:3072
	s_add_u32 s40, s40, 0x40000
	s_addc_u32 s41, s41, 0
	s_mov_b32 m0, s35
	s_nop 0
	ds_read_b128 v[188:191], v153 offset:32768
	ds_read_b128 v[192:195], v153 offset:33792
	ds_read_b128 v[196:199], v153 offset:34816
	ds_read_b128 v[200:203], v153 offset:35840
	ds_read_b128 v[204:207], v153 offset:36864
	ds_read_b128 v[208:211], v153 offset:37888
	ds_read_b128 v[212:215], v153 offset:38912
	ds_read_b128 v[216:219], v153 offset:39936
	global_load_lds_dwordx4 v128, s[40:41]
	s_nop 0
	s_mov_b32 m0, s44
	s_nop 0
	global_load_lds_dwordx4 v132, s[40:41]
	s_waitcnt vmcnt(8)
	s_waitcnt lgkmcnt(0)
	s_barrier
	s_setprio 1
	s_waitcnt lgkmcnt(0)
	v_mfma_f32_16x16x32_bf16 v[124:127], v[144:147], v[188:191], v[124:127]
	v_mfma_f32_16x16x32_bf16 v[120:123], v[164:167], v[188:191], v[120:123]
	v_mfma_f32_16x16x32_bf16 v[108:111], v[144:147], v[196:199], v[108:111]
	v_mfma_f32_16x16x32_bf16 v[104:107], v[164:167], v[196:199], v[104:107]
	v_mfma_f32_16x16x32_bf16 v[92:95], v[144:147], v[204:207], v[92:95]
	v_mfma_f32_16x16x32_bf16 v[88:91], v[164:167], v[204:207], v[88:91]
	v_mfma_f32_16x16x32_bf16 v[76:79], v[144:147], v[212:215], v[76:79]
	v_mfma_f32_16x16x32_bf16 v[72:75], v[164:167], v[212:215], v[72:75]
	v_mfma_f32_16x16x32_bf16 v[124:127], v[160:163], v[192:195], v[124:127]
	v_mfma_f32_16x16x32_bf16 v[120:123], v[168:171], v[192:195], v[120:123]
	v_mfma_f32_16x16x32_bf16 v[108:111], v[160:163], v[200:203], v[108:111]
	v_mfma_f32_16x16x32_bf16 v[104:107], v[168:171], v[200:203], v[104:107]
	v_mfma_f32_16x16x32_bf16 v[92:95], v[160:163], v[208:211], v[92:95]
	v_mfma_f32_16x16x32_bf16 v[88:91], v[168:171], v[208:211], v[88:91]
	v_mfma_f32_16x16x32_bf16 v[76:79], v[160:163], v[216:219], v[76:79]
	v_mfma_f32_16x16x32_bf16 v[72:75], v[168:171], v[216:219], v[72:75]
	s_setprio 0
	s_setprio 1
	v_mfma_f32_16x16x32_bf16 v[116:119], v[172:175], v[188:191], v[116:119]
	v_mfma_f32_16x16x32_bf16 v[112:115], v[180:183], v[188:191], v[112:115]
	v_mfma_f32_16x16x32_bf16 v[100:103], v[172:175], v[196:199], v[100:103]
	v_mfma_f32_16x16x32_bf16 v[96:99], v[180:183], v[196:199], v[96:99]
	v_mfma_f32_16x16x32_bf16 v[84:87], v[172:175], v[204:207], v[84:87]
	v_mfma_f32_16x16x32_bf16 v[80:83], v[180:183], v[204:207], v[80:83]
	v_mfma_f32_16x16x32_bf16 v[68:71], v[172:175], v[212:215], v[68:71]
	v_mfma_f32_16x16x32_bf16 v[64:67], v[180:183], v[212:215], v[64:67]
	v_mfma_f32_16x16x32_bf16 v[116:119], v[176:179], v[192:195], v[116:119]
	v_mfma_f32_16x16x32_bf16 v[112:115], v[184:187], v[192:195], v[112:115]
	v_mfma_f32_16x16x32_bf16 v[100:103], v[176:179], v[200:203], v[100:103]
	v_mfma_f32_16x16x32_bf16 v[96:99], v[184:187], v[200:203], v[96:99]
	v_mfma_f32_16x16x32_bf16 v[84:87], v[176:179], v[208:211], v[84:87]
	v_mfma_f32_16x16x32_bf16 v[80:83], v[184:187], v[208:211], v[80:83]
	v_mfma_f32_16x16x32_bf16 v[68:71], v[176:179], v[216:219], v[68:71]
	v_mfma_f32_16x16x32_bf16 v[64:67], v[184:187], v[216:219], v[64:67]
	s_setprio 0
	s_barrier
; #define PG8_STAGE(bufoff, gbase, voff) do { _Pragma("unroll") for (int _i = 0; _i < 2; ++_i) \
;         __builtin_amdgcn_global_load_lds((const unsigned*)((const char*)(gbase) + (voff)[_i]), (LAS unsigned*)(lds + (bufoff) + ldsw + _i * 8192), 16, 0, 0); } while (0)
; #define PG8_LDA(dst, b, h) do { _Pragma("unroll") for (int m = 0; m < 4; ++m) _Pragma("unroll") for (int k = 0; k < 2; ++k) dst[m][k] = *(const LAS bf16x8*)(lds + PG8_SA(b, h) + aoff + m * 2048 + k * 1024); } while (0)
; #define PG8_MMA(ai, bj, At, Bt) do { __builtin_amdgcn_s_setprio(1); _Pragma("unroll") for (int m = 0; m < 4; ++m) _Pragma("unroll") for (int n = 0; n < 2; ++n) _Pragma("unroll") for (int k = 0; k < 2; ++k) \
;         acc[ai][bj][m][n] = __builtin_amdgcn_mfma_f32_16x16x32_bf16(Bt[n][k], At[m][k], acc[ai][bj][m][n], 0, 0, 0); __builtin_amdgcn_s_setprio(0); } while (0)
; #define PG8_WAIT_V(n) asm volatile("s_waitcnt vmcnt(" #n ")" ::: "memory")
; #define PG8_WAIT_L(n) asm volatile("s_waitcnt lgkmcnt(" #n ")" ::: "memory")
; #define PG8_BAR __builtin_amdgcn_s_barrier()
; #define PG8_SCHED __builtin_amdgcn_sched_barrier(0)
; template <class Epi, class Sched, bool ALIGN_EPI = true, bool SP2 = true>
; __device__ __forceinline__ void gemm_phase(LAS unsigned char* lds, const Gemm g, const Sched& S, const Epi& E) {
;     ...
;         for (int t = 0; t < nt; t += 2) {
;             const bool last = (t == nt - 2);
;     ...
;             PG8_LDA(At, 1, 1); PG8_STAGE(PG8_SB(1, 0), b3, voffB); PG8_STAGE(PG8_SB(1, 1), b3 + hstepB, voffB); PG8_STAGE(PG8_SA(1, 0), a3, voffA);
;             PG8_WAIT_V(8); PG8_WAIT_L(0); PG8_BAR; PG8_MMA(1, 0, At, B0); PG8_MMA(1, 1, At, B1); PG8_BAR; PG8_SCHED;
	s_add_i32 s40, s62, s3
	v_lshl_add_u64 v[220:221], v[220:221], 0, s[14:15]
	s_mov_b32 m0, s40
	ds_read_b128 v[188:191], v153 offset:49152
	ds_read_b128 v[192:195], v153 offset:50176
	ds_read_b128 v[196:199], v153 offset:51200
	ds_read_b128 v[200:203], v153 offset:52224
	ds_read_b128 v[204:207], v153 offset:53248
	ds_read_b128 v[208:211], v153 offset:54272
	ds_read_b128 v[212:215], v153 offset:55296
	ds_read_b128 v[216:219], v153 offset:56320
	global_load_lds_dwordx4 v[220:221], off
	s_add_i32 m0, s40, 0x2000
	s_add_u32 s30, s30, 0x40080
	v_lshl_add_u64 v[220:221], v[222:223], 0, s[14:15]
	s_addc_u32 s31, s31, 0
	s_add_i32 s40, s63, s3
	global_load_lds_dwordx4 v[220:221], off
	s_nop 0
	s_mov_b32 m0, s40
	s_nop 0
	global_load_lds_dwordx4 v130, s[30:31]
	s_nop 0
	s_add_i32 m0, s40, 0x2000
	s_nop 0
	global_load_lds_dwordx4 v134, s[30:31]
	v_lshl_add_u64 v[220:221], v[224:225], 0, s[14:15]
	s_mov_b32 m0, s50
	s_nop 0
	global_load_lds_dwordx4 v[220:221], off
	v_lshl_add_u64 v[220:221], v[226:227], 0, s[14:15]
	s_mov_b32 m0, s51
	s_nop 0
	global_load_lds_dwordx4 v[220:221], off
	s_waitcnt vmcnt(8)
	s_waitcnt lgkmcnt(0)
	s_barrier
	s_setprio 1
	s_waitcnt lgkmcnt(0)
	v_mfma_f32_16x16x32_bf16 v[60:63], v[144:147], v[188:191], v[60:63]
	v_mfma_f32_16x16x32_bf16 v[56:59], v[164:167], v[188:191], v[56:59]
	v_mfma_f32_16x16x32_bf16 v[44:47], v[144:147], v[196:199], v[44:47]
	v_mfma_f32_16x16x32_bf16 v[40:43], v[164:167], v[196:199], v[40:43]
	v_mfma_f32_16x16x32_bf16 v[28:31], v[144:147], v[204:207], v[28:31]
	v_mfma_f32_16x16x32_bf16 v[24:27], v[164:167], v[204:207], v[24:27]
	v_mfma_f32_16x16x32_bf16 v[12:15], v[144:147], v[212:215], v[12:15]
	v_mfma_f32_16x16x32_bf16 v[8:11], v[164:167], v[212:215], v[8:11]
	v_mfma_f32_16x16x32_bf16 v[60:63], v[160:163], v[192:195], v[60:63]
	v_mfma_f32_16x16x32_bf16 v[56:59], v[168:171], v[192:195], v[56:59]
	v_mfma_f32_16x16x32_bf16 v[44:47], v[160:163], v[200:203], v[44:47]
	v_mfma_f32_16x16x32_bf16 v[40:43], v[168:171], v[200:203], v[40:43]
	v_mfma_f32_16x16x32_bf16 v[28:31], v[160:163], v[208:211], v[28:31]
	v_mfma_f32_16x16x32_bf16 v[24:27], v[168:171], v[208:211], v[24:27]
	v_mfma_f32_16x16x32_bf16 v[12:15], v[160:163], v[216:219], v[12:15]
	v_mfma_f32_16x16x32_bf16 v[8:11], v[168:171], v[216:219], v[8:11]
	s_setprio 0
	s_setprio 1
	v_mfma_f32_16x16x32_bf16 v[52:55], v[172:175], v[188:191], v[52:55]
	v_mfma_f32_16x16x32_bf16 v[48:51], v[180:183], v[188:191], v[48:51]
	v_mfma_f32_16x16x32_bf16 v[36:39], v[172:175], v[196:199], v[36:39]
	v_mfma_f32_16x16x32_bf16 v[32:35], v[180:183], v[196:199], v[32:35]
	v_mfma_f32_16x16x32_bf16 v[20:23], v[172:175], v[204:207], v[20:23]
	v_mfma_f32_16x16x32_bf16 v[16:19], v[180:183], v[204:207], v[16:19]
	v_mfma_f32_16x16x32_bf16 v[4:7], v[172:175], v[212:215], v[4:7]
	v_mfma_f32_16x16x32_bf16 v[0:3], v[180:183], v[212:215], v[0:3]
	v_mfma_f32_16x16x32_bf16 v[52:55], v[176:179], v[192:195], v[52:55]
	v_mfma_f32_16x16x32_bf16 v[48:51], v[184:187], v[192:195], v[48:51]
	v_mfma_f32_16x16x32_bf16 v[36:39], v[176:179], v[200:203], v[36:39]
	v_mfma_f32_16x16x32_bf16 v[32:35], v[184:187], v[200:203], v[32:35]
	v_mfma_f32_16x16x32_bf16 v[20:23], v[176:179], v[208:211], v[20:23]
	v_mfma_f32_16x16x32_bf16 v[16:19], v[184:187], v[208:211], v[16:19]
	v_mfma_f32_16x16x32_bf16 v[4:7], v[176:179], v[216:219], v[4:7]
	v_mfma_f32_16x16x32_bf16 v[0:3], v[184:187], v[216:219], v[0:3]
	s_setprio 0
	s_barrier
	s_add_i32 s61, s61, 2
	s_add_u32 s28, s28, 0x100
	s_addc_u32 s29, s29, 0
	s_add_u32 s59, s59, 0x100
	s_addc_u32 s60, s60, 0
	s_cmp_gt_u32 s61, 13
	s_cbranch_scc0 .LBB0_1483
	s_and_b64 vcc, exec, s[16:17]
	s_cbranch_vccz .LBB0_1486
	s_barrier

; #define PG8_STAGE(bufoff, gbase, voff) do { _Pragma("unroll") for (int _i = 0; _i < 2; ++_i) \
;         __builtin_amdgcn_global_load_lds((const unsigned*)((const char*)(gbase) + (voff)[_i]), (LAS unsigned*)(lds + (bufoff) + ldsw + _i * 8192), 16, 0, 0); } while (0)
; #define PG8_LDA(dst, b, h) do { _Pragma("unroll") for (int m = 0; m < 4; ++m) _Pragma("unroll") for (int k = 0; k < 2; ++k) dst[m][k] = *(const LAS bf16x8*)(lds + PG8_SA(b, h) + aoff + m * 2048 + k * 1024); } while (0)
; #define PG8_LDB(dst, b, h) do { _Pragma("unroll") for (int n = 0; n < 2; ++n) _Pragma("unroll") for (int k = 0; k < 2; ++k) dst[n][k] = *(const LAS bf16x8*)(lds + PG8_SB(b, h) + boff + n * 2048 + k * 1024); } while (0)
; #define PG8_MMA(ai, bj, At, Bt) do { __builtin_amdgcn_s_setprio(1); _Pragma("unroll") for (int m = 0; m < 4; ++m) _Pragma("unroll") for (int n = 0; n < 2; ++n) _Pragma("unroll") for (int k = 0; k < 2; ++k) \
;         acc[ai][bj][m][n] = __builtin_amdgcn_mfma_f32_16x16x32_bf16(Bt[n][k], At[m][k], acc[ai][bj][m][n], 0, 0, 0); __builtin_amdgcn_s_setprio(0); } while (0)
; #define PG8_WAIT_V(n) asm volatile("s_waitcnt vmcnt(" #n ")" ::: "memory")
; #define PG8_WAIT_L(n) asm volatile("s_waitcnt lgkmcnt(" #n ")" ::: "memory")
; #define PG8_BAR __builtin_amdgcn_s_barrier()
; template <class Epi, class Sched, bool ALIGN_EPI = true, bool SP2 = true>
; __device__ __forceinline__ void gemm_phase(LAS unsigned char* lds, const Gemm g, const Sched& S, const Epi& E) {
;     ...
;         for (int t = 0; t < nt; t += 2) {
;             const bool last = (t == nt - 2);
;             const char* a1 = cA + (size_t)(t + 1) * kstepA;
;             const char* a2 = last ? nA : cA + (size_t)(t + 2) * kstepA; const char* b2 = last ? nB : cB + (size_t)(t + 2) * kstepB;
;             const char* a3 = a2 + kstepA; const char* b3 = b2 + kstepB;
;             if constexpr (SP2) {
;             PG8_LDB(B0, 0, 0); PG8_LDB(B1, 0, 1); PG8_SCHED; PG8_LDA(At, 0, 0); PG8_STAGE(PG8_SA(1, 1), a1 + hstepA, voffA);
;             PG8_WAIT_V(8); PG8_WAIT_L(0); PG8_BAR; PG8_MMA(0, 0, At, B0); PG8_MMA(0, 1, At, B1); PG8_BAR; PG8_SCHED;
;             PG8_LDA(At, 0, 1); PG8_STAGE(PG8_SB(0, 0), b2, voffB); PG8_STAGE(PG8_SB(0, 1), b2 + hstepB, voffB); PG8_STAGE(PG8_SA(0, 0), a2, voffA);
;             PG8_WAIT_V(8); PG8_WAIT_L(0); PG8_BAR; PG8_MMA(1, 0, At, B0); PG8_MMA(1, 1, At, B1); PG8_BAR; PG8_SCHED;
.LBB0_1644:
	ds_read_b128 v[144:147], v151
	ds_read_b128 v[160:163], v151 offset:1024
	ds_read_b128 v[164:167], v151 offset:2048
	ds_read_b128 v[168:171], v151 offset:3072
	ds_read_b128 v[172:175], v152
	ds_read_b128 v[176:179], v152 offset:1024
	ds_read_b128 v[180:183], v152 offset:2048
	ds_read_b128 v[184:187], v152 offset:3072
	s_add_u32 s28, s26, 0xfffc0080
	s_addc_u32 s29, s27, -1
	s_cmp_eq_u32 s55, 12
	s_cselect_b32 s31, s19, s29
	s_cselect_b32 s30, s51, s28
	s_cselect_b32 s29, s17, s54
	s_cselect_b32 s28, s52, s53
	s_nop 0
	s_add_i32 m0, s25, 0xc000
	ds_read_b128 v[188:191], v153
	ds_read_b128 v[192:195], v153 offset:1024
	ds_read_b128 v[196:199], v153 offset:2048
	ds_read_b128 v[200:203], v153 offset:3072
	ds_read_b128 v[204:207], v153 offset:4096
	ds_read_b128 v[208:211], v153 offset:5120
	ds_read_b128 v[212:215], v153 offset:6144
	ds_read_b128 v[216:219], v153 offset:7168
	global_load_lds_dwordx4 v136, s[26:27]
	s_nop 0
	s_add_i32 m0, s25, 0xe000
	s_nop 0
	global_load_lds_dwordx4 v138, s[26:27]
	s_waitcnt vmcnt(8)
	s_waitcnt lgkmcnt(0)
	s_barrier
	s_setprio 1
	s_waitcnt lgkmcnt(0)
	v_mfma_f32_16x16x32_bf16 v[124:127], v[144:147], v[188:191], v[124:127]
	v_mfma_f32_16x16x32_bf16 v[120:123], v[164:167], v[188:191], v[120:123]
	v_mfma_f32_16x16x32_bf16 v[108:111], v[144:147], v[196:199], v[108:111]
	v_mfma_f32_16x16x32_bf16 v[104:107], v[164:167], v[196:199], v[104:107]
	v_mfma_f32_16x16x32_bf16 v[92:95], v[144:147], v[204:207], v[92:95]
	v_mfma_f32_16x16x32_bf16 v[88:91], v[164:167], v[204:207], v[88:91]
	v_mfma_f32_16x16x32_bf16 v[76:79], v[144:147], v[212:215], v[76:79]
	v_mfma_f32_16x16x32_bf16 v[72:75], v[164:167], v[212:215], v[72:75]
	v_mfma_f32_16x16x32_bf16 v[124:127], v[160:163], v[192:195], v[124:127]
	v_mfma_f32_16x16x32_bf16 v[120:123], v[168:171], v[192:195], v[120:123]
	v_mfma_f32_16x16x32_bf16 v[108:111], v[160:163], v[200:203], v[108:111]
	v_mfma_f32_16x16x32_bf16 v[104:107], v[168:171], v[200:203], v[104:107]
	v_mfma_f32_16x16x32_bf16 v[92:95], v[160:163], v[208:211], v[92:95]
	v_mfma_f32_16x16x32_bf16 v[88:91], v[168:171], v[208:211], v[88:91]
	v_mfma_f32_16x16x32_bf16 v[76:79], v[160:163], v[216:219], v[76:79]
	v_mfma_f32_16x16x32_bf16 v[72:75], v[168:171], v[216:219], v[72:75]
	s_setprio 0
	s_setprio 1
	v_mfma_f32_16x16x32_bf16 v[116:119], v[172:175], v[188:191], v[116:119]
	v_mfma_f32_16x16x32_bf16 v[112:115], v[180:183], v[188:191], v[112:115]
	v_mfma_f32_16x16x32_bf16 v[100:103], v[172:175], v[196:199], v[100:103]
	v_mfma_f32_16x16x32_bf16 v[96:99], v[180:183], v[196:199], v[96:99]
	v_mfma_f32_16x16x32_bf16 v[84:87], v[172:175], v[204:207], v[84:87]
	v_mfma_f32_16x16x32_bf16 v[80:83], v[180:183], v[204:207], v[80:83]
	v_mfma_f32_16x16x32_bf16 v[68:71], v[172:175], v[212:215], v[68:71]
	v_mfma_f32_16x16x32_bf16 v[64:67], v[180:183], v[212:215], v[64:67]
	v_mfma_f32_16x16x32_bf16 v[116:119], v[176:179], v[192:195], v[116:119]
	v_mfma_f32_16x16x32_bf16 v[112:115], v[184:187], v[192:195], v[112:115]
	v_mfma_f32_16x16x32_bf16 v[100:103], v[176:179], v[200:203], v[100:103]
	v_mfma_f32_16x16x32_bf16 v[96:99], v[184:187], v[200:203], v[96:99]
	v_mfma_f32_16x16x32_bf16 v[84:87], v[176:179], v[208:211], v[84:87]
	v_mfma_f32_16x16x32_bf16 v[80:83], v[184:187], v[208:211], v[80:83]
	v_mfma_f32_16x16x32_bf16 v[68:71], v[176:179], v[216:219], v[68:71]
	v_mfma_f32_16x16x32_bf16 v[64:67], v[184:187], v[216:219], v[64:67]
	s_setprio 0
	s_barrier
	s_add_i32 s56, s44, s33
	v_lshl_add_u64 v[154:155], s[28:29], 0, v[130:131]
	s_mov_b32 m0, s56
	ds_read_b128 v[188:191], v153 offset:16384
	ds_read_b128 v[192:195], v153 offset:17408
	ds_read_b128 v[196:199], v153 offset:18432
	ds_read_b128 v[200:203], v153 offset:19456
	ds_read_b128 v[204:207], v153 offset:20480
	ds_read_b128 v[208:211], v153 offset:21504
	ds_read_b128 v[212:215], v153 offset:22528
	ds_read_b128 v[216:219], v153 offset:23552
	global_load_lds_dwordx4 v[154:155], off
	s_add_i32 m0, s56, 0x2000
	s_add_u32 s56, s28, 0x40000
	v_lshl_add_u64 v[220:221], s[28:29], 0, v[134:135]
	s_addc_u32 s57, s29, 0
	s_add_i32 s58, s45, s33
	global_load_lds_dwordx4 v[220:221], off
	s_nop 0
	s_mov_b32 m0, s58
	v_lshl_add_u64 v[224:225], s[30:31], 0, v[132:133]
	global_load_lds_dwordx4 v130, s[56:57]
	s_nop 0
	s_add_i32 m0, s58, 0x2000
	s_nop 0
	global_load_lds_dwordx4 v134, s[56:57]
	v_lshl_add_u64 v[222:223], s[30:31], 0, v[128:129]
	s_mov_b32 m0, s25
	s_nop 0
	global_load_lds_dwordx4 v[222:223], off
	s_mov_b32 m0, s34
	s_nop 0
	global_load_lds_dwordx4 v[224:225], off
	s_waitcnt vmcnt(8)
	s_waitcnt lgkmcnt(0)
	s_barrier
; #define PG8_STAGE(bufoff, gbase, voff) do { _Pragma("unroll") for (int _i = 0; _i < 2; ++_i) \
;         __builtin_amdgcn_global_load_lds((const unsigned*)((const char*)(gbase) + (voff)[_i]), (LAS unsigned*)(lds + (bufoff) + ldsw + _i * 8192), 16, 0, 0); } while (0)
; #define PG8_LDA(dst, b, h) do { _Pragma("unroll") for (int m = 0; m < 4; ++m) _Pragma("unroll") for (int k = 0; k < 2; ++k) dst[m][k] = *(const LAS bf16x8*)(lds + PG8_SA(b, h) + aoff + m * 2048 + k * 1024); } while (0)
; #define PG8_LDB(dst, b, h) do { _Pragma("unroll") for (int n = 0; n < 2; ++n) _Pragma("unroll") for (int k = 0; k < 2; ++k) dst[n][k] = *(const LAS bf16x8*)(lds + PG8_SB(b, h) + boff + n * 2048 + k * 1024); } while (0)
; #define PG8_MMA(ai, bj, At, Bt) do { __builtin_amdgcn_s_setprio(1); _Pragma("unroll") for (int m = 0; m < 4; ++m) _Pragma("unroll") for (int n = 0; n < 2; ++n) _Pragma("unroll") for (int k = 0; k < 2; ++k) \
;         acc[ai][bj][m][n] = __builtin_amdgcn_mfma_f32_16x16x32_bf16(Bt[n][k], At[m][k], acc[ai][bj][m][n], 0, 0, 0); __builtin_amdgcn_s_setprio(0); } while (0)
; #define PG8_WAIT_V(n) asm volatile("s_waitcnt vmcnt(" #n ")" ::: "memory")
; #define PG8_WAIT_L(n) asm volatile("s_waitcnt lgkmcnt(" #n ")" ::: "memory")
; #define PG8_BAR __builtin_amdgcn_s_barrier()
; #define PG8_SCHED __builtin_amdgcn_sched_barrier(0)
; template <class Epi, class Sched, bool ALIGN_EPI = true, bool SP2 = true>
; __device__ __forceinline__ void gemm_phase(LAS unsigned char* lds, const Gemm g, const Sched& S, const Epi& E) {
;     ...
;             PG8_WAIT_V(8); PG8_WAIT_L(0); PG8_BAR; PG8_MMA(1, 0, At, B0); PG8_MMA(1, 1, At, B1); PG8_BAR; PG8_SCHED;
;             PG8_LDB(B0, 1, 0); PG8_LDB(B1, 1, 1); PG8_SCHED; PG8_LDA(At, 1, 0); PG8_STAGE(PG8_SA(0, 1), a2 + hstepA, voffA);
;             PG8_WAIT_V(8); PG8_WAIT_L(0); PG8_BAR; PG8_MMA(0, 0, At, B0); PG8_MMA(0, 1, At, B1); PG8_BAR; PG8_SCHED;
	s_setprio 1
	s_waitcnt lgkmcnt(0)
	v_mfma_f32_16x16x32_bf16 v[60:63], v[144:147], v[188:191], v[60:63]
	v_mfma_f32_16x16x32_bf16 v[56:59], v[164:167], v[188:191], v[56:59]
	v_mfma_f32_16x16x32_bf16 v[44:47], v[144:147], v[196:199], v[44:47]
	v_mfma_f32_16x16x32_bf16 v[40:43], v[164:167], v[196:199], v[40:43]
	v_mfma_f32_16x16x32_bf16 v[28:31], v[144:147], v[204:207], v[28:31]
	v_mfma_f32_16x16x32_bf16 v[24:27], v[164:167], v[204:207], v[24:27]
	v_mfma_f32_16x16x32_bf16 v[12:15], v[144:147], v[212:215], v[12:15]
	v_mfma_f32_16x16x32_bf16 v[8:11], v[164:167], v[212:215], v[8:11]
	v_mfma_f32_16x16x32_bf16 v[60:63], v[160:163], v[192:195], v[60:63]
	v_mfma_f32_16x16x32_bf16 v[56:59], v[168:171], v[192:195], v[56:59]
	v_mfma_f32_16x16x32_bf16 v[44:47], v[160:163], v[200:203], v[44:47]
	v_mfma_f32_16x16x32_bf16 v[40:43], v[168:171], v[200:203], v[40:43]
	v_mfma_f32_16x16x32_bf16 v[28:31], v[160:163], v[208:211], v[28:31]
	v_mfma_f32_16x16x32_bf16 v[24:27], v[168:171], v[208:211], v[24:27]
	v_mfma_f32_16x16x32_bf16 v[12:15], v[160:163], v[216:219], v[12:15]
	v_mfma_f32_16x16x32_bf16 v[8:11], v[168:171], v[216:219], v[8:11]
	s_setprio 0
	s_setprio 1
	v_mfma_f32_16x16x32_bf16 v[52:55], v[172:175], v[188:191], v[52:55]
	v_mfma_f32_16x16x32_bf16 v[48:51], v[180:183], v[188:191], v[48:51]
	v_mfma_f32_16x16x32_bf16 v[36:39], v[172:175], v[196:199], v[36:39]
	v_mfma_f32_16x16x32_bf16 v[32:35], v[180:183], v[196:199], v[32:35]
	v_mfma_f32_16x16x32_bf16 v[20:23], v[172:175], v[204:207], v[20:23]
	v_mfma_f32_16x16x32_bf16 v[16:19], v[180:183], v[204:207], v[16:19]
	v_mfma_f32_16x16x32_bf16 v[4:7], v[172:175], v[212:215], v[4:7]
	v_mfma_f32_16x16x32_bf16 v[0:3], v[180:183], v[212:215], v[0:3]
	v_mfma_f32_16x16x32_bf16 v[52:55], v[176:179], v[192:195], v[52:55]
	v_mfma_f32_16x16x32_bf16 v[48:51], v[184:187], v[192:195], v[48:51]
	v_mfma_f32_16x16x32_bf16 v[36:39], v[176:179], v[200:203], v[36:39]
	v_mfma_f32_16x16x32_bf16 v[32:35], v[184:187], v[200:203], v[32:35]
	v_mfma_f32_16x16x32_bf16 v[20:23], v[176:179], v[208:211], v[20:23]
	v_mfma_f32_16x16x32_bf16 v[16:19], v[184:187], v[208:211], v[16:19]
	v_mfma_f32_16x16x32_bf16 v[4:7], v[176:179], v[216:219], v[4:7]
	v_mfma_f32_16x16x32_bf16 v[0:3], v[184:187], v[216:219], v[0:3]
	s_setprio 0
	s_barrier
	s_add_i32 s56, 0, 0x18000
	v_add_u32_e32 v157, s56, v149
	s_add_i32 s57, 0, 0x1c000
	ds_read_b128 v[144:147], v157
	ds_read_b128 v[160:163], v157 offset:1024
	ds_read_b128 v[164:167], v157 offset:2048
	ds_read_b128 v[168:171], v157 offset:3072
	v_add_u32_e32 v157, s57, v149
	ds_read_b128 v[172:175], v157
	ds_read_b128 v[176:179], v157 offset:1024
	ds_read_b128 v[180:183], v157 offset:2048
	ds_read_b128 v[184:187], v157 offset:3072
	s_add_u32 s30, s30, 0x40000
	s_addc_u32 s31, s31, 0
	s_mov_b32 m0, s35
	s_nop 0
	ds_read_b128 v[188:191], v153 offset:32768
	ds_read_b128 v[192:195], v153 offset:33792
	ds_read_b128 v[196:199], v153 offset:34816
	ds_read_b128 v[200:203], v153 offset:35840
	ds_read_b128 v[204:207], v153 offset:36864
	ds_read_b128 v[208:211], v153 offset:37888
	ds_read_b128 v[212:215], v153 offset:38912
	ds_read_b128 v[216:219], v153 offset:39936
	global_load_lds_dwordx4 v128, s[30:31]
	s_nop 0
	s_mov_b32 m0, s36
	s_nop 0
	global_load_lds_dwordx4 v132, s[30:31]
	s_waitcnt vmcnt(8)
	s_waitcnt lgkmcnt(0)
	s_barrier
	s_setprio 1
	s_waitcnt lgkmcnt(0)
	v_mfma_f32_16x16x32_bf16 v[124:127], v[144:147], v[188:191], v[124:127]
	v_mfma_f32_16x16x32_bf16 v[120:123], v[164:167], v[188:191], v[120:123]
	v_mfma_f32_16x16x32_bf16 v[108:111], v[144:147], v[196:199], v[108:111]
	v_mfma_f32_16x16x32_bf16 v[104:107], v[164:167], v[196:199], v[104:107]
	v_mfma_f32_16x16x32_bf16 v[92:95], v[144:147], v[204:207], v[92:95]
	v_mfma_f32_16x16x32_bf16 v[88:91], v[164:167], v[204:207], v[88:91]
	v_mfma_f32_16x16x32_bf16 v[76:79], v[144:147], v[212:215], v[76:79]
	v_mfma_f32_16x16x32_bf16 v[72:75], v[164:167], v[212:215], v[72:75]
	v_mfma_f32_16x16x32_bf16 v[124:127], v[160:163], v[192:195], v[124:127]
	v_mfma_f32_16x16x32_bf16 v[120:123], v[168:171], v[192:195], v[120:123]
	v_mfma_f32_16x16x32_bf16 v[108:111], v[160:163], v[200:203], v[108:111]
	v_mfma_f32_16x16x32_bf16 v[104:107], v[168:171], v[200:203], v[104:107]
	v_mfma_f32_16x16x32_bf16 v[92:95], v[160:163], v[208:211], v[92:95]
	v_mfma_f32_16x16x32_bf16 v[88:91], v[168:171], v[208:211], v[88:91]
	v_mfma_f32_16x16x32_bf16 v[76:79], v[160:163], v[216:219], v[76:79]
	v_mfma_f32_16x16x32_bf16 v[72:75], v[168:171], v[216:219], v[72:75]
	s_setprio 0
	s_setprio 1
	v_mfma_f32_16x16x32_bf16 v[116:119], v[172:175], v[188:191], v[116:119]
	v_mfma_f32_16x16x32_bf16 v[112:115], v[180:183], v[188:191], v[112:115]
	v_mfma_f32_16x16x32_bf16 v[100:103], v[172:175], v[196:199], v[100:103]
	v_mfma_f32_16x16x32_bf16 v[96:99], v[180:183], v[196:199], v[96:99]
	v_mfma_f32_16x16x32_bf16 v[84:87], v[172:175], v[204:207], v[84:87]
	v_mfma_f32_16x16x32_bf16 v[80:83], v[180:183], v[204:207], v[80:83]
	v_mfma_f32_16x16x32_bf16 v[68:71], v[172:175], v[212:215], v[68:71]
	v_mfma_f32_16x16x32_bf16 v[64:67], v[180:183], v[212:215], v[64:67]
	v_mfma_f32_16x16x32_bf16 v[116:119], v[176:179], v[192:195], v[116:119]
	v_mfma_f32_16x16x32_bf16 v[112:115], v[184:187], v[192:195], v[112:115]
	v_mfma_f32_16x16x32_bf16 v[100:103], v[176:179], v[200:203], v[100:103]
	v_mfma_f32_16x16x32_bf16 v[96:99], v[184:187], v[200:203], v[96:99]
	v_mfma_f32_16x16x32_bf16 v[84:87], v[176:179], v[208:211], v[84:87]
	v_mfma_f32_16x16x32_bf16 v[80:83], v[184:187], v[208:211], v[80:83]
	v_mfma_f32_16x16x32_bf16 v[68:71], v[176:179], v[216:219], v[68:71]
	v_mfma_f32_16x16x32_bf16 v[64:67], v[184:187], v[216:219], v[64:67]
	s_setprio 0
	s_barrier
; #define PG8_STAGE(bufoff, gbase, voff) do { _Pragma("unroll") for (int _i = 0; _i < 2; ++_i) \
;         __builtin_amdgcn_global_load_lds((const unsigned*)((const char*)(gbase) + (voff)[_i]), (LAS unsigned*)(lds + (bufoff) + ldsw + _i * 8192), 16, 0, 0); } while (0)
; #define PG8_LDA(dst, b, h) do { _Pragma("unroll") for (int m = 0; m < 4; ++m) _Pragma("unroll") for (int k = 0; k < 2; ++k) dst[m][k] = *(const LAS bf16x8*)(lds + PG8_SA(b, h) + aoff + m * 2048 + k * 1024); } while (0)
; #define PG8_MMA(ai, bj, At, Bt) do { __builtin_amdgcn_s_setprio(1); _Pragma("unroll") for (int m = 0; m < 4; ++m) _Pragma("unroll") for (int n = 0; n < 2; ++n) _Pragma("unroll") for (int k = 0; k < 2; ++k) \
;         acc[ai][bj][m][n] = __builtin_amdgcn_mfma_f32_16x16x32_bf16(Bt[n][k], At[m][k], acc[ai][bj][m][n], 0, 0, 0); __builtin_amdgcn_s_setprio(0); } while (0)
; #define PG8_WAIT_V(n) asm volatile("s_waitcnt vmcnt(" #n ")" ::: "memory")
; #define PG8_WAIT_L(n) asm volatile("s_waitcnt lgkmcnt(" #n ")" ::: "memory")
; #define PG8_BAR __builtin_amdgcn_s_barrier()
; #define PG8_SCHED __builtin_amdgcn_sched_barrier(0)
; template <class Epi, class Sched, bool ALIGN_EPI = true, bool SP2 = true>
; __device__ __forceinline__ void gemm_phase(LAS unsigned char* lds, const Gemm g, const Sched& S, const Epi& E) {
;     ...
;         for (int t = 0; t < nt; t += 2) {
;             const bool last = (t == nt - 2);
;     ...
;             PG8_LDA(At, 1, 1); PG8_STAGE(PG8_SB(1, 0), b3, voffB); PG8_STAGE(PG8_SB(1, 1), b3 + hstepB, voffB); PG8_STAGE(PG8_SA(1, 0), a3, voffA);
;             PG8_WAIT_V(8); PG8_WAIT_L(0); PG8_BAR; PG8_MMA(1, 0, At, B0); PG8_MMA(1, 1, At, B1); PG8_BAR; PG8_SCHED;
	s_add_i32 s30, s56, s33
	v_lshl_add_u64 v[154:155], v[154:155], 0, s[12:13]
	s_mov_b32 m0, s30
	ds_read_b128 v[188:191], v153 offset:49152
	ds_read_b128 v[192:195], v153 offset:50176
	ds_read_b128 v[196:199], v153 offset:51200
	ds_read_b128 v[200:203], v153 offset:52224
	ds_read_b128 v[204:207], v153 offset:53248
	ds_read_b128 v[208:211], v153 offset:54272
	ds_read_b128 v[212:215], v153 offset:55296
	ds_read_b128 v[216:219], v153 offset:56320
	global_load_lds_dwordx4 v[154:155], off
	s_add_i32 m0, s30, 0x2000
	s_add_u32 s28, s28, 0x40080
	v_lshl_add_u64 v[154:155], v[220:221], 0, s[12:13]
	s_addc_u32 s29, s29, 0
	s_add_i32 s30, s57, s33
	global_load_lds_dwordx4 v[154:155], off
	s_nop 0
	s_mov_b32 m0, s30
	s_nop 0
	global_load_lds_dwordx4 v130, s[28:29]
	s_nop 0
	s_add_i32 m0, s30, 0x2000
	s_nop 0
	global_load_lds_dwordx4 v134, s[28:29]
	v_lshl_add_u64 v[154:155], v[222:223], 0, s[12:13]
	s_mov_b32 m0, s40
	s_nop 0
	global_load_lds_dwordx4 v[154:155], off
	v_lshl_add_u64 v[154:155], v[224:225], 0, s[12:13]
	s_mov_b32 m0, s41
	s_nop 0
	global_load_lds_dwordx4 v[154:155], off
	s_waitcnt vmcnt(8)
	s_waitcnt lgkmcnt(0)
	s_barrier
	s_setprio 1
	s_waitcnt lgkmcnt(0)
	v_mfma_f32_16x16x32_bf16 v[60:63], v[144:147], v[188:191], v[60:63]
	v_mfma_f32_16x16x32_bf16 v[56:59], v[164:167], v[188:191], v[56:59]
	v_mfma_f32_16x16x32_bf16 v[44:47], v[144:147], v[196:199], v[44:47]
	v_mfma_f32_16x16x32_bf16 v[40:43], v[164:167], v[196:199], v[40:43]
	v_mfma_f32_16x16x32_bf16 v[28:31], v[144:147], v[204:207], v[28:31]
	v_mfma_f32_16x16x32_bf16 v[24:27], v[164:167], v[204:207], v[24:27]
	v_mfma_f32_16x16x32_bf16 v[12:15], v[144:147], v[212:215], v[12:15]
	v_mfma_f32_16x16x32_bf16 v[8:11], v[164:167], v[212:215], v[8:11]
	v_mfma_f32_16x16x32_bf16 v[60:63], v[160:163], v[192:195], v[60:63]
	v_mfma_f32_16x16x32_bf16 v[56:59], v[168:171], v[192:195], v[56:59]
	v_mfma_f32_16x16x32_bf16 v[44:47], v[160:163], v[200:203], v[44:47]
	v_mfma_f32_16x16x32_bf16 v[40:43], v[168:171], v[200:203], v[40:43]
	v_mfma_f32_16x16x32_bf16 v[28:31], v[160:163], v[208:211], v[28:31]
	v_mfma_f32_16x16x32_bf16 v[24:27], v[168:171], v[208:211], v[24:27]
	v_mfma_f32_16x16x32_bf16 v[12:15], v[160:163], v[216:219], v[12:15]
	v_mfma_f32_16x16x32_bf16 v[8:11], v[168:171], v[216:219], v[8:11]
	s_setprio 0
	s_setprio 1
	v_mfma_f32_16x16x32_bf16 v[52:55], v[172:175], v[188:191], v[52:55]
	v_mfma_f32_16x16x32_bf16 v[48:51], v[180:183], v[188:191], v[48:51]
	v_mfma_f32_16x16x32_bf16 v[36:39], v[172:175], v[196:199], v[36:39]
	v_mfma_f32_16x16x32_bf16 v[32:35], v[180:183], v[196:199], v[32:35]
	v_mfma_f32_16x16x32_bf16 v[20:23], v[172:175], v[204:207], v[20:23]
	v_mfma_f32_16x16x32_bf16 v[16:19], v[180:183], v[204:207], v[16:19]
	v_mfma_f32_16x16x32_bf16 v[4:7], v[172:175], v[212:215], v[4:7]
	v_mfma_f32_16x16x32_bf16 v[0:3], v[180:183], v[212:215], v[0:3]
	v_mfma_f32_16x16x32_bf16 v[52:55], v[176:179], v[192:195], v[52:55]
	v_mfma_f32_16x16x32_bf16 v[48:51], v[184:187], v[192:195], v[48:51]
	v_mfma_f32_16x16x32_bf16 v[36:39], v[176:179], v[200:203], v[36:39]
	v_mfma_f32_16x16x32_bf16 v[32:35], v[184:187], v[200:203], v[32:35]
	v_mfma_f32_16x16x32_bf16 v[20:23], v[176:179], v[208:211], v[20:23]
	v_mfma_f32_16x16x32_bf16 v[16:19], v[184:187], v[208:211], v[16:19]
	v_mfma_f32_16x16x32_bf16 v[4:7], v[176:179], v[216:219], v[4:7]
	v_mfma_f32_16x16x32_bf16 v[0:3], v[184:187], v[216:219], v[0:3]
	s_setprio 0
	s_barrier
	s_add_i32 s55, s55, 2
	s_add_u32 s53, s53, 0x100
	s_addc_u32 s54, s54, 0
	s_add_u32 s26, s26, 0x100
	s_addc_u32 s27, s27, 0
	s_cmp_gt_u32 s55, 13
	s_cbranch_scc0 .LBB0_1644
	s_and_b64 vcc, exec, s[14:15]
	s_cbranch_vccz .LBB0_1647
	s_barrier

; #define PG8_STAGE(bufoff, gbase, voff) do { _Pragma("unroll") for (int _i = 0; _i < 2; ++_i) \
;         __builtin_amdgcn_global_load_lds((const unsigned*)((const char*)(gbase) + (voff)[_i]), (LAS unsigned*)(lds + (bufoff) + ldsw + _i * 8192), 16, 0, 0); } while (0)
; #define PG8_LDA(dst, b, h) do { _Pragma("unroll") for (int m = 0; m < 4; ++m) _Pragma("unroll") for (int k = 0; k < 2; ++k) dst[m][k] = *(const LAS bf16x8*)(lds + PG8_SA(b, h) + aoff + m * 2048 + k * 1024); } while (0)
; #define PG8_LDB(dst, b, h) do { _Pragma("unroll") for (int n = 0; n < 2; ++n) _Pragma("unroll") for (int k = 0; k < 2; ++k) dst[n][k] = *(const LAS bf16x8*)(lds + PG8_SB(b, h) + boff + n * 2048 + k * 1024); } while (0)
; #define PG8_MMA(ai, bj, At, Bt) do { __builtin_amdgcn_s_setprio(1); _Pragma("unroll") for (int m = 0; m < 4; ++m) _Pragma("unroll") for (int n = 0; n < 2; ++n) _Pragma("unroll") for (int k = 0; k < 2; ++k) \
;         acc[ai][bj][m][n] = __builtin_amdgcn_mfma_f32_16x16x32_bf16(Bt[n][k], At[m][k], acc[ai][bj][m][n], 0, 0, 0); __builtin_amdgcn_s_setprio(0); } while (0)
; #define PG8_WAIT_V(n) asm volatile("s_waitcnt vmcnt(" #n ")" ::: "memory")
; #define PG8_WAIT_L(n) asm volatile("s_waitcnt lgkmcnt(" #n ")" ::: "memory")
; #define PG8_BAR __builtin_amdgcn_s_barrier()
; template <class Epi, class Sched, bool ALIGN_EPI = true, bool SP2 = true>
; __device__ __forceinline__ void gemm_phase(LAS unsigned char* lds, const Gemm g, const Sched& S, const Epi& E) {
;     ...
;         for (int t = 0; t < nt; t += 2) {
;             const bool last = (t == nt - 2);
;             const char* a1 = cA + (size_t)(t + 1) * kstepA;
;             const char* a2 = last ? nA : cA + (size_t)(t + 2) * kstepA; const char* b2 = last ? nB : cB + (size_t)(t + 2) * kstepB;
;             const char* a3 = a2 + kstepA; const char* b3 = b2 + kstepB;
;             if constexpr (SP2) {
;             PG8_LDB(B0, 0, 0); PG8_LDB(B1, 0, 1); PG8_SCHED; PG8_LDA(At, 0, 0); PG8_STAGE(PG8_SA(1, 1), a1 + hstepA, voffA);
;             PG8_WAIT_V(8); PG8_WAIT_L(0); PG8_BAR; PG8_MMA(0, 0, At, B0); PG8_MMA(0, 1, At, B1); PG8_BAR; PG8_SCHED;
;             PG8_LDA(At, 0, 1); PG8_STAGE(PG8_SB(0, 0), b2, voffB); PG8_STAGE(PG8_SB(0, 1), b2 + hstepB, voffB); PG8_STAGE(PG8_SA(0, 0), a2, voffA);
;             PG8_WAIT_V(8); PG8_WAIT_L(0); PG8_BAR; PG8_MMA(1, 0, At, B0); PG8_MMA(1, 1, At, B1); PG8_BAR; PG8_SCHED;
.LBB0_1725:
	ds_read_b128 v[144:147], v151
	ds_read_b128 v[160:163], v151 offset:1024
	ds_read_b128 v[164:167], v151 offset:2048
	ds_read_b128 v[168:171], v151 offset:3072
	ds_read_b128 v[172:175], v152
	ds_read_b128 v[176:179], v152 offset:1024
	ds_read_b128 v[180:183], v152 offset:2048
	ds_read_b128 v[184:187], v152 offset:3072
	s_add_u32 s30, s28, 0xfff00080
	s_addc_u32 s31, s29, -1
	s_cmp_eq_u32 s57, 60
	s_cselect_b32 s37, s21, s31
	s_cselect_b32 s36, s27, s30
	s_cselect_b32 s31, s19, s56
	s_cselect_b32 s30, s54, s55
	s_nop 0
	s_add_i32 m0, s33, 0xc000
	ds_read_b128 v[188:191], v153
	ds_read_b128 v[192:195], v153 offset:1024
	ds_read_b128 v[196:199], v153 offset:2048
	ds_read_b128 v[200:203], v153 offset:3072
	ds_read_b128 v[204:207], v153 offset:4096
	ds_read_b128 v[208:211], v153 offset:5120
	ds_read_b128 v[212:215], v153 offset:6144
	ds_read_b128 v[216:219], v153 offset:7168
	global_load_lds_dwordx4 v136, s[28:29]
	s_nop 0
	s_add_i32 m0, s33, 0xe000
	s_nop 0
	global_load_lds_dwordx4 v138, s[28:29]
	s_waitcnt vmcnt(8)
	s_waitcnt lgkmcnt(0)
	s_barrier
	s_setprio 1
	s_waitcnt lgkmcnt(0)
	v_mfma_f32_16x16x32_bf16 v[124:127], v[144:147], v[188:191], v[124:127]
	v_mfma_f32_16x16x32_bf16 v[120:123], v[164:167], v[188:191], v[120:123]
	v_mfma_f32_16x16x32_bf16 v[108:111], v[144:147], v[196:199], v[108:111]
	v_mfma_f32_16x16x32_bf16 v[104:107], v[164:167], v[196:199], v[104:107]
	v_mfma_f32_16x16x32_bf16 v[92:95], v[144:147], v[204:207], v[92:95]
	v_mfma_f32_16x16x32_bf16 v[88:91], v[164:167], v[204:207], v[88:91]
	v_mfma_f32_16x16x32_bf16 v[76:79], v[144:147], v[212:215], v[76:79]
	v_mfma_f32_16x16x32_bf16 v[72:75], v[164:167], v[212:215], v[72:75]
	v_mfma_f32_16x16x32_bf16 v[124:127], v[160:163], v[192:195], v[124:127]
	v_mfma_f32_16x16x32_bf16 v[120:123], v[168:171], v[192:195], v[120:123]
	v_mfma_f32_16x16x32_bf16 v[108:111], v[160:163], v[200:203], v[108:111]
	v_mfma_f32_16x16x32_bf16 v[104:107], v[168:171], v[200:203], v[104:107]
	v_mfma_f32_16x16x32_bf16 v[92:95], v[160:163], v[208:211], v[92:95]
	v_mfma_f32_16x16x32_bf16 v[88:91], v[168:171], v[208:211], v[88:91]
	v_mfma_f32_16x16x32_bf16 v[76:79], v[160:163], v[216:219], v[76:79]
	v_mfma_f32_16x16x32_bf16 v[72:75], v[168:171], v[216:219], v[72:75]
	s_setprio 0
	s_setprio 1
	v_mfma_f32_16x16x32_bf16 v[116:119], v[172:175], v[188:191], v[116:119]
	v_mfma_f32_16x16x32_bf16 v[112:115], v[180:183], v[188:191], v[112:115]
	v_mfma_f32_16x16x32_bf16 v[100:103], v[172:175], v[196:199], v[100:103]
	v_mfma_f32_16x16x32_bf16 v[96:99], v[180:183], v[196:199], v[96:99]
	v_mfma_f32_16x16x32_bf16 v[84:87], v[172:175], v[204:207], v[84:87]
	v_mfma_f32_16x16x32_bf16 v[80:83], v[180:183], v[204:207], v[80:83]
	v_mfma_f32_16x16x32_bf16 v[68:71], v[172:175], v[212:215], v[68:71]
	v_mfma_f32_16x16x32_bf16 v[64:67], v[180:183], v[212:215], v[64:67]
	v_mfma_f32_16x16x32_bf16 v[116:119], v[176:179], v[192:195], v[116:119]
	v_mfma_f32_16x16x32_bf16 v[112:115], v[184:187], v[192:195], v[112:115]
	v_mfma_f32_16x16x32_bf16 v[100:103], v[176:179], v[200:203], v[100:103]
	v_mfma_f32_16x16x32_bf16 v[96:99], v[184:187], v[200:203], v[96:99]
	v_mfma_f32_16x16x32_bf16 v[84:87], v[176:179], v[208:211], v[84:87]
	v_mfma_f32_16x16x32_bf16 v[80:83], v[184:187], v[208:211], v[80:83]
	v_mfma_f32_16x16x32_bf16 v[68:71], v[176:179], v[216:219], v[68:71]
	v_mfma_f32_16x16x32_bf16 v[64:67], v[184:187], v[216:219], v[64:67]
	s_setprio 0
	s_barrier
	s_add_i32 s58, s51, s3
	v_lshl_add_u64 v[220:221], s[30:31], 0, v[130:131]
	s_mov_b32 m0, s58
	ds_read_b128 v[188:191], v153 offset:16384
	ds_read_b128 v[192:195], v153 offset:17408
	ds_read_b128 v[196:199], v153 offset:18432
	ds_read_b128 v[200:203], v153 offset:19456
	ds_read_b128 v[204:207], v153 offset:20480
	ds_read_b128 v[208:211], v153 offset:21504
	ds_read_b128 v[212:215], v153 offset:22528
	ds_read_b128 v[216:219], v153 offset:23552
	global_load_lds_dwordx4 v[220:221], off
	s_add_i32 m0, s58, 0x2000
	s_add_u32 s58, s30, 0x100000
	v_lshl_add_u64 v[222:223], s[30:31], 0, v[134:135]
	s_addc_u32 s59, s31, 0
	s_add_i32 s60, s52, s3
	global_load_lds_dwordx4 v[222:223], off
	s_nop 0
	s_mov_b32 m0, s60
	v_lshl_add_u64 v[226:227], s[36:37], 0, v[132:133]
	global_load_lds_dwordx4 v130, s[58:59]
	s_nop 0
	s_add_i32 m0, s60, 0x2000
	s_nop 0
	global_load_lds_dwordx4 v134, s[58:59]
	v_lshl_add_u64 v[224:225], s[36:37], 0, v[128:129]
	s_mov_b32 m0, s33
	s_nop 0
	global_load_lds_dwordx4 v[224:225], off
	s_mov_b32 m0, s34
	s_nop 0
	global_load_lds_dwordx4 v[226:227], off
	s_waitcnt vmcnt(8)
	s_waitcnt lgkmcnt(0)
	s_barrier
; #define PG8_STAGE(bufoff, gbase, voff) do { _Pragma("unroll") for (int _i = 0; _i < 2; ++_i) \
;         __builtin_amdgcn_global_load_lds((const unsigned*)((const char*)(gbase) + (voff)[_i]), (LAS unsigned*)(lds + (bufoff) + ldsw + _i * 8192), 16, 0, 0); } while (0)
; #define PG8_LDA(dst, b, h) do { _Pragma("unroll") for (int m = 0; m < 4; ++m) _Pragma("unroll") for (int k = 0; k < 2; ++k) dst[m][k] = *(const LAS bf16x8*)(lds + PG8_SA(b, h) + aoff + m * 2048 + k * 1024); } while (0)
; #define PG8_LDB(dst, b, h) do { _Pragma("unroll") for (int n = 0; n < 2; ++n) _Pragma("unroll") for (int k = 0; k < 2; ++k) dst[n][k] = *(const LAS bf16x8*)(lds + PG8_SB(b, h) + boff + n * 2048 + k * 1024); } while (0)
; #define PG8_MMA(ai, bj, At, Bt) do { __builtin_amdgcn_s_setprio(1); _Pragma("unroll") for (int m = 0; m < 4; ++m) _Pragma("unroll") for (int n = 0; n < 2; ++n) _Pragma("unroll") for (int k = 0; k < 2; ++k) \
;         acc[ai][bj][m][n] = __builtin_amdgcn_mfma_f32_16x16x32_bf16(Bt[n][k], At[m][k], acc[ai][bj][m][n], 0, 0, 0); __builtin_amdgcn_s_setprio(0); } while (0)
; #define PG8_WAIT_V(n) asm volatile("s_waitcnt vmcnt(" #n ")" ::: "memory")
; #define PG8_WAIT_L(n) asm volatile("s_waitcnt lgkmcnt(" #n ")" ::: "memory")
; #define PG8_BAR __builtin_amdgcn_s_barrier()
; #define PG8_SCHED __builtin_amdgcn_sched_barrier(0)
; template <class Epi, class Sched, bool ALIGN_EPI = true, bool SP2 = true>
; __device__ __forceinline__ void gemm_phase(LAS unsigned char* lds, const Gemm g, const Sched& S, const Epi& E) {
;     ...
;             PG8_WAIT_V(8); PG8_WAIT_L(0); PG8_BAR; PG8_MMA(1, 0, At, B0); PG8_MMA(1, 1, At, B1); PG8_BAR; PG8_SCHED;
;             PG8_LDB(B0, 1, 0); PG8_LDB(B1, 1, 1); PG8_SCHED; PG8_LDA(At, 1, 0); PG8_STAGE(PG8_SA(0, 1), a2 + hstepA, voffA);
;             PG8_WAIT_V(8); PG8_WAIT_L(0); PG8_BAR; PG8_MMA(0, 0, At, B0); PG8_MMA(0, 1, At, B1); PG8_BAR; PG8_SCHED;
	s_setprio 1
	s_waitcnt lgkmcnt(0)
	v_mfma_f32_16x16x32_bf16 v[60:63], v[144:147], v[188:191], v[60:63]
	v_mfma_f32_16x16x32_bf16 v[56:59], v[164:167], v[188:191], v[56:59]
	v_mfma_f32_16x16x32_bf16 v[44:47], v[144:147], v[196:199], v[44:47]
	v_mfma_f32_16x16x32_bf16 v[40:43], v[164:167], v[196:199], v[40:43]
	v_mfma_f32_16x16x32_bf16 v[28:31], v[144:147], v[204:207], v[28:31]
	v_mfma_f32_16x16x32_bf16 v[24:27], v[164:167], v[204:207], v[24:27]
	v_mfma_f32_16x16x32_bf16 v[12:15], v[144:147], v[212:215], v[12:15]
	v_mfma_f32_16x16x32_bf16 v[8:11], v[164:167], v[212:215], v[8:11]
	v_mfma_f32_16x16x32_bf16 v[60:63], v[160:163], v[192:195], v[60:63]
	v_mfma_f32_16x16x32_bf16 v[56:59], v[168:171], v[192:195], v[56:59]
	v_mfma_f32_16x16x32_bf16 v[44:47], v[160:163], v[200:203], v[44:47]
	v_mfma_f32_16x16x32_bf16 v[40:43], v[168:171], v[200:203], v[40:43]
	v_mfma_f32_16x16x32_bf16 v[28:31], v[160:163], v[208:211], v[28:31]
	v_mfma_f32_16x16x32_bf16 v[24:27], v[168:171], v[208:211], v[24:27]
	v_mfma_f32_16x16x32_bf16 v[12:15], v[160:163], v[216:219], v[12:15]
	v_mfma_f32_16x16x32_bf16 v[8:11], v[168:171], v[216:219], v[8:11]
	s_setprio 0
	s_setprio 1
	v_mfma_f32_16x16x32_bf16 v[52:55], v[172:175], v[188:191], v[52:55]
	v_mfma_f32_16x16x32_bf16 v[48:51], v[180:183], v[188:191], v[48:51]
	v_mfma_f32_16x16x32_bf16 v[36:39], v[172:175], v[196:199], v[36:39]
	v_mfma_f32_16x16x32_bf16 v[32:35], v[180:183], v[196:199], v[32:35]
	v_mfma_f32_16x16x32_bf16 v[20:23], v[172:175], v[204:207], v[20:23]
	v_mfma_f32_16x16x32_bf16 v[16:19], v[180:183], v[204:207], v[16:19]
	v_mfma_f32_16x16x32_bf16 v[4:7], v[172:175], v[212:215], v[4:7]
	v_mfma_f32_16x16x32_bf16 v[0:3], v[180:183], v[212:215], v[0:3]
	v_mfma_f32_16x16x32_bf16 v[52:55], v[176:179], v[192:195], v[52:55]
	v_mfma_f32_16x16x32_bf16 v[48:51], v[184:187], v[192:195], v[48:51]
	v_mfma_f32_16x16x32_bf16 v[36:39], v[176:179], v[200:203], v[36:39]
	v_mfma_f32_16x16x32_bf16 v[32:35], v[184:187], v[200:203], v[32:35]
	v_mfma_f32_16x16x32_bf16 v[20:23], v[176:179], v[208:211], v[20:23]
	v_mfma_f32_16x16x32_bf16 v[16:19], v[184:187], v[208:211], v[16:19]
	v_mfma_f32_16x16x32_bf16 v[4:7], v[176:179], v[216:219], v[4:7]
	v_mfma_f32_16x16x32_bf16 v[0:3], v[184:187], v[216:219], v[0:3]
	s_setprio 0
	s_barrier
	s_add_i32 s58, 0, 0x18000
	v_add_u32_e32 v155, s58, v149
	s_add_i32 s59, 0, 0x1c000
	ds_read_b128 v[144:147], v155
	ds_read_b128 v[160:163], v155 offset:1024
	ds_read_b128 v[164:167], v155 offset:2048
	ds_read_b128 v[168:171], v155 offset:3072
	v_add_u32_e32 v155, s59, v149
	ds_read_b128 v[172:175], v155
	ds_read_b128 v[176:179], v155 offset:1024
	ds_read_b128 v[180:183], v155 offset:2048
	ds_read_b128 v[184:187], v155 offset:3072
	s_add_u32 s36, s36, 0x100000
	s_addc_u32 s37, s37, 0
	s_mov_b32 m0, s35
	s_nop 0
	ds_read_b128 v[188:191], v153 offset:32768
	ds_read_b128 v[192:195], v153 offset:33792
	ds_read_b128 v[196:199], v153 offset:34816
	ds_read_b128 v[200:203], v153 offset:35840
	ds_read_b128 v[204:207], v153 offset:36864
	ds_read_b128 v[208:211], v153 offset:37888
	ds_read_b128 v[212:215], v153 offset:38912
	ds_read_b128 v[216:219], v153 offset:39936
	global_load_lds_dwordx4 v128, s[36:37]
	s_nop 0
	s_mov_b32 m0, s40
	s_nop 0
	global_load_lds_dwordx4 v132, s[36:37]
	s_waitcnt vmcnt(8)
	s_waitcnt lgkmcnt(0)
	s_barrier
	s_setprio 1
	s_waitcnt lgkmcnt(0)
	v_mfma_f32_16x16x32_bf16 v[124:127], v[144:147], v[188:191], v[124:127]
	v_mfma_f32_16x16x32_bf16 v[120:123], v[164:167], v[188:191], v[120:123]
	v_mfma_f32_16x16x32_bf16 v[108:111], v[144:147], v[196:199], v[108:111]
	v_mfma_f32_16x16x32_bf16 v[104:107], v[164:167], v[196:199], v[104:107]
	v_mfma_f32_16x16x32_bf16 v[92:95], v[144:147], v[204:207], v[92:95]
	v_mfma_f32_16x16x32_bf16 v[88:91], v[164:167], v[204:207], v[88:91]
	v_mfma_f32_16x16x32_bf16 v[76:79], v[144:147], v[212:215], v[76:79]
	v_mfma_f32_16x16x32_bf16 v[72:75], v[164:167], v[212:215], v[72:75]
	v_mfma_f32_16x16x32_bf16 v[124:127], v[160:163], v[192:195], v[124:127]
	v_mfma_f32_16x16x32_bf16 v[120:123], v[168:171], v[192:195], v[120:123]
	v_mfma_f32_16x16x32_bf16 v[108:111], v[160:163], v[200:203], v[108:111]
	v_mfma_f32_16x16x32_bf16 v[104:107], v[168:171], v[200:203], v[104:107]
	v_mfma_f32_16x16x32_bf16 v[92:95], v[160:163], v[208:211], v[92:95]
	v_mfma_f32_16x16x32_bf16 v[88:91], v[168:171], v[208:211], v[88:91]
	v_mfma_f32_16x16x32_bf16 v[76:79], v[160:163], v[216:219], v[76:79]
	v_mfma_f32_16x16x32_bf16 v[72:75], v[168:171], v[216:219], v[72:75]
	s_setprio 0
	s_setprio 1
	v_mfma_f32_16x16x32_bf16 v[116:119], v[172:175], v[188:191], v[116:119]
	v_mfma_f32_16x16x32_bf16 v[112:115], v[180:183], v[188:191], v[112:115]
	v_mfma_f32_16x16x32_bf16 v[100:103], v[172:175], v[196:199], v[100:103]
	v_mfma_f32_16x16x32_bf16 v[96:99], v[180:183], v[196:199], v[96:99]
	v_mfma_f32_16x16x32_bf16 v[84:87], v[172:175], v[204:207], v[84:87]
	v_mfma_f32_16x16x32_bf16 v[80:83], v[180:183], v[204:207], v[80:83]
	v_mfma_f32_16x16x32_bf16 v[68:71], v[172:175], v[212:215], v[68:71]
	v_mfma_f32_16x16x32_bf16 v[64:67], v[180:183], v[212:215], v[64:67]
	v_mfma_f32_16x16x32_bf16 v[116:119], v[176:179], v[192:195], v[116:119]
	v_mfma_f32_16x16x32_bf16 v[112:115], v[184:187], v[192:195], v[112:115]
	v_mfma_f32_16x16x32_bf16 v[100:103], v[176:179], v[200:203], v[100:103]
	v_mfma_f32_16x16x32_bf16 v[96:99], v[184:187], v[200:203], v[96:99]
	v_mfma_f32_16x16x32_bf16 v[84:87], v[176:179], v[208:211], v[84:87]
	v_mfma_f32_16x16x32_bf16 v[80:83], v[184:187], v[208:211], v[80:83]
	v_mfma_f32_16x16x32_bf16 v[68:71], v[176:179], v[216:219], v[68:71]
	v_mfma_f32_16x16x32_bf16 v[64:67], v[184:187], v[216:219], v[64:67]
	s_setprio 0
	s_barrier
; #define PG8_STAGE(bufoff, gbase, voff) do { _Pragma("unroll") for (int _i = 0; _i < 2; ++_i) \
;         __builtin_amdgcn_global_load_lds((const unsigned*)((const char*)(gbase) + (voff)[_i]), (LAS unsigned*)(lds + (bufoff) + ldsw + _i * 8192), 16, 0, 0); } while (0)
; #define PG8_LDA(dst, b, h) do { _Pragma("unroll") for (int m = 0; m < 4; ++m) _Pragma("unroll") for (int k = 0; k < 2; ++k) dst[m][k] = *(const LAS bf16x8*)(lds + PG8_SA(b, h) + aoff + m * 2048 + k * 1024); } while (0)
; #define PG8_MMA(ai, bj, At, Bt) do { __builtin_amdgcn_s_setprio(1); _Pragma("unroll") for (int m = 0; m < 4; ++m) _Pragma("unroll") for (int n = 0; n < 2; ++n) _Pragma("unroll") for (int k = 0; k < 2; ++k) \
;         acc[ai][bj][m][n] = __builtin_amdgcn_mfma_f32_16x16x32_bf16(Bt[n][k], At[m][k], acc[ai][bj][m][n], 0, 0, 0); __builtin_amdgcn_s_setprio(0); } while (0)
; #define PG8_WAIT_V(n) asm volatile("s_waitcnt vmcnt(" #n ")" ::: "memory")
; #define PG8_WAIT_L(n) asm volatile("s_waitcnt lgkmcnt(" #n ")" ::: "memory")
; #define PG8_BAR __builtin_amdgcn_s_barrier()
; #define PG8_SCHED __builtin_amdgcn_sched_barrier(0)
; template <class Epi, class Sched, bool ALIGN_EPI = true, bool SP2 = true>
; __device__ __forceinline__ void gemm_phase(LAS unsigned char* lds, const Gemm g, const Sched& S, const Epi& E) {
;     ...
;         for (int t = 0; t < nt; t += 2) {
;             const bool last = (t == nt - 2);
;     ...
;             PG8_LDA(At, 1, 1); PG8_STAGE(PG8_SB(1, 0), b3, voffB); PG8_STAGE(PG8_SB(1, 1), b3 + hstepB, voffB); PG8_STAGE(PG8_SA(1, 0), a3, voffA);
;             PG8_WAIT_V(8); PG8_WAIT_L(0); PG8_BAR; PG8_MMA(1, 0, At, B0); PG8_MMA(1, 1, At, B1); PG8_BAR; PG8_SCHED;
	s_add_i32 s36, s58, s3
	v_lshl_add_u64 v[220:221], v[220:221], 0, s[14:15]
	s_mov_b32 m0, s36
	ds_read_b128 v[188:191], v153 offset:49152
	ds_read_b128 v[192:195], v153 offset:50176
	ds_read_b128 v[196:199], v153 offset:51200
	ds_read_b128 v[200:203], v153 offset:52224
	ds_read_b128 v[204:207], v153 offset:53248
	ds_read_b128 v[208:211], v153 offset:54272
	ds_read_b128 v[212:215], v153 offset:55296
	ds_read_b128 v[216:219], v153 offset:56320
	global_load_lds_dwordx4 v[220:221], off
	s_add_i32 m0, s36, 0x2000
	s_add_u32 s30, s30, 0x100080
	v_lshl_add_u64 v[220:221], v[222:223], 0, s[14:15]
	s_addc_u32 s31, s31, 0
	s_add_i32 s36, s59, s3
	global_load_lds_dwordx4 v[220:221], off
	s_nop 0
	s_mov_b32 m0, s36
	s_nop 0
	global_load_lds_dwordx4 v130, s[30:31]
	s_nop 0
	s_add_i32 m0, s36, 0x2000
	s_nop 0
	global_load_lds_dwordx4 v134, s[30:31]
	v_lshl_add_u64 v[220:221], v[224:225], 0, s[14:15]
	s_mov_b32 m0, s42
	s_nop 0
	global_load_lds_dwordx4 v[220:221], off
	v_lshl_add_u64 v[220:221], v[226:227], 0, s[14:15]
	s_mov_b32 m0, s43
	s_nop 0
	global_load_lds_dwordx4 v[220:221], off
	s_waitcnt vmcnt(8)
	s_waitcnt lgkmcnt(0)
	s_barrier
	s_setprio 1
	s_waitcnt lgkmcnt(0)
	v_mfma_f32_16x16x32_bf16 v[60:63], v[144:147], v[188:191], v[60:63]
	v_mfma_f32_16x16x32_bf16 v[56:59], v[164:167], v[188:191], v[56:59]
	v_mfma_f32_16x16x32_bf16 v[44:47], v[144:147], v[196:199], v[44:47]
	v_mfma_f32_16x16x32_bf16 v[40:43], v[164:167], v[196:199], v[40:43]
	v_mfma_f32_16x16x32_bf16 v[28:31], v[144:147], v[204:207], v[28:31]
	v_mfma_f32_16x16x32_bf16 v[24:27], v[164:167], v[204:207], v[24:27]
	v_mfma_f32_16x16x32_bf16 v[12:15], v[144:147], v[212:215], v[12:15]
	v_mfma_f32_16x16x32_bf16 v[8:11], v[164:167], v[212:215], v[8:11]
	v_mfma_f32_16x16x32_bf16 v[60:63], v[160:163], v[192:195], v[60:63]
	v_mfma_f32_16x16x32_bf16 v[56:59], v[168:171], v[192:195], v[56:59]
	v_mfma_f32_16x16x32_bf16 v[44:47], v[160:163], v[200:203], v[44:47]
	v_mfma_f32_16x16x32_bf16 v[40:43], v[168:171], v[200:203], v[40:43]
	v_mfma_f32_16x16x32_bf16 v[28:31], v[160:163], v[208:211], v[28:31]
	v_mfma_f32_16x16x32_bf16 v[24:27], v[168:171], v[208:211], v[24:27]
	v_mfma_f32_16x16x32_bf16 v[12:15], v[160:163], v[216:219], v[12:15]
	v_mfma_f32_16x16x32_bf16 v[8:11], v[168:171], v[216:219], v[8:11]
	s_setprio 0
	s_setprio 1
	v_mfma_f32_16x16x32_bf16 v[52:55], v[172:175], v[188:191], v[52:55]
	v_mfma_f32_16x16x32_bf16 v[48:51], v[180:183], v[188:191], v[48:51]
	v_mfma_f32_16x16x32_bf16 v[36:39], v[172:175], v[196:199], v[36:39]
	v_mfma_f32_16x16x32_bf16 v[32:35], v[180:183], v[196:199], v[32:35]
	v_mfma_f32_16x16x32_bf16 v[20:23], v[172:175], v[204:207], v[20:23]
	v_mfma_f32_16x16x32_bf16 v[16:19], v[180:183], v[204:207], v[16:19]
	v_mfma_f32_16x16x32_bf16 v[4:7], v[172:175], v[212:215], v[4:7]
	v_mfma_f32_16x16x32_bf16 v[0:3], v[180:183], v[212:215], v[0:3]
	v_mfma_f32_16x16x32_bf16 v[52:55], v[176:179], v[192:195], v[52:55]
	v_mfma_f32_16x16x32_bf16 v[48:51], v[184:187], v[192:195], v[48:51]
	v_mfma_f32_16x16x32_bf16 v[36:39], v[176:179], v[200:203], v[36:39]
	v_mfma_f32_16x16x32_bf16 v[32:35], v[184:187], v[200:203], v[32:35]
	v_mfma_f32_16x16x32_bf16 v[20:23], v[176:179], v[208:211], v[20:23]
	v_mfma_f32_16x16x32_bf16 v[16:19], v[184:187], v[208:211], v[16:19]
	v_mfma_f32_16x16x32_bf16 v[4:7], v[176:179], v[216:219], v[4:7]
	v_mfma_f32_16x16x32_bf16 v[0:3], v[184:187], v[216:219], v[0:3]
	s_setprio 0
	s_barrier
	s_add_i32 s57, s57, 2
	s_add_u32 s28, s28, 0x100
	s_addc_u32 s29, s29, 0
	s_add_u32 s55, s55, 0x100
	s_addc_u32 s56, s56, 0
	s_cmp_gt_u32 s57, 61
	s_cbranch_scc0 .LBB0_1725
	s_and_b64 vcc, exec, s[16:17]
	s_cbranch_vccz .LBB0_1728
	s_barrier

; #define PG8_STAGE(bufoff, gbase, voff) do { _Pragma("unroll") for (int _i = 0; _i < 2; ++_i) \
;         __builtin_amdgcn_global_load_lds((const unsigned*)((const char*)(gbase) + (voff)[_i]), (LAS unsigned*)(lds + (bufoff) + ldsw + _i * 8192), 16, 0, 0); } while (0)
; #define PG8_LDA(dst, b, h) do { _Pragma("unroll") for (int m = 0; m < 4; ++m) _Pragma("unroll") for (int k = 0; k < 2; ++k) dst[m][k] = *(const LAS bf16x8*)(lds + PG8_SA(b, h) + aoff + m * 2048 + k * 1024); } while (0)
; #define PG8_LDB(dst, b, h) do { _Pragma("unroll") for (int n = 0; n < 2; ++n) _Pragma("unroll") for (int k = 0; k < 2; ++k) dst[n][k] = *(const LAS bf16x8*)(lds + PG8_SB(b, h) + boff + n * 2048 + k * 1024); } while (0)
; #define PG8_WAIT_V(n) asm volatile("s_waitcnt vmcnt(" #n ")" ::: "memory")
; #define PG8_WAIT_L(n) asm volatile("s_waitcnt lgkmcnt(" #n ")" ::: "memory")
; #define PG8_BAR __builtin_amdgcn_s_barrier()
; #define PG8_SCHED __builtin_amdgcn_sched_barrier(0)
; template <class Epi, class Sched, bool ALIGN_EPI = true, bool SP2 = true>
; __device__ __forceinline__ void gemm_phase(LAS unsigned char* lds, const Gemm g, const Sched& S, const Epi& E) {
;     ...
;         const bool has_next = S.next(ui + 1, nxt);
;         const char* nA = has_next ? (const char*)g.A + a_unit_off(g, nxt.pm) : cA; const char* nB = has_next ? (const char*)g.Bt + (size_t)nxt.pn * tstepB : cB;
; #pragma nounroll
;         for (int t = 0; t < nt; t += 2) {
;             const bool last = (t == nt - 2);
;             const char* a1 = cA + (size_t)(t + 1) * kstepA;
;             const char* a2 = last ? nA : cA + (size_t)(t + 2) * kstepA; const char* b2 = last ? nB : cB + (size_t)(t + 2) * kstepB;
;             const char* a3 = a2 + kstepA; const char* b3 = b2 + kstepB;
;             if constexpr (SP2) {
;             PG8_LDB(B0, 0, 0); PG8_LDB(B1, 0, 1); PG8_SCHED; PG8_LDA(At, 0, 0); PG8_STAGE(PG8_SA(1, 1), a1 + hstepA, voffA);
;             PG8_WAIT_V(8); PG8_WAIT_L(0); PG8_BAR; PG8_MMA(0, 0, At, B0); PG8_MMA(0, 1, At, B1); PG8_BAR; PG8_SCHED;
;             PG8_LDA(At, 0, 1); PG8_STAGE(PG8_SB(0, 0), b2, voffB); PG8_STAGE(PG8_SB(0, 1), b2 + hstepB, voffB); PG8_STAGE(PG8_SA(0, 0), a2, voffA);
;             PG8_WAIT_V(8); PG8_WAIT_L(0); PG8_BAR; PG8_MMA(1, 0, At, B0); PG8_MMA(1, 1, At, B1); PG8_BAR; PG8_SCHED;
.LBB0_1820:
	s_add_u32 s44, s24, s36
	s_addc_u32 s45, s25, s37
	s_add_u32 s42, s44, 0x100
	s_addc_u32 s43, s45, 0
	s_and_b64 s[40:41], s[30:31], exec
	s_cselect_b32 s41, s17, s43
	s_cselect_b32 s40, s63, s42
	s_add_u32 s36, s20, s36
	s_addc_u32 s37, s21, s37
	s_add_u32 s36, s36, 0x100
	s_addc_u32 s37, s37, 0
	s_and_b64 s[30:31], s[30:31], exec
	s_cselect_b32 s43, s15, s37
	s_cselect_b32 s42, s64, s36
	s_add_u32 s50, s44, 0x10080
	ds_read_b128 v[146:149], v143
	ds_read_b128 v[150:153], v143 offset:1024
	ds_read_b128 v[160:163], v143 offset:2048
	ds_read_b128 v[164:167], v143 offset:3072
	ds_read_b128 v[168:171], v144
	ds_read_b128 v[172:175], v144 offset:1024
	ds_read_b128 v[176:179], v144 offset:2048
	ds_read_b128 v[180:183], v144 offset:3072
	s_addc_u32 s51, s45, 0
	s_add_i32 s72, s60, s33
	s_add_i32 m0, s19, 0xc000
	s_add_i32 s75, s19, 0xe000
	s_add_i32 s69, s72, 0x2000
	s_add_u32 s44, s42, 0x10000
	s_addc_u32 s45, s43, 0
	s_add_i32 s71, s61, s33
	s_add_i32 s70, s71, 0x2000
	s_add_i32 s68, 0, 0x18000
	s_add_i32 s67, 0, 0x1c000
	s_add_u32 s36, s40, 0x10000
	s_addc_u32 s37, s41, 0
	s_add_i32 s66, s68, s33
	s_add_i32 s65, s66, 0x2000
	s_add_u32 s30, s42, 0x10080
	s_addc_u32 s31, s43, 0
	s_add_i32 s74, s67, s33
	s_add_i32 s73, s74, 0x2000
	s_nop 0
	ds_read_b128 v[184:187], v145
	ds_read_b128 v[188:191], v145 offset:1024
	ds_read_b128 v[192:195], v145 offset:2048
	ds_read_b128 v[196:199], v145 offset:3072
	ds_read_b128 v[200:203], v145 offset:4096
	ds_read_b128 v[204:207], v145 offset:5120
	ds_read_b128 v[208:211], v145 offset:6144
	ds_read_b128 v[212:215], v145 offset:7168
	global_load_lds_dwordx4 v128, s[50:51]
	s_nop 0
	s_mov_b32 m0, s75
	s_nop 0
	global_load_lds_dwordx4 v132, s[50:51]
	s_waitcnt vmcnt(8)
	s_waitcnt lgkmcnt(0)
	s_barrier
	s_setprio 1
	s_waitcnt lgkmcnt(0)
	v_mfma_f32_16x16x32_bf16 v[124:127], v[146:149], v[184:187], v[124:127]
	v_mfma_f32_16x16x32_bf16 v[120:123], v[160:163], v[184:187], v[120:123]
	v_mfma_f32_16x16x32_bf16 v[116:119], v[146:149], v[192:195], v[116:119]
	v_mfma_f32_16x16x32_bf16 v[112:115], v[160:163], v[192:195], v[112:115]
	v_mfma_f32_16x16x32_bf16 v[100:103], v[146:149], v[200:203], v[100:103]
	v_mfma_f32_16x16x32_bf16 v[96:99], v[160:163], v[200:203], v[96:99]
	v_mfma_f32_16x16x32_bf16 v[84:87], v[146:149], v[208:211], v[84:87]
	v_mfma_f32_16x16x32_bf16 v[80:83], v[160:163], v[208:211], v[80:83]
	v_mfma_f32_16x16x32_bf16 v[124:127], v[150:153], v[188:191], v[124:127]
	v_mfma_f32_16x16x32_bf16 v[120:123], v[164:167], v[188:191], v[120:123]
	v_mfma_f32_16x16x32_bf16 v[116:119], v[150:153], v[196:199], v[116:119]
	v_mfma_f32_16x16x32_bf16 v[112:115], v[164:167], v[196:199], v[112:115]
	v_mfma_f32_16x16x32_bf16 v[100:103], v[150:153], v[204:207], v[100:103]
	v_mfma_f32_16x16x32_bf16 v[96:99], v[164:167], v[204:207], v[96:99]
	v_mfma_f32_16x16x32_bf16 v[84:87], v[150:153], v[212:215], v[84:87]
	v_mfma_f32_16x16x32_bf16 v[80:83], v[164:167], v[212:215], v[80:83]
	s_setprio 0
	s_setprio 1
	v_mfma_f32_16x16x32_bf16 v[108:111], v[168:171], v[184:187], v[108:111]
	v_mfma_f32_16x16x32_bf16 v[104:107], v[176:179], v[184:187], v[104:107]
	v_mfma_f32_16x16x32_bf16 v[92:95], v[168:171], v[192:195], v[92:95]
	v_mfma_f32_16x16x32_bf16 v[88:91], v[176:179], v[192:195], v[88:91]
	v_mfma_f32_16x16x32_bf16 v[76:79], v[168:171], v[200:203], v[76:79]
	v_mfma_f32_16x16x32_bf16 v[72:75], v[176:179], v[200:203], v[72:75]
	v_mfma_f32_16x16x32_bf16 v[68:71], v[168:171], v[208:211], v[68:71]
	v_mfma_f32_16x16x32_bf16 v[64:67], v[176:179], v[208:211], v[64:67]
	v_mfma_f32_16x16x32_bf16 v[108:111], v[172:175], v[188:191], v[108:111]
	v_mfma_f32_16x16x32_bf16 v[104:107], v[180:183], v[188:191], v[104:107]
	v_mfma_f32_16x16x32_bf16 v[92:95], v[172:175], v[196:199], v[92:95]
	v_mfma_f32_16x16x32_bf16 v[88:91], v[180:183], v[196:199], v[88:91]
	v_mfma_f32_16x16x32_bf16 v[76:79], v[172:175], v[204:207], v[76:79]
	v_mfma_f32_16x16x32_bf16 v[72:75], v[180:183], v[204:207], v[72:75]
	v_mfma_f32_16x16x32_bf16 v[68:71], v[172:175], v[212:215], v[68:71]
	v_mfma_f32_16x16x32_bf16 v[64:67], v[180:183], v[212:215], v[64:67]
	s_setprio 0
	s_barrier
	s_mov_b32 m0, s72
	v_lshl_add_u64 v[154:155], s[42:43], 0, v[130:131]
	ds_read_b128 v[184:187], v145 offset:16384
	ds_read_b128 v[188:191], v145 offset:17408
	ds_read_b128 v[192:195], v145 offset:18432
	ds_read_b128 v[196:199], v145 offset:19456
	ds_read_b128 v[200:203], v145 offset:20480
	ds_read_b128 v[204:207], v145 offset:21504
	ds_read_b128 v[208:211], v145 offset:22528
	ds_read_b128 v[212:215], v145 offset:23552
	global_load_lds_dwordx4 v[154:155], off
	v_lshl_add_u64 v[216:217], s[42:43], 0, v[134:135]
	s_mov_b32 m0, s69
	s_nop 0
	global_load_lds_dwordx4 v[216:217], off
	s_mov_b32 m0, s71
	v_lshl_add_u64 v[220:221], s[40:41], 0, v[132:133]
	global_load_lds_dwordx4 v130, s[44:45]
	s_nop 0
	s_mov_b32 m0, s70
	s_nop 0
	global_load_lds_dwordx4 v134, s[44:45]
	v_lshl_add_u64 v[218:219], s[40:41], 0, v[128:129]
	s_mov_b32 m0, s19
	s_nop 0
	global_load_lds_dwordx4 v[218:219], off
	s_mov_b32 m0, s52
	s_nop 0
	global_load_lds_dwordx4 v[220:221], off
	s_waitcnt vmcnt(8)
	s_waitcnt lgkmcnt(0)
	s_barrier
; #define PG8_STAGE(bufoff, gbase, voff) do { _Pragma("unroll") for (int _i = 0; _i < 2; ++_i) \
;         __builtin_amdgcn_global_load_lds((const unsigned*)((const char*)(gbase) + (voff)[_i]), (LAS unsigned*)(lds + (bufoff) + ldsw + _i * 8192), 16, 0, 0); } while (0)
; #define PG8_LDA(dst, b, h) do { _Pragma("unroll") for (int m = 0; m < 4; ++m) _Pragma("unroll") for (int k = 0; k < 2; ++k) dst[m][k] = *(const LAS bf16x8*)(lds + PG8_SA(b, h) + aoff + m * 2048 + k * 1024); } while (0)
; #define PG8_LDB(dst, b, h) do { _Pragma("unroll") for (int n = 0; n < 2; ++n) _Pragma("unroll") for (int k = 0; k < 2; ++k) dst[n][k] = *(const LAS bf16x8*)(lds + PG8_SB(b, h) + boff + n * 2048 + k * 1024); } while (0)
; #define PG8_MMA(ai, bj, At, Bt) do { __builtin_amdgcn_s_setprio(1); _Pragma("unroll") for (int m = 0; m < 4; ++m) _Pragma("unroll") for (int n = 0; n < 2; ++n) _Pragma("unroll") for (int k = 0; k < 2; ++k) \
;         acc[ai][bj][m][n] = __builtin_amdgcn_mfma_f32_16x16x32_bf16(Bt[n][k], At[m][k], acc[ai][bj][m][n], 0, 0, 0); __builtin_amdgcn_s_setprio(0); } while (0)
; #define PG8_WAIT_V(n) asm volatile("s_waitcnt vmcnt(" #n ")" ::: "memory")
; #define PG8_WAIT_L(n) asm volatile("s_waitcnt lgkmcnt(" #n ")" ::: "memory")
; #define PG8_BAR __builtin_amdgcn_s_barrier()
; #define PG8_SCHED __builtin_amdgcn_sched_barrier(0)
; template <class Epi, class Sched, bool ALIGN_EPI = true, bool SP2 = true>
; __device__ __forceinline__ void gemm_phase(LAS unsigned char* lds, const Gemm g, const Sched& S, const Epi& E) {
;     ...
;             PG8_WAIT_V(8); PG8_WAIT_L(0); PG8_BAR; PG8_MMA(1, 0, At, B0); PG8_MMA(1, 1, At, B1); PG8_BAR; PG8_SCHED;
;             PG8_LDB(B0, 1, 0); PG8_LDB(B1, 1, 1); PG8_SCHED; PG8_LDA(At, 1, 0); PG8_STAGE(PG8_SA(0, 1), a2 + hstepA, voffA);
;             PG8_WAIT_V(8); PG8_WAIT_L(0); PG8_BAR; PG8_MMA(0, 0, At, B0); PG8_MMA(0, 1, At, B1); PG8_BAR; PG8_SCHED;
	s_setprio 1
	s_waitcnt lgkmcnt(0)
	v_mfma_f32_16x16x32_bf16 v[60:63], v[146:149], v[184:187], v[60:63]
	v_mfma_f32_16x16x32_bf16 v[56:59], v[160:163], v[184:187], v[56:59]
	v_mfma_f32_16x16x32_bf16 v[52:55], v[146:149], v[192:195], v[52:55]
	v_mfma_f32_16x16x32_bf16 v[48:51], v[160:163], v[192:195], v[48:51]
	v_mfma_f32_16x16x32_bf16 v[36:39], v[146:149], v[200:203], v[36:39]
	v_mfma_f32_16x16x32_bf16 v[32:35], v[160:163], v[200:203], v[32:35]
	v_mfma_f32_16x16x32_bf16 v[20:23], v[146:149], v[208:211], v[20:23]
	v_mfma_f32_16x16x32_bf16 v[16:19], v[160:163], v[208:211], v[16:19]
	v_mfma_f32_16x16x32_bf16 v[60:63], v[150:153], v[188:191], v[60:63]
	v_mfma_f32_16x16x32_bf16 v[56:59], v[164:167], v[188:191], v[56:59]
	v_mfma_f32_16x16x32_bf16 v[52:55], v[150:153], v[196:199], v[52:55]
	v_mfma_f32_16x16x32_bf16 v[48:51], v[164:167], v[196:199], v[48:51]
	v_mfma_f32_16x16x32_bf16 v[36:39], v[150:153], v[204:207], v[36:39]
	v_mfma_f32_16x16x32_bf16 v[32:35], v[164:167], v[204:207], v[32:35]
	v_mfma_f32_16x16x32_bf16 v[20:23], v[150:153], v[212:215], v[20:23]
	v_mfma_f32_16x16x32_bf16 v[16:19], v[164:167], v[212:215], v[16:19]
	s_setprio 0
	s_setprio 1
	v_mfma_f32_16x16x32_bf16 v[44:47], v[168:171], v[184:187], v[44:47]
	v_mfma_f32_16x16x32_bf16 v[40:43], v[176:179], v[184:187], v[40:43]
	v_mfma_f32_16x16x32_bf16 v[28:31], v[168:171], v[192:195], v[28:31]
	v_mfma_f32_16x16x32_bf16 v[24:27], v[176:179], v[192:195], v[24:27]
	v_mfma_f32_16x16x32_bf16 v[12:15], v[168:171], v[200:203], v[12:15]
	v_mfma_f32_16x16x32_bf16 v[8:11], v[176:179], v[200:203], v[8:11]
	v_mfma_f32_16x16x32_bf16 v[4:7], v[168:171], v[208:211], v[4:7]
	v_mfma_f32_16x16x32_bf16 v[0:3], v[176:179], v[208:211], v[0:3]
	v_mfma_f32_16x16x32_bf16 v[44:47], v[172:175], v[188:191], v[44:47]
	v_mfma_f32_16x16x32_bf16 v[40:43], v[180:183], v[188:191], v[40:43]
	v_mfma_f32_16x16x32_bf16 v[28:31], v[172:175], v[196:199], v[28:31]
	v_mfma_f32_16x16x32_bf16 v[24:27], v[180:183], v[196:199], v[24:27]
	v_mfma_f32_16x16x32_bf16 v[12:15], v[172:175], v[204:207], v[12:15]
	v_mfma_f32_16x16x32_bf16 v[8:11], v[180:183], v[204:207], v[8:11]
	v_mfma_f32_16x16x32_bf16 v[4:7], v[172:175], v[212:215], v[4:7]
	v_mfma_f32_16x16x32_bf16 v[0:3], v[180:183], v[212:215], v[0:3]
	s_setprio 0
	s_barrier
	v_add_u32_e32 v157, s68, v141
	ds_read_b128 v[146:149], v157
	ds_read_b128 v[150:153], v157 offset:1024
	ds_read_b128 v[160:163], v157 offset:2048
	ds_read_b128 v[164:167], v157 offset:3072
	v_add_u32_e32 v157, s67, v141
	ds_read_b128 v[168:171], v157
	ds_read_b128 v[172:175], v157 offset:1024
	ds_read_b128 v[176:179], v157 offset:2048
	ds_read_b128 v[180:183], v157 offset:3072
	s_mov_b32 m0, s53
	s_nop 0
	ds_read_b128 v[184:187], v145 offset:32768
	ds_read_b128 v[188:191], v145 offset:33792
	ds_read_b128 v[192:195], v145 offset:34816
	ds_read_b128 v[196:199], v145 offset:35840
	ds_read_b128 v[200:203], v145 offset:36864
	ds_read_b128 v[204:207], v145 offset:37888
	ds_read_b128 v[208:211], v145 offset:38912
	ds_read_b128 v[212:215], v145 offset:39936
	global_load_lds_dwordx4 v128, s[36:37]
	s_nop 0
	s_mov_b32 m0, s54
	s_nop 0
	global_load_lds_dwordx4 v132, s[36:37]
	s_waitcnt vmcnt(8)
	s_waitcnt lgkmcnt(0)
	s_barrier
	s_setprio 1
	s_waitcnt lgkmcnt(0)
	v_mfma_f32_16x16x32_bf16 v[124:127], v[146:149], v[184:187], v[124:127]
	v_mfma_f32_16x16x32_bf16 v[120:123], v[160:163], v[184:187], v[120:123]
	v_mfma_f32_16x16x32_bf16 v[116:119], v[146:149], v[192:195], v[116:119]
	v_mfma_f32_16x16x32_bf16 v[112:115], v[160:163], v[192:195], v[112:115]
	v_mfma_f32_16x16x32_bf16 v[100:103], v[146:149], v[200:203], v[100:103]
	v_mfma_f32_16x16x32_bf16 v[96:99], v[160:163], v[200:203], v[96:99]
	v_mfma_f32_16x16x32_bf16 v[84:87], v[146:149], v[208:211], v[84:87]
	v_mfma_f32_16x16x32_bf16 v[80:83], v[160:163], v[208:211], v[80:83]
	v_mfma_f32_16x16x32_bf16 v[124:127], v[150:153], v[188:191], v[124:127]
	v_mfma_f32_16x16x32_bf16 v[120:123], v[164:167], v[188:191], v[120:123]
	v_mfma_f32_16x16x32_bf16 v[116:119], v[150:153], v[196:199], v[116:119]
	v_mfma_f32_16x16x32_bf16 v[112:115], v[164:167], v[196:199], v[112:115]
	v_mfma_f32_16x16x32_bf16 v[100:103], v[150:153], v[204:207], v[100:103]
	v_mfma_f32_16x16x32_bf16 v[96:99], v[164:167], v[204:207], v[96:99]
	v_mfma_f32_16x16x32_bf16 v[84:87], v[150:153], v[212:215], v[84:87]
	v_mfma_f32_16x16x32_bf16 v[80:83], v[164:167], v[212:215], v[80:83]
	s_setprio 0
	s_setprio 1
	v_mfma_f32_16x16x32_bf16 v[108:111], v[168:171], v[184:187], v[108:111]
	v_mfma_f32_16x16x32_bf16 v[104:107], v[176:179], v[184:187], v[104:107]
	v_mfma_f32_16x16x32_bf16 v[92:95], v[168:171], v[192:195], v[92:95]
	v_mfma_f32_16x16x32_bf16 v[88:91], v[176:179], v[192:195], v[88:91]
	v_mfma_f32_16x16x32_bf16 v[76:79], v[168:171], v[200:203], v[76:79]
	v_mfma_f32_16x16x32_bf16 v[72:75], v[176:179], v[200:203], v[72:75]
	v_mfma_f32_16x16x32_bf16 v[68:71], v[168:171], v[208:211], v[68:71]
	v_mfma_f32_16x16x32_bf16 v[64:67], v[176:179], v[208:211], v[64:67]
	v_mfma_f32_16x16x32_bf16 v[108:111], v[172:175], v[188:191], v[108:111]
	v_mfma_f32_16x16x32_bf16 v[104:107], v[180:183], v[188:191], v[104:107]
	v_mfma_f32_16x16x32_bf16 v[92:95], v[172:175], v[196:199], v[92:95]
	v_mfma_f32_16x16x32_bf16 v[88:91], v[180:183], v[196:199], v[88:91]
	v_mfma_f32_16x16x32_bf16 v[76:79], v[172:175], v[204:207], v[76:79]
	v_mfma_f32_16x16x32_bf16 v[72:75], v[180:183], v[204:207], v[72:75]
	v_mfma_f32_16x16x32_bf16 v[68:71], v[172:175], v[212:215], v[68:71]
	v_mfma_f32_16x16x32_bf16 v[64:67], v[180:183], v[212:215], v[64:67]
	s_setprio 0
	s_barrier
; #define PG8_STAGE(bufoff, gbase, voff) do { _Pragma("unroll") for (int _i = 0; _i < 2; ++_i) \
;         __builtin_amdgcn_global_load_lds((const unsigned*)((const char*)(gbase) + (voff)[_i]), (LAS unsigned*)(lds + (bufoff) + ldsw + _i * 8192), 16, 0, 0); } while (0)
; #define PG8_LDA(dst, b, h) do { _Pragma("unroll") for (int m = 0; m < 4; ++m) _Pragma("unroll") for (int k = 0; k < 2; ++k) dst[m][k] = *(const LAS bf16x8*)(lds + PG8_SA(b, h) + aoff + m * 2048 + k * 1024); } while (0)
; #define PG8_MMA(ai, bj, At, Bt) do { __builtin_amdgcn_s_setprio(1); _Pragma("unroll") for (int m = 0; m < 4; ++m) _Pragma("unroll") for (int n = 0; n < 2; ++n) _Pragma("unroll") for (int k = 0; k < 2; ++k) \
;         acc[ai][bj][m][n] = __builtin_amdgcn_mfma_f32_16x16x32_bf16(Bt[n][k], At[m][k], acc[ai][bj][m][n], 0, 0, 0); __builtin_amdgcn_s_setprio(0); } while (0)
; #define PG8_WAIT_V(n) asm volatile("s_waitcnt vmcnt(" #n ")" ::: "memory")
; #define PG8_WAIT_L(n) asm volatile("s_waitcnt lgkmcnt(" #n ")" ::: "memory")
; #define PG8_BAR __builtin_amdgcn_s_barrier()
; #define PG8_SCHED __builtin_amdgcn_sched_barrier(0)
; template <class Epi, class Sched, bool ALIGN_EPI = true, bool SP2 = true>
; __device__ __forceinline__ void gemm_phase(LAS unsigned char* lds, const Gemm g, const Sched& S, const Epi& E) {
;     ...
;         for (int t = 0; t < nt; t += 2) {
;             const bool last = (t == nt - 2);
;     ...
;             PG8_LDA(At, 1, 1); PG8_STAGE(PG8_SB(1, 0), b3, voffB); PG8_STAGE(PG8_SB(1, 1), b3 + hstepB, voffB); PG8_STAGE(PG8_SA(1, 0), a3, voffA);
;             PG8_WAIT_V(8); PG8_WAIT_L(0); PG8_BAR; PG8_MMA(1, 0, At, B0); PG8_MMA(1, 1, At, B1); PG8_BAR; PG8_SCHED;
	s_mov_b32 m0, s66
	v_lshl_add_u64 v[154:155], v[154:155], 0, s[10:11]
	ds_read_b128 v[184:187], v145 offset:49152
	ds_read_b128 v[188:191], v145 offset:50176
	ds_read_b128 v[192:195], v145 offset:51200
	ds_read_b128 v[196:199], v145 offset:52224
	ds_read_b128 v[200:203], v145 offset:53248
	ds_read_b128 v[204:207], v145 offset:54272
	ds_read_b128 v[208:211], v145 offset:55296
	ds_read_b128 v[212:215], v145 offset:56320
	global_load_lds_dwordx4 v[154:155], off
	v_lshl_add_u64 v[154:155], v[216:217], 0, s[10:11]
	s_mov_b32 m0, s65
	s_nop 0
	global_load_lds_dwordx4 v[154:155], off
	s_nop 0
	s_mov_b32 m0, s74
	s_nop 0
	global_load_lds_dwordx4 v130, s[30:31]
	s_nop 0
	s_mov_b32 m0, s73
	s_nop 0
	global_load_lds_dwordx4 v134, s[30:31]
	v_lshl_add_u64 v[154:155], v[218:219], 0, s[10:11]
	s_mov_b32 m0, s56
	s_nop 0
	global_load_lds_dwordx4 v[154:155], off
	v_lshl_add_u64 v[154:155], v[220:221], 0, s[10:11]
	s_mov_b32 m0, s57
	s_nop 0
	global_load_lds_dwordx4 v[154:155], off
	s_waitcnt vmcnt(8)
	s_waitcnt lgkmcnt(0)
	s_barrier
	s_setprio 1
	s_waitcnt lgkmcnt(0)
	v_mfma_f32_16x16x32_bf16 v[60:63], v[146:149], v[184:187], v[60:63]
	v_mfma_f32_16x16x32_bf16 v[56:59], v[160:163], v[184:187], v[56:59]
	v_mfma_f32_16x16x32_bf16 v[52:55], v[146:149], v[192:195], v[52:55]
	v_mfma_f32_16x16x32_bf16 v[48:51], v[160:163], v[192:195], v[48:51]
	v_mfma_f32_16x16x32_bf16 v[36:39], v[146:149], v[200:203], v[36:39]
	v_mfma_f32_16x16x32_bf16 v[32:35], v[160:163], v[200:203], v[32:35]
	v_mfma_f32_16x16x32_bf16 v[20:23], v[146:149], v[208:211], v[20:23]
	v_mfma_f32_16x16x32_bf16 v[16:19], v[160:163], v[208:211], v[16:19]
	v_mfma_f32_16x16x32_bf16 v[60:63], v[150:153], v[188:191], v[60:63]
	v_mfma_f32_16x16x32_bf16 v[56:59], v[164:167], v[188:191], v[56:59]
	v_mfma_f32_16x16x32_bf16 v[52:55], v[150:153], v[196:199], v[52:55]
	v_mfma_f32_16x16x32_bf16 v[48:51], v[164:167], v[196:199], v[48:51]
	v_mfma_f32_16x16x32_bf16 v[36:39], v[150:153], v[204:207], v[36:39]
	v_mfma_f32_16x16x32_bf16 v[32:35], v[164:167], v[204:207], v[32:35]
	v_mfma_f32_16x16x32_bf16 v[20:23], v[150:153], v[212:215], v[20:23]
	v_mfma_f32_16x16x32_bf16 v[16:19], v[164:167], v[212:215], v[16:19]
	s_setprio 0
	s_setprio 1
	v_mfma_f32_16x16x32_bf16 v[44:47], v[168:171], v[184:187], v[44:47]
	v_mfma_f32_16x16x32_bf16 v[40:43], v[176:179], v[184:187], v[40:43]
	v_mfma_f32_16x16x32_bf16 v[28:31], v[168:171], v[192:195], v[28:31]
	v_mfma_f32_16x16x32_bf16 v[24:27], v[176:179], v[192:195], v[24:27]
	v_mfma_f32_16x16x32_bf16 v[12:15], v[168:171], v[200:203], v[12:15]
	v_mfma_f32_16x16x32_bf16 v[8:11], v[176:179], v[200:203], v[8:11]
	v_mfma_f32_16x16x32_bf16 v[4:7], v[168:171], v[208:211], v[4:7]
	v_mfma_f32_16x16x32_bf16 v[0:3], v[176:179], v[208:211], v[0:3]
	v_mfma_f32_16x16x32_bf16 v[44:47], v[172:175], v[188:191], v[44:47]
	v_mfma_f32_16x16x32_bf16 v[40:43], v[180:183], v[188:191], v[40:43]
	v_mfma_f32_16x16x32_bf16 v[28:31], v[172:175], v[196:199], v[28:31]
	v_mfma_f32_16x16x32_bf16 v[24:27], v[180:183], v[196:199], v[24:27]
	v_mfma_f32_16x16x32_bf16 v[12:15], v[172:175], v[204:207], v[12:15]
	v_mfma_f32_16x16x32_bf16 v[8:11], v[180:183], v[204:207], v[8:11]
	v_mfma_f32_16x16x32_bf16 v[4:7], v[172:175], v[212:215], v[4:7]
	v_mfma_f32_16x16x32_bf16 v[0:3], v[180:183], v[212:215], v[0:3]
	s_setprio 0
	s_barrier
	s_andn2_b64 vcc, exec, s[28:29]
	s_mov_b64 s[30:31], -1
	s_mov_b64 s[28:29], 0
	s_mov_b64 s[36:37], 0x100
	s_cbranch_vccz .LBB0_1820
	s_and_b64 vcc, exec, s[12:13]
	s_cbranch_vccz .LBB0_1823
	s_barrier

; #define PG8_STAGE(bufoff, gbase, voff) do { _Pragma("unroll") for (int _i = 0; _i < 2; ++_i) \
;         __builtin_amdgcn_global_load_lds((const unsigned*)((const char*)(gbase) + (voff)[_i]), (LAS unsigned*)(lds + (bufoff) + ldsw + _i * 8192), 16, 0, 0); } while (0)
; #define PG8_LDA(dst, b, h) do { _Pragma("unroll") for (int m = 0; m < 4; ++m) _Pragma("unroll") for (int k = 0; k < 2; ++k) dst[m][k] = *(const LAS bf16x8*)(lds + PG8_SA(b, h) + aoff + m * 2048 + k * 1024); } while (0)
; #define PG8_LDB(dst, b, h) do { _Pragma("unroll") for (int n = 0; n < 2; ++n) _Pragma("unroll") for (int k = 0; k < 2; ++k) dst[n][k] = *(const LAS bf16x8*)(lds + PG8_SB(b, h) + boff + n * 2048 + k * 1024); } while (0)
; #define PG8_MMA(ai, bj, At, Bt) do { __builtin_amdgcn_s_setprio(1); _Pragma("unroll") for (int m = 0; m < 4; ++m) _Pragma("unroll") for (int n = 0; n < 2; ++n) _Pragma("unroll") for (int k = 0; k < 2; ++k) \
;         acc[ai][bj][m][n] = __builtin_amdgcn_mfma_f32_16x16x32_bf16(Bt[n][k], At[m][k], acc[ai][bj][m][n], 0, 0, 0); __builtin_amdgcn_s_setprio(0); } while (0)
; #define PG8_WAIT_V(n) asm volatile("s_waitcnt vmcnt(" #n ")" ::: "memory")
; #define PG8_WAIT_L(n) asm volatile("s_waitcnt lgkmcnt(" #n ")" ::: "memory")
; #define PG8_BAR __builtin_amdgcn_s_barrier()
; template <class Epi, class Sched, bool ALIGN_EPI = true, bool SP2 = true>
; __device__ __forceinline__ void gemm_phase(LAS unsigned char* lds, const Gemm g, const Sched& S, const Epi& E) {
;     ...
;         for (int t = 0; t < nt; t += 2) {
;             const bool last = (t == nt - 2);
;             const char* a1 = cA + (size_t)(t + 1) * kstepA;
;             const char* a2 = last ? nA : cA + (size_t)(t + 2) * kstepA; const char* b2 = last ? nB : cB + (size_t)(t + 2) * kstepB;
;             const char* a3 = a2 + kstepA; const char* b3 = b2 + kstepB;
;             if constexpr (SP2) {
;             PG8_LDB(B0, 0, 0); PG8_LDB(B1, 0, 1); PG8_SCHED; PG8_LDA(At, 0, 0); PG8_STAGE(PG8_SA(1, 1), a1 + hstepA, voffA);
;             PG8_WAIT_V(8); PG8_WAIT_L(0); PG8_BAR; PG8_MMA(0, 0, At, B0); PG8_MMA(0, 1, At, B1); PG8_BAR; PG8_SCHED;
;             PG8_LDA(At, 0, 1); PG8_STAGE(PG8_SB(0, 0), b2, voffB); PG8_STAGE(PG8_SB(0, 1), b2 + hstepB, voffB); PG8_STAGE(PG8_SA(0, 0), a2, voffA);
;             PG8_WAIT_V(8); PG8_WAIT_L(0); PG8_BAR; PG8_MMA(1, 0, At, B0); PG8_MMA(1, 1, At, B1); PG8_BAR; PG8_SCHED;
.LBB0_1909:
	ds_read_b128 v[144:147], v151
	ds_read_b128 v[154:157], v151 offset:1024
	ds_read_b128 v[158:161], v151 offset:2048
	ds_read_b128 v[162:165], v151 offset:3072
	ds_read_b128 v[166:169], v152
	ds_read_b128 v[170:173], v152 offset:1024
	ds_read_b128 v[174:177], v152 offset:2048
	ds_read_b128 v[178:181], v152 offset:3072
	s_add_u32 s22, s20, 0xfffc0080
	s_addc_u32 s23, s21, -1
	s_cmp_eq_u32 s44, 12
	s_cselect_b32 s25, s13, s23
	s_cselect_b32 s24, s40, s22
	s_cselect_b32 s23, s11, s43
	s_cselect_b32 s22, s41, s42
	s_nop 0
	s_add_i32 m0, s19, 0xc000
	ds_read_b128 v[182:185], v153
	ds_read_b128 v[186:189], v153 offset:1024
	ds_read_b128 v[190:193], v153 offset:2048
	ds_read_b128 v[194:197], v153 offset:3072
	ds_read_b128 v[198:201], v153 offset:4096
	ds_read_b128 v[202:205], v153 offset:5120
	ds_read_b128 v[206:209], v153 offset:6144
	ds_read_b128 v[210:213], v153 offset:7168
	global_load_lds_dwordx4 v136, s[20:21]
	s_nop 0
	s_add_i32 m0, s19, 0xe000
	s_nop 0
	global_load_lds_dwordx4 v138, s[20:21]
	s_waitcnt vmcnt(8)
	s_waitcnt lgkmcnt(0)
	s_barrier
	s_setprio 1
	s_waitcnt lgkmcnt(0)
	v_mfma_f32_16x16x32_bf16 v[124:127], v[144:147], v[182:185], v[124:127]
	v_mfma_f32_16x16x32_bf16 v[120:123], v[158:161], v[182:185], v[120:123]
	v_mfma_f32_16x16x32_bf16 v[108:111], v[144:147], v[190:193], v[108:111]
	v_mfma_f32_16x16x32_bf16 v[104:107], v[158:161], v[190:193], v[104:107]
	v_mfma_f32_16x16x32_bf16 v[92:95], v[144:147], v[198:201], v[92:95]
	v_mfma_f32_16x16x32_bf16 v[88:91], v[158:161], v[198:201], v[88:91]
	v_mfma_f32_16x16x32_bf16 v[76:79], v[144:147], v[206:209], v[76:79]
	v_mfma_f32_16x16x32_bf16 v[72:75], v[158:161], v[206:209], v[72:75]
	v_mfma_f32_16x16x32_bf16 v[124:127], v[154:157], v[186:189], v[124:127]
	v_mfma_f32_16x16x32_bf16 v[120:123], v[162:165], v[186:189], v[120:123]
	v_mfma_f32_16x16x32_bf16 v[108:111], v[154:157], v[194:197], v[108:111]
	v_mfma_f32_16x16x32_bf16 v[104:107], v[162:165], v[194:197], v[104:107]
	v_mfma_f32_16x16x32_bf16 v[92:95], v[154:157], v[202:205], v[92:95]
	v_mfma_f32_16x16x32_bf16 v[88:91], v[162:165], v[202:205], v[88:91]
	v_mfma_f32_16x16x32_bf16 v[76:79], v[154:157], v[210:213], v[76:79]
	v_mfma_f32_16x16x32_bf16 v[72:75], v[162:165], v[210:213], v[72:75]
	s_setprio 0
	s_setprio 1
	v_mfma_f32_16x16x32_bf16 v[116:119], v[166:169], v[182:185], v[116:119]
	v_mfma_f32_16x16x32_bf16 v[112:115], v[174:177], v[182:185], v[112:115]
	v_mfma_f32_16x16x32_bf16 v[100:103], v[166:169], v[190:193], v[100:103]
	v_mfma_f32_16x16x32_bf16 v[96:99], v[174:177], v[190:193], v[96:99]
	v_mfma_f32_16x16x32_bf16 v[84:87], v[166:169], v[198:201], v[84:87]
	v_mfma_f32_16x16x32_bf16 v[80:83], v[174:177], v[198:201], v[80:83]
	v_mfma_f32_16x16x32_bf16 v[68:71], v[166:169], v[206:209], v[68:71]
	v_mfma_f32_16x16x32_bf16 v[64:67], v[174:177], v[206:209], v[64:67]
	v_mfma_f32_16x16x32_bf16 v[116:119], v[170:173], v[186:189], v[116:119]
	v_mfma_f32_16x16x32_bf16 v[112:115], v[178:181], v[186:189], v[112:115]
	v_mfma_f32_16x16x32_bf16 v[100:103], v[170:173], v[194:197], v[100:103]
	v_mfma_f32_16x16x32_bf16 v[96:99], v[178:181], v[194:197], v[96:99]
	v_mfma_f32_16x16x32_bf16 v[84:87], v[170:173], v[202:205], v[84:87]
	v_mfma_f32_16x16x32_bf16 v[80:83], v[178:181], v[202:205], v[80:83]
	v_mfma_f32_16x16x32_bf16 v[68:71], v[170:173], v[210:213], v[68:71]
	v_mfma_f32_16x16x32_bf16 v[64:67], v[178:181], v[210:213], v[64:67]
	s_setprio 0
	s_barrier
	s_add_i32 s45, s35, s26
	v_lshl_add_u64 v[214:215], s[22:23], 0, v[130:131]
	s_mov_b32 m0, s45
	ds_read_b128 v[182:185], v153 offset:16384
	ds_read_b128 v[186:189], v153 offset:17408
	ds_read_b128 v[190:193], v153 offset:18432
	ds_read_b128 v[194:197], v153 offset:19456
	ds_read_b128 v[198:201], v153 offset:20480
	ds_read_b128 v[202:205], v153 offset:21504
	ds_read_b128 v[206:209], v153 offset:22528
	ds_read_b128 v[210:213], v153 offset:23552
	global_load_lds_dwordx4 v[214:215], off
	s_add_i32 m0, s45, 0x2000
	s_add_u32 s46, s22, 0x40000
	v_lshl_add_u64 v[216:217], s[22:23], 0, v[134:135]
	s_addc_u32 s47, s23, 0
	s_add_i32 s45, s36, s26
	global_load_lds_dwordx4 v[216:217], off
	s_nop 0
	s_mov_b32 m0, s45
	v_lshl_add_u64 v[220:221], s[24:25], 0, v[132:133]
	global_load_lds_dwordx4 v130, s[46:47]
	s_nop 0
	s_add_i32 m0, s45, 0x2000
	s_nop 0
	global_load_lds_dwordx4 v134, s[46:47]
	v_lshl_add_u64 v[218:219], s[24:25], 0, v[128:129]
	s_mov_b32 m0, s19
	s_nop 0
	global_load_lds_dwordx4 v[218:219], off
	s_mov_b32 m0, s27
	s_nop 0
	global_load_lds_dwordx4 v[220:221], off
	s_waitcnt vmcnt(8)
	s_waitcnt lgkmcnt(0)
	s_barrier
; #define PG8_STAGE(bufoff, gbase, voff) do { _Pragma("unroll") for (int _i = 0; _i < 2; ++_i) \
;         __builtin_amdgcn_global_load_lds((const unsigned*)((const char*)(gbase) + (voff)[_i]), (LAS unsigned*)(lds + (bufoff) + ldsw + _i * 8192), 16, 0, 0); } while (0)
; #define PG8_LDA(dst, b, h) do { _Pragma("unroll") for (int m = 0; m < 4; ++m) _Pragma("unroll") for (int k = 0; k < 2; ++k) dst[m][k] = *(const LAS bf16x8*)(lds + PG8_SA(b, h) + aoff + m * 2048 + k * 1024); } while (0)
; #define PG8_LDB(dst, b, h) do { _Pragma("unroll") for (int n = 0; n < 2; ++n) _Pragma("unroll") for (int k = 0; k < 2; ++k) dst[n][k] = *(const LAS bf16x8*)(lds + PG8_SB(b, h) + boff + n * 2048 + k * 1024); } while (0)
; #define PG8_MMA(ai, bj, At, Bt) do { __builtin_amdgcn_s_setprio(1); _Pragma("unroll") for (int m = 0; m < 4; ++m) _Pragma("unroll") for (int n = 0; n < 2; ++n) _Pragma("unroll") for (int k = 0; k < 2; ++k) \
;         acc[ai][bj][m][n] = __builtin_amdgcn_mfma_f32_16x16x32_bf16(Bt[n][k], At[m][k], acc[ai][bj][m][n], 0, 0, 0); __builtin_amdgcn_s_setprio(0); } while (0)
; #define PG8_WAIT_V(n) asm volatile("s_waitcnt vmcnt(" #n ")" ::: "memory")
; #define PG8_WAIT_L(n) asm volatile("s_waitcnt lgkmcnt(" #n ")" ::: "memory")
; #define PG8_BAR __builtin_amdgcn_s_barrier()
; #define PG8_SCHED __builtin_amdgcn_sched_barrier(0)
; template <class Epi, class Sched, bool ALIGN_EPI = true, bool SP2 = true>
; __device__ __forceinline__ void gemm_phase(LAS unsigned char* lds, const Gemm g, const Sched& S, const Epi& E) {
;     ...
;             PG8_WAIT_V(8); PG8_WAIT_L(0); PG8_BAR; PG8_MMA(1, 0, At, B0); PG8_MMA(1, 1, At, B1); PG8_BAR; PG8_SCHED;
;             PG8_LDB(B0, 1, 0); PG8_LDB(B1, 1, 1); PG8_SCHED; PG8_LDA(At, 1, 0); PG8_STAGE(PG8_SA(0, 1), a2 + hstepA, voffA);
;             PG8_WAIT_V(8); PG8_WAIT_L(0); PG8_BAR; PG8_MMA(0, 0, At, B0); PG8_MMA(0, 1, At, B1); PG8_BAR; PG8_SCHED;
	s_setprio 1
	s_waitcnt lgkmcnt(0)
	v_mfma_f32_16x16x32_bf16 v[60:63], v[144:147], v[182:185], v[60:63]
	v_mfma_f32_16x16x32_bf16 v[56:59], v[158:161], v[182:185], v[56:59]
	v_mfma_f32_16x16x32_bf16 v[44:47], v[144:147], v[190:193], v[44:47]
	v_mfma_f32_16x16x32_bf16 v[40:43], v[158:161], v[190:193], v[40:43]
	v_mfma_f32_16x16x32_bf16 v[28:31], v[144:147], v[198:201], v[28:31]
	v_mfma_f32_16x16x32_bf16 v[24:27], v[158:161], v[198:201], v[24:27]
	v_mfma_f32_16x16x32_bf16 v[12:15], v[144:147], v[206:209], v[12:15]
	v_mfma_f32_16x16x32_bf16 v[8:11], v[158:161], v[206:209], v[8:11]
	v_mfma_f32_16x16x32_bf16 v[60:63], v[154:157], v[186:189], v[60:63]
	v_mfma_f32_16x16x32_bf16 v[56:59], v[162:165], v[186:189], v[56:59]
	v_mfma_f32_16x16x32_bf16 v[44:47], v[154:157], v[194:197], v[44:47]
	v_mfma_f32_16x16x32_bf16 v[40:43], v[162:165], v[194:197], v[40:43]
	v_mfma_f32_16x16x32_bf16 v[28:31], v[154:157], v[202:205], v[28:31]
	v_mfma_f32_16x16x32_bf16 v[24:27], v[162:165], v[202:205], v[24:27]
	v_mfma_f32_16x16x32_bf16 v[12:15], v[154:157], v[210:213], v[12:15]
	v_mfma_f32_16x16x32_bf16 v[8:11], v[162:165], v[210:213], v[8:11]
	s_setprio 0
	s_setprio 1
	v_mfma_f32_16x16x32_bf16 v[52:55], v[166:169], v[182:185], v[52:55]
	v_mfma_f32_16x16x32_bf16 v[48:51], v[174:177], v[182:185], v[48:51]
	v_mfma_f32_16x16x32_bf16 v[36:39], v[166:169], v[190:193], v[36:39]
	v_mfma_f32_16x16x32_bf16 v[32:35], v[174:177], v[190:193], v[32:35]
	v_mfma_f32_16x16x32_bf16 v[20:23], v[166:169], v[198:201], v[20:23]
	v_mfma_f32_16x16x32_bf16 v[16:19], v[174:177], v[198:201], v[16:19]
	v_mfma_f32_16x16x32_bf16 v[4:7], v[166:169], v[206:209], v[4:7]
	v_mfma_f32_16x16x32_bf16 v[0:3], v[174:177], v[206:209], v[0:3]
	v_mfma_f32_16x16x32_bf16 v[52:55], v[170:173], v[186:189], v[52:55]
	v_mfma_f32_16x16x32_bf16 v[48:51], v[178:181], v[186:189], v[48:51]
	v_mfma_f32_16x16x32_bf16 v[36:39], v[170:173], v[194:197], v[36:39]
	v_mfma_f32_16x16x32_bf16 v[32:35], v[178:181], v[194:197], v[32:35]
	v_mfma_f32_16x16x32_bf16 v[20:23], v[170:173], v[202:205], v[20:23]
	v_mfma_f32_16x16x32_bf16 v[16:19], v[178:181], v[202:205], v[16:19]
	v_mfma_f32_16x16x32_bf16 v[4:7], v[170:173], v[210:213], v[4:7]
	v_mfma_f32_16x16x32_bf16 v[0:3], v[178:181], v[210:213], v[0:3]
	s_setprio 0
	s_barrier
	s_add_i32 s45, 0, 0x18000
	s_add_i32 s46, 0, 0x1c000
	v_add_u32_e32 v162, s45, v149
	v_add_u32_e32 v178, s46, v149
	ds_read_b128 v[144:147], v162
	ds_read_b128 v[154:157], v162 offset:1024
	ds_read_b128 v[158:161], v162 offset:2048
	ds_read_b128 v[162:165], v162 offset:3072
	ds_read_b128 v[166:169], v178
	ds_read_b128 v[170:173], v178 offset:1024
	ds_read_b128 v[174:177], v178 offset:2048
	ds_read_b128 v[178:181], v178 offset:3072
	s_add_u32 s24, s24, 0x40000
	s_addc_u32 s25, s25, 0
	s_mov_b32 m0, s28
	s_nop 0
	ds_read_b128 v[182:185], v153 offset:32768
	ds_read_b128 v[186:189], v153 offset:33792
	ds_read_b128 v[190:193], v153 offset:34816
	ds_read_b128 v[194:197], v153 offset:35840
	ds_read_b128 v[198:201], v153 offset:36864
	ds_read_b128 v[202:205], v153 offset:37888
	ds_read_b128 v[206:209], v153 offset:38912
	ds_read_b128 v[210:213], v153 offset:39936
	global_load_lds_dwordx4 v128, s[24:25]
	s_nop 0
	s_mov_b32 m0, s29
	s_nop 0
	global_load_lds_dwordx4 v132, s[24:25]
	s_waitcnt vmcnt(8)
	s_waitcnt lgkmcnt(0)
	s_barrier
	s_setprio 1
	s_waitcnt lgkmcnt(0)
	v_mfma_f32_16x16x32_bf16 v[124:127], v[144:147], v[182:185], v[124:127]
	v_mfma_f32_16x16x32_bf16 v[120:123], v[158:161], v[182:185], v[120:123]
	v_mfma_f32_16x16x32_bf16 v[108:111], v[144:147], v[190:193], v[108:111]
	v_mfma_f32_16x16x32_bf16 v[104:107], v[158:161], v[190:193], v[104:107]
	v_mfma_f32_16x16x32_bf16 v[92:95], v[144:147], v[198:201], v[92:95]
	v_mfma_f32_16x16x32_bf16 v[88:91], v[158:161], v[198:201], v[88:91]
	v_mfma_f32_16x16x32_bf16 v[76:79], v[144:147], v[206:209], v[76:79]
	v_mfma_f32_16x16x32_bf16 v[72:75], v[158:161], v[206:209], v[72:75]
	v_mfma_f32_16x16x32_bf16 v[124:127], v[154:157], v[186:189], v[124:127]
	v_mfma_f32_16x16x32_bf16 v[120:123], v[162:165], v[186:189], v[120:123]
	v_mfma_f32_16x16x32_bf16 v[108:111], v[154:157], v[194:197], v[108:111]
	v_mfma_f32_16x16x32_bf16 v[104:107], v[162:165], v[194:197], v[104:107]
	v_mfma_f32_16x16x32_bf16 v[92:95], v[154:157], v[202:205], v[92:95]
	v_mfma_f32_16x16x32_bf16 v[88:91], v[162:165], v[202:205], v[88:91]
	v_mfma_f32_16x16x32_bf16 v[76:79], v[154:157], v[210:213], v[76:79]
	v_mfma_f32_16x16x32_bf16 v[72:75], v[162:165], v[210:213], v[72:75]
	s_setprio 0
	s_setprio 1
	v_mfma_f32_16x16x32_bf16 v[116:119], v[166:169], v[182:185], v[116:119]
	v_mfma_f32_16x16x32_bf16 v[112:115], v[174:177], v[182:185], v[112:115]
	v_mfma_f32_16x16x32_bf16 v[100:103], v[166:169], v[190:193], v[100:103]
	v_mfma_f32_16x16x32_bf16 v[96:99], v[174:177], v[190:193], v[96:99]
	v_mfma_f32_16x16x32_bf16 v[84:87], v[166:169], v[198:201], v[84:87]
	v_mfma_f32_16x16x32_bf16 v[80:83], v[174:177], v[198:201], v[80:83]
	v_mfma_f32_16x16x32_bf16 v[68:71], v[166:169], v[206:209], v[68:71]
	v_mfma_f32_16x16x32_bf16 v[64:67], v[174:177], v[206:209], v[64:67]
	v_mfma_f32_16x16x32_bf16 v[116:119], v[170:173], v[186:189], v[116:119]
	v_mfma_f32_16x16x32_bf16 v[112:115], v[178:181], v[186:189], v[112:115]
	v_mfma_f32_16x16x32_bf16 v[100:103], v[170:173], v[194:197], v[100:103]
	v_mfma_f32_16x16x32_bf16 v[96:99], v[178:181], v[194:197], v[96:99]
	v_mfma_f32_16x16x32_bf16 v[84:87], v[170:173], v[202:205], v[84:87]
	v_mfma_f32_16x16x32_bf16 v[80:83], v[178:181], v[202:205], v[80:83]
	v_mfma_f32_16x16x32_bf16 v[68:71], v[170:173], v[210:213], v[68:71]
	v_mfma_f32_16x16x32_bf16 v[64:67], v[178:181], v[210:213], v[64:67]
	s_setprio 0
	s_barrier
; #define PG8_STAGE(bufoff, gbase, voff) do { _Pragma("unroll") for (int _i = 0; _i < 2; ++_i) \
;         __builtin_amdgcn_global_load_lds((const unsigned*)((const char*)(gbase) + (voff)[_i]), (LAS unsigned*)(lds + (bufoff) + ldsw + _i * 8192), 16, 0, 0); } while (0)
; #define PG8_LDA(dst, b, h) do { _Pragma("unroll") for (int m = 0; m < 4; ++m) _Pragma("unroll") for (int k = 0; k < 2; ++k) dst[m][k] = *(const LAS bf16x8*)(lds + PG8_SA(b, h) + aoff + m * 2048 + k * 1024); } while (0)
; #define PG8_MMA(ai, bj, At, Bt) do { __builtin_amdgcn_s_setprio(1); _Pragma("unroll") for (int m = 0; m < 4; ++m) _Pragma("unroll") for (int n = 0; n < 2; ++n) _Pragma("unroll") for (int k = 0; k < 2; ++k) \
;         acc[ai][bj][m][n] = __builtin_amdgcn_mfma_f32_16x16x32_bf16(Bt[n][k], At[m][k], acc[ai][bj][m][n], 0, 0, 0); __builtin_amdgcn_s_setprio(0); } while (0)
; #define PG8_WAIT_V(n) asm volatile("s_waitcnt vmcnt(" #n ")" ::: "memory")
; #define PG8_WAIT_L(n) asm volatile("s_waitcnt lgkmcnt(" #n ")" ::: "memory")
; #define PG8_BAR __builtin_amdgcn_s_barrier()
; #define PG8_SCHED __builtin_amdgcn_sched_barrier(0)
; template <class Epi, class Sched, bool ALIGN_EPI = true, bool SP2 = true>
; __device__ __forceinline__ void gemm_phase(LAS unsigned char* lds, const Gemm g, const Sched& S, const Epi& E) {
;     ...
;         for (int t = 0; t < nt; t += 2) {
;             const bool last = (t == nt - 2);
;     ...
;             PG8_LDA(At, 1, 1); PG8_STAGE(PG8_SB(1, 0), b3, voffB); PG8_STAGE(PG8_SB(1, 1), b3 + hstepB, voffB); PG8_STAGE(PG8_SA(1, 0), a3, voffA);
;             PG8_WAIT_V(8); PG8_WAIT_L(0); PG8_BAR; PG8_MMA(1, 0, At, B0); PG8_MMA(1, 1, At, B1); PG8_BAR; PG8_SCHED;
	s_add_i32 s24, s45, s26
	v_lshl_add_u64 v[214:215], v[214:215], 0, s[6:7]
	s_mov_b32 m0, s24
	ds_read_b128 v[182:185], v153 offset:49152
	ds_read_b128 v[186:189], v153 offset:50176
	ds_read_b128 v[190:193], v153 offset:51200
	ds_read_b128 v[194:197], v153 offset:52224
	ds_read_b128 v[198:201], v153 offset:53248
	ds_read_b128 v[202:205], v153 offset:54272
	ds_read_b128 v[206:209], v153 offset:55296
	ds_read_b128 v[210:213], v153 offset:56320
	global_load_lds_dwordx4 v[214:215], off
	s_add_i32 m0, s24, 0x2000
	s_add_u32 s22, s22, 0x40080
	v_lshl_add_u64 v[214:215], v[216:217], 0, s[6:7]
	s_addc_u32 s23, s23, 0
	s_add_i32 s24, s46, s26
	global_load_lds_dwordx4 v[214:215], off
	s_nop 0
	s_mov_b32 m0, s24
	s_nop 0
	global_load_lds_dwordx4 v130, s[22:23]
	s_nop 0
	s_add_i32 m0, s24, 0x2000
	s_nop 0
	global_load_lds_dwordx4 v134, s[22:23]
	v_lshl_add_u64 v[214:215], v[218:219], 0, s[6:7]
	s_mov_b32 m0, s31
	s_nop 0
	global_load_lds_dwordx4 v[214:215], off
	v_lshl_add_u64 v[214:215], v[220:221], 0, s[6:7]
	s_mov_b32 m0, s33
	s_nop 0
	global_load_lds_dwordx4 v[214:215], off
	s_waitcnt vmcnt(8)
	s_waitcnt lgkmcnt(0)
	s_barrier
	s_setprio 1
	s_waitcnt lgkmcnt(0)
	v_mfma_f32_16x16x32_bf16 v[60:63], v[144:147], v[182:185], v[60:63]
	v_mfma_f32_16x16x32_bf16 v[56:59], v[158:161], v[182:185], v[56:59]
	v_mfma_f32_16x16x32_bf16 v[44:47], v[144:147], v[190:193], v[44:47]
	v_mfma_f32_16x16x32_bf16 v[40:43], v[158:161], v[190:193], v[40:43]
	v_mfma_f32_16x16x32_bf16 v[28:31], v[144:147], v[198:201], v[28:31]
	v_mfma_f32_16x16x32_bf16 v[24:27], v[158:161], v[198:201], v[24:27]
	v_mfma_f32_16x16x32_bf16 v[12:15], v[144:147], v[206:209], v[12:15]
	v_mfma_f32_16x16x32_bf16 v[8:11], v[158:161], v[206:209], v[8:11]
	v_mfma_f32_16x16x32_bf16 v[60:63], v[154:157], v[186:189], v[60:63]
	v_mfma_f32_16x16x32_bf16 v[56:59], v[162:165], v[186:189], v[56:59]
	v_mfma_f32_16x16x32_bf16 v[44:47], v[154:157], v[194:197], v[44:47]
	v_mfma_f32_16x16x32_bf16 v[40:43], v[162:165], v[194:197], v[40:43]
	v_mfma_f32_16x16x32_bf16 v[28:31], v[154:157], v[202:205], v[28:31]
	v_mfma_f32_16x16x32_bf16 v[24:27], v[162:165], v[202:205], v[24:27]
	v_mfma_f32_16x16x32_bf16 v[12:15], v[154:157], v[210:213], v[12:15]
	v_mfma_f32_16x16x32_bf16 v[8:11], v[162:165], v[210:213], v[8:11]
	s_setprio 0
	s_setprio 1
	v_mfma_f32_16x16x32_bf16 v[52:55], v[166:169], v[182:185], v[52:55]
	v_mfma_f32_16x16x32_bf16 v[48:51], v[174:177], v[182:185], v[48:51]
	v_mfma_f32_16x16x32_bf16 v[36:39], v[166:169], v[190:193], v[36:39]
	v_mfma_f32_16x16x32_bf16 v[32:35], v[174:177], v[190:193], v[32:35]
	v_mfma_f32_16x16x32_bf16 v[20:23], v[166:169], v[198:201], v[20:23]
	v_mfma_f32_16x16x32_bf16 v[16:19], v[174:177], v[198:201], v[16:19]
	v_mfma_f32_16x16x32_bf16 v[4:7], v[166:169], v[206:209], v[4:7]
	v_mfma_f32_16x16x32_bf16 v[0:3], v[174:177], v[206:209], v[0:3]
	v_mfma_f32_16x16x32_bf16 v[52:55], v[170:173], v[186:189], v[52:55]
	v_mfma_f32_16x16x32_bf16 v[48:51], v[178:181], v[186:189], v[48:51]
	v_mfma_f32_16x16x32_bf16 v[36:39], v[170:173], v[194:197], v[36:39]
	v_mfma_f32_16x16x32_bf16 v[32:35], v[178:181], v[194:197], v[32:35]
	v_mfma_f32_16x16x32_bf16 v[20:23], v[170:173], v[202:205], v[20:23]
	v_mfma_f32_16x16x32_bf16 v[16:19], v[178:181], v[202:205], v[16:19]
	v_mfma_f32_16x16x32_bf16 v[4:7], v[170:173], v[210:213], v[4:7]
	v_mfma_f32_16x16x32_bf16 v[0:3], v[178:181], v[210:213], v[0:3]
	s_setprio 0
	s_barrier
	s_add_i32 s44, s44, 2
	s_add_u32 s42, s42, 0x100
	s_addc_u32 s43, s43, 0
	s_add_u32 s20, s20, 0x100
	s_addc_u32 s21, s21, 0
	s_cmp_gt_u32 s44, 13
	s_cbranch_scc0 .LBB0_1909
	s_and_b64 vcc, exec, s[8:9]
	s_cbranch_vccz .LBB0_1912
	s_barrier
